# attention phase: every packed f32 VALU op split into two scalar ops (bit-identical), on top of best PEER version
# speedup vs baseline: 1.0055x; 1.0055x over previous
.LBB0_1285:
	s_or_b64 exec, exec, s[2:3]
	v_cmp_gt_u32_e32 vcc, s18, v145
	s_and_saveexec_b64 s[0:1], vcc
	s_cbranch_execz .LBB0_1289
	v_mov_b32_e32 v74, 0
	v_mov_b32_e32 v75, 0
	v_mov_b32_e32 v72, 0
	v_mov_b32_e32 v73, 0
	v_mov_b32_e32 v62, 0
	v_mov_b32_e32 v63, 0
	v_mov_b32_e32 v60, 0
	v_mov_b32_e32 v61, 0
	v_mov_b32_e32 v70, 0
	v_mov_b32_e32 v71, 0
	v_mov_b32_e32 v68, 0
	v_mov_b32_e32 v69, 0
	v_mov_b32_e32 v66, 0
	v_mov_b32_e32 v67, 0
	v_mov_b32_e32 v64, 0
	v_mov_b32_e32 v65, 0
	s_mov_b64 s[2:3], exec
	v_readlane_b32 s8, v253, 49
	v_readlane_b32 s9, v253, 50
	s_and_b64 s[8:9], s[2:3], s[8:9]
	s_mov_b64 exec, s[8:9]
	s_cbranch_execz .LBB0_1288
	s_waitcnt vmcnt(3)
	v_lshlrev_b32_e32 v60, 16, v56
	v_and_b32_e32 v61, 0xffff0000, v56
	s_waitcnt vmcnt(2)
	v_lshlrev_b32_e32 v62, 16, v52
	v_and_b32_e32 v63, 0xffff0000, v52
	v_lshlrev_b32_e32 v56, 16, v57
	v_and_b32_e32 v57, 0xffff0000, v57
	v_lshlrev_b32_e32 v52, 16, v53
	v_and_b32_e32 v53, 0xffff0000, v53
	s_waitcnt vmcnt(1)
	v_lshlrev_b32_e32 v72, 16, v48
	v_and_b32_e32 v73, 0xffff0000, v48
	s_waitcnt vmcnt(0)
	v_lshlrev_b32_e32 v74, 16, v44
	v_and_b32_e32 v75, 0xffff0000, v44
	v_lshlrev_b32_e32 v48, 16, v49
	v_and_b32_e32 v49, 0xffff0000, v49
	v_lshlrev_b32_e32 v44, 16, v45
	v_and_b32_e32 v45, 0xffff0000, v45
	v_lshlrev_b32_e32 v64, 16, v58
	v_and_b32_e32 v65, 0xffff0000, v58
	v_lshlrev_b32_e32 v66, 16, v54
	v_and_b32_e32 v67, 0xffff0000, v54
	v_lshlrev_b32_e32 v76, 16, v50
	v_and_b32_e32 v77, 0xffff0000, v50
	v_lshlrev_b32_e32 v78, 16, v46
	v_and_b32_e32 v79, 0xffff0000, v46
	v_lshlrev_b32_e32 v58, 16, v59
	v_lshlrev_b32_e32 v54, 16, v55
	v_and_b32_e32 v59, 0xffff0000, v59
	v_and_b32_e32 v55, 0xffff0000, v55
	v_add_f32_e32 v52, v52, v56
	v_add_f32_e32 v53, v53, v57
	v_lshlrev_b32_e32 v50, 16, v51
	v_lshlrev_b32_e32 v46, 16, v47
	v_and_b32_e32 v51, 0xffff0000, v51
	v_and_b32_e32 v47, 0xffff0000, v47
	v_add_f32_e32 v60, v62, v60
	v_add_f32_e32 v61, v63, v61
	v_add_f32_e32 v56, v66, v64
	v_add_f32_e32 v57, v67, v65
	v_add_f32_e32 v54, v54, v58
	v_add_f32_e32 v55, v55, v59
	v_add_f32_e32 v68, v22, v52
	v_add_f32_e32 v69, v23, v53
	v_add_f32_e32 v52, v74, v72
	v_add_f32_e32 v53, v75, v73
	v_add_f32_e32 v44, v44, v48
	v_add_f32_e32 v45, v45, v49
	v_add_f32_e32 v48, v78, v76
	v_add_f32_e32 v49, v79, v77
	v_add_f32_e32 v46, v46, v50
	v_add_f32_e32 v47, v47, v51
	v_add_f32_e32 v64, v26, v54
	v_add_f32_e32 v65, v27, v55
	v_add_f32_e32 v66, v24, v56
	v_add_f32_e32 v67, v25, v57
	v_add_f32_e32 v70, v20, v60
	v_add_f32_e32 v71, v21, v61
	v_add_f32_e32 v60, v18, v46
	v_add_f32_e32 v61, v19, v47
	v_add_f32_e32 v62, v16, v48
	v_add_f32_e32 v63, v17, v49
	v_add_f32_e32 v72, v14, v44
	v_add_f32_e32 v73, v15, v45
	v_add_f32_e32 v74, v12, v52
	v_add_f32_e32 v75, v13, v53
.LBB0_1288:
	s_or_b64 exec, exec, s[2:3]
	s_waitcnt vmcnt(1)
	v_mul_f32_e32 v50, v71, v71
	v_fmac_f32_e32 v50, v70, v70
	v_mul_f32_e32 v48, v68, v68
	v_mul_f32_e32 v49, v69, v69
	s_waitcnt vmcnt(0)
	v_mul_f32_e32 v46, v66, v66
	v_mul_f32_e32 v47, v67, v67
	v_add_f32_e32 v48, v48, v50
	v_add_f32_e32 v48, v49, v48
	v_add_f32_e32 v46, v46, v48
	v_mul_f32_e32 v44, v64, v64
	v_mul_f32_e32 v45, v65, v65
	v_add_f32_e32 v46, v47, v46
	v_add_f32_e32 v44, v44, v46
	v_add_f32_e32 v44, v45, v44
	ds_bpermute_b32 v45, v184, v44
	v_add_u32_e32 v54, v194, v173
	v_cvt_pk_bf16_f32 v55, v74, s0
	v_add_u32_e32 v56, v199, v174
	s_waitcnt lgkmcnt(0)
	v_add_f32_e32 v44, v44, v45
	ds_bpermute_b32 v45, v185, v44
	s_waitcnt lgkmcnt(0)
	v_add_f32_e32 v44, v44, v45
	ds_bpermute_b32 v45, v188, v44
	s_waitcnt lgkmcnt(0)
	v_add_f32_e32 v44, v44, v45
	v_fmamk_f32 v44, v44, 0x3c800000, v213
	v_rsq_f32_e32 v44, v44
	s_nop 0
	v_mul_f32_e32 v46, v70, v44
	v_mul_f32_e32 v47, v71, v44
	v_mul_f32_e32 v48, v66, v44
	v_mul_f32_e32 v49, v67, v44
	v_mul_f32_e32 v50, v68, v44
	v_mul_f32_e32 v51, v69, v44
	v_mul_f32_e32 v45, v65, v44
	v_mul_f32_e32 v44, v64, v44
	v_mul_f32_e32 v46, v8, v46
	v_mul_f32_e32 v47, v9, v47
	v_mul_f32_e32 v48, v4, v48
	v_mul_f32_e32 v49, v5, v49
	v_mul_f32_e32 v50, v10, v50
	v_mul_f32_e32 v51, v11, v51
	v_mul_f32_e32 v52, v6, v44
	v_mul_f32_e32 v53, v7, v45
	v_cvt_pk_bf16_f32 v44, v46, v47
	v_cvt_pk_bf16_f32 v46, v48, v49
	v_cvt_pk_bf16_f32 v45, v50, v51
	v_cvt_pk_bf16_f32 v47, v52, v53
	ds_write_b128 v54, v[44:47]
	ds_write_b16 v56, v55 offset:18432
	v_cvt_pk_bf16_f32 v44, v75, s0
	ds_write_b16 v56, v44 offset:18704
	v_cvt_pk_bf16_f32 v44, v72, s0
	ds_write_b16 v56, v44 offset:18976
	v_cvt_pk_bf16_f32 v44, v73, s0
	ds_write_b16 v56, v44 offset:19248
	v_cvt_pk_bf16_f32 v44, v62, s0
	ds_write_b16 v56, v44 offset:19520
	v_cvt_pk_bf16_f32 v44, v63, s0
	ds_write_b16 v56, v44 offset:19792
	v_cvt_pk_bf16_f32 v44, v60, s0
	ds_write_b16 v56, v44 offset:20064
	v_cvt_pk_bf16_f32 v44, v61, s0
	ds_write_b16 v56, v44 offset:20336
.LBB0_1289:
	s_or_b64 exec, exec, s[0:1]
	v_lshlrev_b32_e32 v155, 6, v3
	s_lshl_b32 s5, s5, 6
	v_cmp_gt_u32_e32 vcc, s18, v172
	s_and_saveexec_b64 s[0:1], vcc
	s_cbranch_execz .LBB0_1293
	s_waitcnt vmcnt(3)
	v_mov_b32_e32 v58, 0
	v_mov_b32_e32 v59, 0
	v_mov_b32_e32 v56, 0
	v_mov_b32_e32 v57, 0
	s_waitcnt vmcnt(0)
	v_mov_b32_e32 v46, 0
	v_mov_b32_e32 v47, 0
	v_mov_b32_e32 v44, 0
	v_mov_b32_e32 v45, 0
	v_mov_b32_e32 v54, 0
	v_mov_b32_e32 v55, 0
	v_mov_b32_e32 v52, 0
	v_mov_b32_e32 v53, 0
	v_mov_b32_e32 v50, 0
	v_mov_b32_e32 v51, 0
	v_mov_b32_e32 v48, 0
	v_mov_b32_e32 v49, 0
	s_mov_b64 s[2:3], exec
	v_readlane_b32 s8, v253, 51
	v_readlane_b32 s9, v253, 52
	s_and_b64 s[8:9], s[2:3], s[8:9]
	s_mov_b64 exec, s[8:9]
	s_cbranch_execz .LBB0_1292
	v_lshlrev_b32_e32 v44, 16, v40
	v_and_b32_e32 v45, 0xffff0000, v40
	v_lshlrev_b32_e32 v46, 16, v36
	v_and_b32_e32 v47, 0xffff0000, v36
	v_lshlrev_b32_e32 v40, 16, v41
	v_and_b32_e32 v41, 0xffff0000, v41
	v_lshlrev_b32_e32 v36, 16, v37
	v_and_b32_e32 v37, 0xffff0000, v37
	v_lshlrev_b32_e32 v48, 16, v42
	v_and_b32_e32 v49, 0xffff0000, v42
	v_lshlrev_b32_e32 v50, 16, v38
	v_and_b32_e32 v51, 0xffff0000, v38
	v_lshlrev_b32_e32 v42, 16, v43
	v_lshlrev_b32_e32 v38, 16, v39
	v_and_b32_e32 v43, 0xffff0000, v43
	v_and_b32_e32 v39, 0xffff0000, v39
	v_add_f32_e32 v44, v46, v44
	v_add_f32_e32 v45, v47, v45
	v_add_f32_e32 v36, v36, v40
	v_add_f32_e32 v37, v37, v41
	v_lshlrev_b32_e32 v56, 16, v32
	v_and_b32_e32 v57, 0xffff0000, v32
	v_lshlrev_b32_e32 v58, 16, v28
	v_and_b32_e32 v59, 0xffff0000, v28
	v_lshlrev_b32_e32 v32, 16, v33
	v_and_b32_e32 v33, 0xffff0000, v33
	v_lshlrev_b32_e32 v28, 16, v29
	v_and_b32_e32 v29, 0xffff0000, v29
	v_lshlrev_b32_e32 v60, 16, v34
	v_and_b32_e32 v61, 0xffff0000, v34
	v_lshlrev_b32_e32 v62, 16, v30
	v_and_b32_e32 v63, 0xffff0000, v30
	v_add_f32_e32 v40, v50, v48
	v_add_f32_e32 v41, v51, v49
	v_add_f32_e32 v38, v38, v42
	v_add_f32_e32 v39, v39, v43
	v_add_f32_e32 v52, v22, v36
	v_add_f32_e32 v53, v23, v37
	v_add_f32_e32 v54, v20, v44
	v_add_f32_e32 v55, v21, v45
	v_lshlrev_b32_e32 v20, 16, v35
	v_lshlrev_b32_e32 v22, 16, v31
	v_and_b32_e32 v21, 0xffff0000, v35
	v_and_b32_e32 v23, 0xffff0000, v31
	v_add_f32_e32 v48, v26, v38
	v_add_f32_e32 v49, v27, v39
	v_add_f32_e32 v50, v24, v40
	v_add_f32_e32 v51, v25, v41
	v_add_f32_e32 v24, v58, v56
	v_add_f32_e32 v25, v59, v57
	v_add_f32_e32 v26, v28, v32
	v_add_f32_e32 v27, v29, v33
	v_add_f32_e32 v28, v62, v60
	v_add_f32_e32 v29, v63, v61
	v_add_f32_e32 v20, v22, v20
	v_add_f32_e32 v21, v23, v21
	v_add_f32_e32 v46, v16, v28
	v_add_f32_e32 v47, v17, v29
	v_add_f32_e32 v44, v18, v20
	v_add_f32_e32 v45, v19, v21
	v_add_f32_e32 v56, v14, v26
	v_add_f32_e32 v57, v15, v27
	v_add_f32_e32 v58, v12, v24
	v_add_f32_e32 v59, v13, v25
.LBB0_1292:
	s_or_b64 exec, exec, s[2:3]
	v_mul_f32_e32 v18, v55, v55
	v_fmac_f32_e32 v18, v54, v54
	v_mul_f32_e32 v16, v52, v52
	v_mul_f32_e32 v17, v53, v53
	v_mul_f32_e32 v14, v50, v50
	v_mul_f32_e32 v15, v51, v51
	v_add_f32_e32 v16, v16, v18
	v_add_f32_e32 v16, v17, v16
	v_add_f32_e32 v14, v14, v16
	v_mul_f32_e32 v12, v48, v48
	v_mul_f32_e32 v13, v49, v49
	v_add_f32_e32 v14, v15, v14
	v_add_f32_e32 v12, v12, v14
	v_add_f32_e32 v12, v13, v12
	ds_bpermute_b32 v13, v184, v12
	v_add_u32_e32 v20, v194, v173
	v_cvt_pk_bf16_f32 v21, v58, s0
	v_add_u32_e32 v22, v199, v174
	s_waitcnt lgkmcnt(0)
	v_add_f32_e32 v12, v12, v13
	ds_bpermute_b32 v13, v185, v12
	s_waitcnt lgkmcnt(0)
	v_add_f32_e32 v12, v12, v13
	ds_bpermute_b32 v13, v188, v12
	s_waitcnt lgkmcnt(0)
	v_add_f32_e32 v12, v12, v13
	v_fmamk_f32 v12, v12, 0x3c800000, v213
	v_rsq_f32_e32 v12, v12
	s_nop 0
	v_mul_f32_e32 v14, v54, v12
	v_mul_f32_e32 v15, v55, v12
	v_mul_f32_e32 v16, v50, v12
	v_mul_f32_e32 v17, v51, v12
	v_mul_f32_e32 v18, v52, v12
	v_mul_f32_e32 v19, v53, v12
	v_mul_f32_e32 v13, v49, v12
	v_mul_f32_e32 v12, v48, v12
	v_mul_f32_e32 v8, v8, v14
	v_mul_f32_e32 v9, v9, v15
	v_mul_f32_e32 v14, v4, v16
	v_mul_f32_e32 v15, v5, v17
	v_mul_f32_e32 v10, v10, v18
	v_mul_f32_e32 v11, v11, v19
	v_mul_f32_e32 v12, v6, v12
	v_mul_f32_e32 v13, v7, v13
	v_cvt_pk_bf16_f32 v4, v8, v9
	v_cvt_pk_bf16_f32 v6, v14, v15
	v_cvt_pk_bf16_f32 v5, v10, v11
	v_cvt_pk_bf16_f32 v7, v12, v13
	ds_write_b128 v20, v[4:7] offset:9216
	ds_write_b16 v22, v21 offset:18560
	v_cvt_pk_bf16_f32 v4, v59, s0
	ds_write_b16 v22, v4 offset:18832
	v_cvt_pk_bf16_f32 v4, v56, s0
	ds_write_b16 v22, v4 offset:19104
	v_cvt_pk_bf16_f32 v4, v57, s0
	ds_write_b16 v22, v4 offset:19376
	v_cvt_pk_bf16_f32 v4, v46, s0
	ds_write_b16 v22, v4 offset:19648
	v_cvt_pk_bf16_f32 v4, v47, s0
	ds_write_b16 v22, v4 offset:19920
	v_cvt_pk_bf16_f32 v4, v44, s0
	ds_write_b16 v22, v4 offset:20192
	v_cvt_pk_bf16_f32 v4, v45, s0
	ds_write_b16 v22, v4 offset:20464

.LBB0_1304:
	ds_bpermute_b32 v4, v179, v36
	s_andn2_b64 vcc, exec, s[76:77]
	v_add_u32_e32 v72, 0x4800, v216
	s_waitcnt lgkmcnt(0)
	v_max3_f32 v75, v36, v4, s46
	v_add_u32_e32 v4, v197, v149
	v_add_u32_e32 v74, 0x4800, v4
	s_cbranch_vccnz .LBB0_1309
	ds_read_b128 v[4:7], v61
	ds_read_b128 v[36:39], v61 offset:32
	v_cmp_lt_i32_e32 vcc, -1, v64
	s_waitcnt lgkmcnt(1)
	v_mfma_f32_32x32x16_bf16 v[4:19], v[4:7], v[100:103], 0
	s_waitcnt lgkmcnt(0)
	v_mfma_f32_32x32x16_bf16 v[4:19], v[36:39], v[104:107], v[4:19]
	ds_read_b128 v[36:39], v61 offset:64
	s_waitcnt lgkmcnt(0)
	v_mfma_f32_32x32x16_bf16 v[4:19], v[36:39], v[108:111], v[4:19]
	ds_read_b128 v[36:39], v61 offset:96
	s_waitcnt lgkmcnt(0)
	v_mfma_f32_32x32x16_bf16 v[4:19], v[36:39], v[112:115], v[4:19]
	s_nop 11
	v_add_f32_e32 v4, v21, v4
	v_cndmask_b32_e32 v4, v214, v4, vcc
	v_sub_f32_e32 v4, v4, v75
	v_exp_f32_e32 v21, v4
	v_add_f32_e32 v4, v34, v5
	v_cmp_lt_i32_e32 vcc, 0, v64
	v_add_f32_e32 v3, v3, v19
	s_nop 0
	v_cndmask_b32_e32 v4, v214, v4, vcc
	v_sub_f32_e32 v4, v4, v75
	v_exp_f32_e32 v5, v4
	v_add_f32_e32 v4, v23, v6
	v_cmp_lt_i32_e32 vcc, 1, v64
	v_add_f32_e32 v6, v22, v10
	s_nop 0
	v_cndmask_b32_e32 v4, v214, v4, vcc
	v_sub_f32_e32 v4, v4, v75
	v_exp_f32_e32 v23, v4
	v_add_f32_e32 v4, v33, v7
	v_cmp_lt_i32_e32 vcc, 2, v64
	s_nop 1
	v_cndmask_b32_e32 v4, v214, v4, vcc
	v_sub_f32_e32 v4, v4, v75
	v_exp_f32_e32 v7, v4
	v_add_f32_e32 v4, v20, v8
	v_cmp_lt_i32_e32 vcc, 7, v64
	v_add_f32_e32 v8, v30, v12
	s_nop 0
	v_cndmask_b32_e32 v4, v214, v4, vcc
	v_sub_f32_e32 v4, v4, v75
	v_exp_f32_e32 v20, v4
	v_add_f32_e32 v4, v32, v9
	v_cmp_lt_i32_e32 vcc, 8, v64
	s_nop 1
	v_cndmask_b32_e32 v4, v214, v4, vcc
	v_cmp_lt_i32_e32 vcc, 9, v64
	v_sub_f32_e32 v4, v4, v75
	v_exp_f32_e32 v4, v4
	v_cndmask_b32_e32 v6, v214, v6, vcc
	v_sub_f32_e32 v6, v6, v75
	v_exp_f32_e32 v22, v6
	v_add_f32_e32 v6, v31, v11
	v_cmp_lt_i32_e32 vcc, 10, v64
	s_nop 1
	v_cndmask_b32_e32 v6, v214, v6, vcc
	v_cmp_lt_i32_e32 vcc, 15, v64
	v_sub_f32_e32 v6, v6, v75
	v_exp_f32_e32 v6, v6
	v_cndmask_b32_e32 v8, v214, v8, vcc
	v_sub_f32_e32 v8, v8, v75
	v_exp_f32_e32 v39, v8
	v_add_f32_e32 v8, v29, v13
	v_cmp_lt_i32_e32 vcc, 16, v64
	v_add_f32_e32 v12, v20, v4
	v_add_f32_e32 v13, v21, v5
	s_nop 0
	v_cndmask_b32_e32 v8, v214, v8, vcc
	v_sub_f32_e32 v8, v8, v75
	v_exp_f32_e32 v41, v8
	v_add_f32_e32 v8, v28, v14
	v_cmp_lt_i32_e32 vcc, 17, v64
	v_add_f32_e32 v12, v22, v12
	v_add_f32_e32 v13, v23, v13
	v_cvt_pk_bf16_f32 v128, v39, v41
	v_cndmask_b32_e32 v8, v214, v8, vcc
	v_sub_f32_e32 v8, v8, v75
	v_exp_f32_e32 v43, v8
	v_add_f32_e32 v8, v27, v15
	v_cmp_lt_i32_e32 vcc, 18, v64
	v_fma_f32 v12, v6, 0.5, v12
	v_fma_f32 v13, v7, 0.5, v13
	v_cvt_pk_bf16_f32 v27, v22, v6
	v_cndmask_b32_e32 v8, v214, v8, vcc
	v_sub_f32_e32 v8, v8, v75
	v_exp_f32_e32 v37, v8
	v_add_f32_e32 v8, v26, v16
	v_cmp_lt_i32_e32 vcc, 23, v64
	v_cvt_pk_bf16_f32 v26, v20, v4
	v_cvt_pk_bf16_f32 v129, v43, v37
	v_cndmask_b32_e32 v8, v214, v8, vcc
	v_sub_f32_e32 v8, v8, v75
	v_exp_f32_e32 v38, v8
	v_add_f32_e32 v8, v25, v17
	v_cmp_lt_i32_e32 vcc, 24, v64
	v_cvt_pk_bf16_f32 v25, v23, v7
	s_nop 0
	v_cndmask_b32_e32 v8, v214, v8, vcc
	v_sub_f32_e32 v8, v8, v75
	v_exp_f32_e32 v40, v8
	v_add_f32_e32 v8, v24, v18
	v_cmp_lt_i32_e32 vcc, 25, v64
	v_cvt_pk_bf16_f32 v24, v21, v5
	v_add_f32_e32 v10, v38, v40
	v_add_f32_e32 v11, v39, v41
	v_cndmask_b32_e32 v8, v214, v8, vcc
	v_cmp_lt_i32_e32 vcc, 26, v64
	v_sub_f32_e32 v8, v8, v75
	v_exp_f32_e32 v42, v8
	v_cndmask_b32_e32 v3, v214, v3, vcc
	v_sub_f32_e32 v3, v3, v75
	v_exp_f32_e32 v36, v3
	v_add_f32_e32 v3, 0, v21
	v_add_f32_e32 v3, v5, v3
	v_add_f32_e32 v3, v23, v3
	v_mul_f32_e32 v8, 0.5, v36
	v_mul_f32_e32 v9, 0.5, v37
	v_add_f32_e32 v3, v7, v3
	ds_bpermute_b32 v14, v179, v9
	ds_bpermute_b32 v98, v179, v8
	v_mul_f32_e32 v8, 0.5, v6
	v_mul_f32_e32 v9, 0.5, v7
	v_add_f32_e32 v3, v20, v3
	ds_bpermute_b32 v9, v179, v9
	ds_bpermute_b32 v15, v179, v8
	v_add_f32_e32 v3, v4, v3
	v_add_f32_e32 v3, v22, v3
	v_add_f32_e32 v3, v6, v3
	ds_read2_b64 v[4:7], v74 offset1:2
	ds_read2_b64 v[44:47], v74 offset0:4 offset1:6
	ds_read2_b64 v[20:23], v72 offset1:2
	ds_read2_b64 v[48:51], v72 offset0:4 offset1:6
	v_add_f32_e32 v10, v42, v10
	v_add_f32_e32 v11, v43, v11
	s_waitcnt lgkmcnt(4)
	v_cndmask_b32_e64 v8, v15, v9, s[10:11]
	v_cndmask_b32_e64 v9, v9, 0, s[10:11]
	v_fma_f32 v10, v36, 0.5, v10
	v_fma_f32 v11, v37, 0.5, v11
	v_add_f32_e32 v54, v8, v12
	v_add_f32_e32 v55, v9, v13
	v_cndmask_b32_e64 v9, v14, v15, s[10:11]
	v_cndmask_b32_e64 v8, v98, v14, s[10:11]
	v_add_f32_e32 v52, v10, v8
	v_add_f32_e32 v53, v11, v9
	s_waitcnt lgkmcnt(3)
	v_mfma_f32_32x32x16_bf16 v[4:19], v[4:7], v[24:27], 0
	v_cvt_pk_bf16_f32 v130, v38, v40
	v_cvt_pk_bf16_f32 v131, v42, v36
	v_add_f32_e32 v3, v39, v3
	v_add_f32_e32 v3, v41, v3
	v_add_f32_e32 v3, v43, v3
	v_add_f32_e32 v3, v37, v3
	v_add_f32_e32 v3, v38, v3
	s_waitcnt lgkmcnt(1)
	v_mfma_f32_32x32x16_bf16 v[20:35], v[20:23], v[24:27], 0
	v_add_f32_e32 v3, v40, v3
	v_add_f32_e32 v3, v42, v3
	v_add_f32_e32 v3, v36, v3
	v_mfma_f32_32x32x16_bf16 v[4:19], v[44:47], v[128:131], v[4:19]
	s_waitcnt lgkmcnt(0)
	v_mfma_f32_32x32x16_bf16 v[20:35], v[48:51], v[128:131], v[20:35]
	s_andn2_b64 vcc, exec, s[54:55]
	v_mov_b32_e32 v60, 0
	s_cbranch_vccnz .LBB0_1310
.LBB0_1306:
	ds_read_b128 v[36:39], v121
	ds_read_b128 v[128:131], v121 offset:32
	v_cmp_lt_i32_e32 vcc, 31, v64
	s_waitcnt lgkmcnt(1)
	v_mfma_f32_32x32x16_bf16 v[36:51], v[36:39], v[100:103], 0
	s_waitcnt lgkmcnt(0)
	v_mfma_f32_32x32x16_bf16 v[36:51], v[128:131], v[104:107], v[36:51]
	ds_read_b128 v[128:131], v121 offset:64
	ds_read_b128 v[166:169], v121 offset:96
	s_waitcnt lgkmcnt(1)
	v_mfma_f32_32x32x16_bf16 v[36:51], v[128:131], v[108:111], v[36:51]
	s_waitcnt lgkmcnt(0)
	v_mfma_f32_32x32x16_bf16 v[36:51], v[166:169], v[112:115], v[36:51]
	s_nop 11
	v_add_f32_e32 v36, v119, v36
	v_add_f32_e32 v37, v120, v37
	v_cndmask_b32_e32 v36, v214, v36, vcc
	v_cmp_lt_i32_e32 vcc, 32, v64
	v_add_f32_e32 v38, v122, v38
	v_add_f32_e32 v39, v123, v39
	v_cndmask_b32_e32 v37, v214, v37, vcc
	v_cmp_lt_i32_e32 vcc, 33, v64
	v_add_f32_e32 v40, v124, v40
	v_add_f32_e32 v41, v125, v41
	v_cndmask_b32_e32 v38, v214, v38, vcc
	v_cmp_lt_i32_e32 vcc, 34, v64
	v_add_f32_e32 v42, v126, v42
	v_add_f32_e32 v43, v127, v43
	v_cndmask_b32_e32 v39, v214, v39, vcc
	v_cmp_lt_i32_e32 vcc, 39, v64
	v_sub_f32_e32 v36, v36, v75
	v_exp_f32_e32 v121, v36
	v_cndmask_b32_e32 v40, v214, v40, vcc
	v_cmp_lt_i32_e32 vcc, 40, v64
	v_sub_f32_e32 v37, v37, v75
	v_sub_f32_e32 v38, v38, v75
	v_cndmask_b32_e32 v41, v214, v41, vcc
	v_cmp_lt_i32_e32 vcc, 41, v64
	v_sub_f32_e32 v39, v39, v75
	v_exp_f32_e32 v123, v37
	v_cndmask_b32_e32 v42, v214, v42, vcc
	v_cmp_lt_i32_e32 vcc, 42, v64
	v_exp_f32_e32 v125, v38
	v_exp_f32_e32 v127, v39
	v_cndmask_b32_e32 v36, v214, v43, vcc
	v_sub_f32_e32 v36, v36, v75
	v_exp_f32_e32 v126, v36
	v_add_f32_e32 v36, v118, v44
	v_cmp_lt_i32_e32 vcc, 47, v64
	v_sub_f32_e32 v40, v40, v75
	v_sub_f32_e32 v41, v41, v75
	v_cndmask_b32_e32 v36, v214, v36, vcc
	v_sub_f32_e32 v36, v36, v75
	v_exp_f32_e32 v119, v36
	v_add_f32_e32 v36, v117, v45
	v_cmp_lt_i32_e32 vcc, 48, v64
	v_sub_f32_e32 v42, v42, v75
	v_exp_f32_e32 v120, v40
	v_cndmask_b32_e32 v36, v214, v36, vcc
	v_sub_f32_e32 v36, v36, v75
	v_exp_f32_e32 v117, v36
	v_add_f32_e32 v36, v116, v46
	v_cmp_lt_i32_e32 vcc, 49, v64
	v_exp_f32_e32 v122, v41
	v_exp_f32_e32 v124, v42
	v_cndmask_b32_e32 v36, v214, v36, vcc
	v_sub_f32_e32 v36, v36, v75
	v_exp_f32_e32 v129, v36
	v_add_f32_e32 v36, v99, v47
	v_cmp_lt_i32_e32 vcc, 50, v64
	ds_read2_b64 v[44:47], v72 offset0:8 offset1:10
	v_cvt_pk_bf16_f32 v40, v121, v123
	v_cndmask_b32_e32 v36, v214, v36, vcc
	v_sub_f32_e32 v36, v36, v75
	v_exp_f32_e32 v131, v36
	v_add_f32_e32 v36, v59, v48
	v_cmp_lt_i32_e32 vcc, 55, v64
	v_cvt_pk_bf16_f32 v41, v125, v127
	v_cvt_pk_bf16_f32 v42, v120, v122
	v_cndmask_b32_e32 v36, v214, v36, vcc
	v_sub_f32_e32 v36, v36, v75
	v_exp_f32_e32 v118, v36
	v_add_f32_e32 v36, v58, v49
	v_cmp_lt_i32_e32 vcc, 56, v64
	v_cvt_pk_bf16_f32 v43, v124, v126
	v_add_f32_e32 v3, v3, v121
	v_cndmask_b32_e32 v36, v214, v36, vcc
	v_sub_f32_e32 v36, v36, v75
	v_exp_f32_e32 v116, v36
	v_add_f32_e32 v36, v57, v50
	v_cmp_lt_i32_e32 vcc, 57, v64
	s_waitcnt lgkmcnt(0)
	v_mfma_f32_32x32x16_bf16 v[20:35], v[44:47], v[40:43], v[20:35]
	v_add_f32_e32 v3, v123, v3
	v_cndmask_b32_e32 v36, v214, v36, vcc
	v_sub_f32_e32 v36, v36, v75
	v_exp_f32_e32 v128, v36
	v_add_f32_e32 v36, v56, v51
	v_cmp_lt_i32_e32 vcc, 58, v64
	v_add_f32_e32 v50, v118, v116
	v_add_f32_e32 v51, v119, v117
	v_add_f32_e32 v3, v125, v3
	v_cndmask_b32_e32 v36, v214, v36, vcc
	v_sub_f32_e32 v36, v36, v75
	v_exp_f32_e32 v130, v36
	ds_read2_b64 v[36:39], v74 offset0:8 offset1:10
	s_waitcnt lgkmcnt(0)
	v_mfma_f32_32x32x16_bf16 v[4:19], v[36:39], v[40:43], v[4:19]
	v_add_f32_e64 v36, v128, v50
	v_add_f32_e64 v37, v129, v51
	ds_read2_b64 v[40:43], v72 offset0:12 offset1:14
	v_fma_f32 v50, v130, 0.5, v36
	v_fma_f32 v51, v131, 0.5, v37
	ds_read2_b64 v[36:39], v74 offset0:12 offset1:14
	v_add_f32_e32 v3, v127, v3
	v_add_f32_e32 v3, v120, v3
	v_add_f32_e32 v3, v122, v3
	v_add_f32_e32 v3, v124, v3
	v_mul_f32_e32 v48, 0.5, v130
	v_mul_f32_e32 v49, 0.5, v131
	v_add_f32_e32 v3, v126, v3
	ds_bpermute_b32 v99, v179, v49
	ds_bpermute_b32 v159, v179, v48
	v_mul_f32_e32 v48, 0.5, v126
	v_mul_f32_e32 v49, 0.5, v127
	v_cvt_pk_bf16_f32 v44, v119, v117
	v_cvt_pk_bf16_f32 v45, v129, v131
	v_cvt_pk_bf16_f32 v46, v118, v116
	v_cvt_pk_bf16_f32 v47, v128, v130
	v_add_f32_e32 v3, v119, v3
	ds_bpermute_b32 v49, v179, v49
	ds_bpermute_b32 v48, v179, v48
	s_waitcnt lgkmcnt(4)
	v_mfma_f32_32x32x16_bf16 v[4:19], v[36:39], v[44:47], v[4:19]
	v_add_f32_e32 v3, v117, v3
	v_add_f32_e32 v3, v129, v3
	v_add_f32_e32 v3, v131, v3
	v_add_f32_e64 v56, v120, v122
	v_add_f32_e64 v57, v121, v123
	v_add_f32_e32 v3, v118, v3
	v_add_f32_e32 v56, v124, v56
	v_add_f32_e32 v57, v125, v57
	v_add_f32_e32 v3, v116, v3
	v_mfma_f32_32x32x16_bf16 v[20:35], v[40:43], v[44:47], v[20:35]
	v_fma_f32 v36, v126, 0.5, v56
	v_fma_f32 v37, v127, 0.5, v57
	s_waitcnt lgkmcnt(0)
	v_cndmask_b32_e64 v38, v48, v49, s[10:11]
	v_cndmask_b32_e64 v39, v49, v98, s[10:11]
	v_add_f32_e32 v3, v128, v3
	v_add_f32_e32 v58, v38, v36
	v_add_f32_e32 v59, v39, v37
	v_cndmask_b32_e64 v37, v99, v48, s[10:11]
	v_cndmask_b32_e64 v36, v159, v99, s[10:11]
	v_add_f32_e32 v56, v50, v36
	v_add_f32_e32 v57, v51, v37
	v_add_f32_e32 v3, v130, v3
	v_mov_b32_e32 v98, v159
	s_andn2_b64 vcc, exec, s[52:53]
	s_cbranch_vccz .LBB0_1311

.LBB0_1311:
	ds_read_b128 v[36:39], v61 offset:9216
	ds_read_b128 v[116:119], v61 offset:9248
	v_cmp_lt_i32_e32 vcc, 63, v64
	s_movk_i32 s0, 0x41
	s_waitcnt lgkmcnt(1)
	v_mfma_f32_32x32x16_bf16 v[36:51], v[36:39], v[100:103], 0
	s_waitcnt lgkmcnt(0)
	v_mfma_f32_32x32x16_bf16 v[36:51], v[116:119], v[104:107], v[36:51]
	ds_read_b128 v[116:119], v61 offset:9280
	ds_read_b128 v[120:123], v61 offset:9312
	s_waitcnt lgkmcnt(1)
	v_mfma_f32_32x32x16_bf16 v[36:51], v[116:119], v[108:111], v[36:51]
	s_waitcnt lgkmcnt(0)
	v_mfma_f32_32x32x16_bf16 v[36:51], v[120:123], v[112:115], v[36:51]
	s_nop 11
	v_add_f32_e32 v36, v90, v36
	v_add_f32_e32 v37, v91, v37
	v_cndmask_b32_e32 v36, v214, v36, vcc
	v_cmp_lt_i32_e32 vcc, 64, v64
	v_add_f32_e32 v38, v92, v38
	v_add_f32_e32 v39, v93, v39
	v_cndmask_b32_e32 v37, v214, v37, vcc
	v_cmp_lt_i32_e32 vcc, s0, v64
	s_movk_i32 s0, 0x42
	v_add_f32_e32 v40, v94, v40
	v_cndmask_b32_e32 v38, v214, v38, vcc
	v_cmp_lt_i32_e32 vcc, s0, v64
	s_movk_i32 s0, 0x47
	v_add_f32_e32 v41, v95, v41
	v_cndmask_b32_e32 v39, v214, v39, vcc
	v_cmp_lt_i32_e32 vcc, s0, v64
	s_movk_i32 s0, 0x48
	v_add_f32_e32 v42, v96, v42
	v_cndmask_b32_e32 v40, v214, v40, vcc
	v_cmp_lt_i32_e32 vcc, s0, v64
	s_movk_i32 s0, 0x49
	v_add_f32_e32 v43, v97, v43
	v_cndmask_b32_e32 v41, v214, v41, vcc
	v_cmp_lt_i32_e32 vcc, s0, v64
	s_movk_i32 s0, 0x4a
	v_sub_f32_e32 v36, v36, v75
	v_cndmask_b32_e32 v42, v214, v42, vcc
	v_cmp_lt_i32_e32 vcc, s0, v64
	v_exp_f32_e32 v61, v36
	s_movk_i32 s0, 0x4f
	v_cndmask_b32_e32 v36, v214, v43, vcc
	v_sub_f32_e32 v36, v36, v75
	v_exp_f32_e32 v94, v36
	v_add_f32_e32 v36, v89, v44
	v_cmp_lt_i32_e32 vcc, s0, v64
	s_movk_i32 s0, 0x50
	v_sub_f32_e32 v37, v37, v75
	v_cndmask_b32_e32 v36, v214, v36, vcc
	v_sub_f32_e32 v36, v36, v75
	v_exp_f32_e32 v89, v36
	v_add_f32_e32 v36, v88, v45
	v_cmp_lt_i32_e32 vcc, s0, v64
	s_movk_i32 s0, 0x51
	v_sub_f32_e32 v38, v38, v75
	v_cndmask_b32_e32 v36, v214, v36, vcc
	v_sub_f32_e32 v36, v36, v75
	v_exp_f32_e32 v97, v36
	v_add_f32_e32 v36, v87, v46
	v_cmp_lt_i32_e32 vcc, s0, v64
	s_movk_i32 s0, 0x52
	v_sub_f32_e32 v39, v39, v75
	v_cndmask_b32_e32 v36, v214, v36, vcc
	v_sub_f32_e32 v36, v36, v75
	v_exp_f32_e32 v87, v36
	v_add_f32_e32 v36, v86, v47
	v_cmp_lt_i32_e32 vcc, s0, v64
	s_movk_i32 s0, 0x57
	v_exp_f32_e32 v91, v37
	v_cndmask_b32_e32 v36, v214, v36, vcc
	v_sub_f32_e32 v36, v36, v75
	v_exp_f32_e32 v117, v36
	v_add_f32_e32 v36, v85, v48
	v_cmp_lt_i32_e32 vcc, s0, v64
	s_movk_i32 s0, 0x58
	v_exp_f32_e32 v93, v38
	v_cndmask_b32_e32 v36, v214, v36, vcc
	v_sub_f32_e32 v36, v36, v75
	v_exp_f32_e32 v88, v36
	v_add_f32_e32 v36, v84, v49
	v_cmp_lt_i32_e32 vcc, s0, v64
	s_movk_i32 s0, 0x59
	v_exp_f32_e32 v95, v39
	v_cndmask_b32_e32 v36, v214, v36, vcc
	v_sub_f32_e32 v36, v36, v75
	v_exp_f32_e32 v96, v36
	v_add_f32_e32 v36, v63, v50
	v_cmp_lt_i32_e32 vcc, s0, v64
	s_movk_i32 s0, 0x5a
	ds_read2_b64 v[44:47], v72 offset0:16 offset1:18
	v_cndmask_b32_e32 v36, v214, v36, vcc
	v_sub_f32_e32 v36, v36, v75
	v_exp_f32_e32 v86, v36
	v_add_f32_e32 v36, v62, v51
	v_cmp_lt_i32_e32 vcc, s0, v64
	v_sub_f32_e32 v40, v40, v75
	v_sub_f32_e32 v41, v41, v75
	v_cndmask_b32_e32 v36, v214, v36, vcc
	v_sub_f32_e32 v36, v36, v75
	v_exp_f32_e32 v116, v36
	ds_read2_b64 v[36:39], v74 offset0:16 offset1:18
	v_sub_f32_e32 v42, v42, v75
	v_exp_f32_e32 v60, v40
	v_exp_f32_e32 v90, v41
	v_exp_f32_e32 v92, v42
	v_add_f32_e32 v50, v88, v96
	v_add_f32_e32 v51, v89, v97
	v_cvt_pk_bf16_f32 v40, v61, v91
	v_cvt_pk_bf16_f32 v41, v93, v95
	v_cvt_pk_bf16_f32 v42, v60, v90
	v_cvt_pk_bf16_f32 v43, v92, v94
	v_add_f32_e32 v3, v3, v61
	v_add_f32_e32 v3, v91, v3
	s_waitcnt lgkmcnt(0)
	v_mfma_f32_32x32x16_bf16 v[4:19], v[36:39], v[40:43], v[4:19]
	v_add_f32_e64 v36, v86, v50
	v_add_f32_e64 v37, v87, v51
	v_add_f32_e32 v3, v93, v3
	v_fma_f32 v50, v116, 0.5, v36
	v_fma_f32 v51, v117, 0.5, v37
	ds_read2_b64 v[36:39], v74 offset0:20 offset1:22
	v_add_f32_e32 v3, v95, v3
	v_add_f32_e32 v3, v60, v3
	v_add_f32_e32 v3, v90, v3
	v_mfma_f32_32x32x16_bf16 v[20:35], v[44:47], v[40:43], v[20:35]
	ds_read2_b64 v[40:43], v72 offset0:20 offset1:22
	v_add_f32_e32 v3, v92, v3
	v_mul_f32_e64 v48, v116, 0.5
	v_mul_f32_e64 v49, v117, 0.5
	v_add_f32_e32 v3, v94, v3
	ds_bpermute_b32 v84, v179, v49
	ds_bpermute_b32 v85, v179, v48
	v_mul_f32_e32 v48, 0.5, v94
	v_mul_f32_e32 v49, 0.5, v95
	v_cvt_pk_bf16_f32 v44, v89, v97
	v_cvt_pk_bf16_f32 v45, v87, v117
	v_cvt_pk_bf16_f32 v46, v88, v96
	v_cvt_pk_bf16_f32 v47, v86, v116
	v_add_f32_e32 v3, v89, v3
	ds_bpermute_b32 v49, v179, v49
	ds_bpermute_b32 v48, v179, v48
	s_waitcnt lgkmcnt(5)
	v_mfma_f32_32x32x16_bf16 v[4:19], v[36:39], v[44:47], v[4:19]
	v_add_f32_e32 v3, v97, v3
	v_add_f32_e32 v3, v87, v3
	v_add_f32_e32 v3, v117, v3
	v_add_f32_e64 v60, v60, v90
	v_add_f32_e64 v61, v61, v91
	v_add_f32_e32 v3, v88, v3
	v_add_f32_e32 v60, v92, v60
	v_add_f32_e32 v61, v93, v61
	v_add_f32_e32 v3, v96, v3
	s_waitcnt lgkmcnt(4)
	v_mfma_f32_32x32x16_bf16 v[20:35], v[40:43], v[44:47], v[20:35]
	v_fma_f32 v36, v94, 0.5, v60
	v_fma_f32 v37, v95, 0.5, v61
	s_waitcnt lgkmcnt(0)
	v_cndmask_b32_e64 v38, v48, v49, s[10:11]
	v_cndmask_b32_e64 v39, v49, v98, s[10:11]
	v_add_f32_e32 v3, v86, v3
	v_add_f32_e32 v62, v38, v36
	v_add_f32_e32 v63, v39, v37
	v_cndmask_b32_e64 v37, v84, v48, s[10:11]
	v_cndmask_b32_e64 v36, v85, v84, s[10:11]
	v_add_f32_e32 v60, v50, v36
	v_add_f32_e32 v61, v51, v37
	v_add_f32_e32 v3, v116, v3
	v_mov_b32_e32 v98, v85
	s_andn2_b64 vcc, exec, s[50:51]
	v_mov_b32_e32 v36, 0
	s_cbranch_vccnz .LBB0_1308
.LBB0_1312:
	ds_read_b128 v[36:39], v215
	ds_read_b128 v[84:87], v215 offset:32
	s_movk_i32 s0, 0x5f
	v_cmp_lt_i32_e32 vcc, s0, v64
	s_movk_i32 s0, 0x60
	s_waitcnt lgkmcnt(1)
	v_mfma_f32_32x32x16_bf16 v[36:51], v[36:39], v[100:103], 0
	s_waitcnt lgkmcnt(0)
	v_mfma_f32_32x32x16_bf16 v[36:51], v[84:87], v[104:107], v[36:51]
	ds_read_b128 v[84:87], v215 offset:64
	ds_read_b128 v[88:91], v215 offset:96
	s_waitcnt lgkmcnt(1)
	v_mfma_f32_32x32x16_bf16 v[36:51], v[84:87], v[108:111], v[36:51]
	s_waitcnt lgkmcnt(0)
	v_mfma_f32_32x32x16_bf16 v[36:51], v[88:91], v[112:115], v[36:51]
	s_nop 11
	v_add_f32_e32 v36, v76, v36
	v_add_f32_e32 v37, v77, v37
	v_cndmask_b32_e32 v36, v214, v36, vcc
	v_cmp_lt_i32_e32 vcc, s0, v64
	s_movk_i32 s0, 0x61
	v_add_f32_e32 v38, v78, v38
	v_cndmask_b32_e32 v37, v214, v37, vcc
	v_cmp_lt_i32_e32 vcc, s0, v64
	s_movk_i32 s0, 0x62
	v_add_f32_e32 v39, v79, v39
	v_cndmask_b32_e32 v38, v214, v38, vcc
	v_cmp_lt_i32_e32 vcc, s0, v64
	s_movk_i32 s0, 0x67
	v_add_f32_e32 v40, v80, v40
	v_cndmask_b32_e32 v39, v214, v39, vcc
	v_cmp_lt_i32_e32 vcc, s0, v64
	s_movk_i32 s0, 0x68
	v_add_f32_e32 v41, v81, v41
	v_cndmask_b32_e32 v40, v214, v40, vcc
	v_cmp_lt_i32_e32 vcc, s0, v64
	s_movk_i32 s0, 0x69
	v_add_f32_e32 v42, v82, v42
	v_cndmask_b32_e32 v41, v214, v41, vcc
	v_cmp_lt_i32_e32 vcc, s0, v64
	s_movk_i32 s0, 0x6a
	v_add_f32_e32 v43, v83, v43
	v_cndmask_b32_e32 v42, v214, v42, vcc
	v_sub_f32_e32 v36, v36, v75
	v_cmp_lt_i32_e32 vcc, s0, v64
	v_exp_f32_e32 v77, v36
	s_movk_i32 s0, 0x6f
	v_cndmask_b32_e32 v36, v214, v43, vcc
	v_sub_f32_e32 v36, v36, v75
	v_exp_f32_e32 v82, v36
	v_add_f32_e32 v36, v73, v44
	v_cmp_lt_i32_e32 vcc, s0, v64
	s_movk_i32 s0, 0x70
	v_sub_f32_e32 v37, v37, v75
	v_cndmask_b32_e32 v36, v214, v36, vcc
	v_sub_f32_e32 v36, v36, v75
	v_exp_f32_e32 v85, v36
	v_add_f32_e32 v36, v71, v45
	v_cmp_lt_i32_e32 vcc, s0, v64
	s_movk_i32 s0, 0x71
	v_sub_f32_e32 v38, v38, v75
	v_cndmask_b32_e32 v36, v214, v36, vcc
	v_sub_f32_e32 v36, v36, v75
	v_exp_f32_e32 v71, v36
	v_add_f32_e32 v36, v70, v46
	v_cmp_lt_i32_e32 vcc, s0, v64
	s_movk_i32 s0, 0x72
	v_sub_f32_e32 v39, v39, v75
	v_cndmask_b32_e32 v36, v214, v36, vcc
	v_sub_f32_e32 v36, v36, v75
	v_exp_f32_e32 v87, v36
	v_add_f32_e32 v36, v69, v47
	v_cmp_lt_i32_e32 vcc, s0, v64
	s_movk_i32 s0, 0x77
	v_exp_f32_e32 v79, v37
	v_cndmask_b32_e32 v36, v214, v36, vcc
	v_sub_f32_e32 v36, v36, v75
	v_exp_f32_e32 v69, v36
	v_add_f32_e32 v36, v68, v48
	v_cmp_lt_i32_e32 vcc, s0, v64
	s_movk_i32 s0, 0x78
	v_exp_f32_e32 v81, v38
	v_cndmask_b32_e32 v36, v214, v36, vcc
	v_sub_f32_e32 v36, v36, v75
	v_exp_f32_e32 v84, v36
	v_add_f32_e32 v36, v67, v49
	v_cmp_lt_i32_e32 vcc, s0, v64
	s_movk_i32 s0, 0x79
	v_exp_f32_e32 v83, v39
	v_cndmask_b32_e32 v36, v214, v36, vcc
	v_sub_f32_e32 v36, v36, v75
	v_exp_f32_e32 v70, v36
	v_add_f32_e32 v36, v66, v50
	v_cmp_lt_i32_e32 vcc, s0, v64
	s_movk_i32 s0, 0x7a
	ds_read2_b64 v[44:47], v72 offset0:24 offset1:26
	v_cndmask_b32_e32 v36, v214, v36, vcc
	v_sub_f32_e32 v36, v36, v75
	v_exp_f32_e32 v86, v36
	v_add_f32_e32 v36, v65, v51
	v_cmp_lt_i32_e32 vcc, s0, v64
	v_sub_f32_e32 v40, v40, v75
	v_sub_f32_e32 v41, v41, v75
	v_cndmask_b32_e32 v36, v214, v36, vcc
	v_sub_f32_e32 v36, v36, v75
	v_exp_f32_e32 v68, v36
	ds_read2_b64 v[36:39], v74 offset0:24 offset1:26
	v_sub_f32_e32 v42, v42, v75
	v_exp_f32_e32 v76, v40
	v_exp_f32_e32 v78, v41
	v_exp_f32_e32 v80, v42
	v_add_f32_e32 v50, v84, v70
	v_add_f32_e32 v51, v85, v71
	v_cvt_pk_bf16_f32 v40, v77, v79
	v_cvt_pk_bf16_f32 v41, v81, v83
	v_cvt_pk_bf16_f32 v42, v76, v78
	v_cvt_pk_bf16_f32 v43, v80, v82
	v_add_f32_e32 v3, v3, v77
	v_add_f32_e32 v3, v79, v3
	s_waitcnt lgkmcnt(0)
	v_mfma_f32_32x32x16_bf16 v[4:19], v[36:39], v[40:43], v[4:19]
	v_add_f32_e64 v36, v86, v50
	v_add_f32_e64 v37, v87, v51
	v_add_f32_e32 v3, v81, v3
	v_fma_f32 v50, v68, 0.5, v36
	v_fma_f32 v51, v69, 0.5, v37
	ds_read2_b64 v[36:39], v74 offset0:28 offset1:30
	v_add_f32_e32 v3, v83, v3
	v_add_f32_e32 v3, v76, v3
	v_add_f32_e32 v3, v78, v3
	v_mfma_f32_32x32x16_bf16 v[20:35], v[44:47], v[40:43], v[20:35]
	ds_read2_b64 v[40:43], v72 offset0:28 offset1:30
	v_add_f32_e32 v3, v80, v3
	v_mul_f32_e64 v48, v68, 0.5
	v_mul_f32_e64 v49, v69, 0.5
	v_add_f32_e32 v3, v82, v3
	ds_bpermute_b32 v66, v179, v49
	ds_bpermute_b32 v67, v179, v48
	v_mul_f32_e32 v48, 0.5, v82
	v_mul_f32_e32 v49, 0.5, v83
	v_cvt_pk_bf16_f32 v44, v85, v71
	v_cvt_pk_bf16_f32 v45, v87, v69
	v_cvt_pk_bf16_f32 v46, v84, v70
	v_cvt_pk_bf16_f32 v47, v86, v68
	v_add_f32_e32 v3, v85, v3
	ds_bpermute_b32 v49, v179, v49
	ds_bpermute_b32 v48, v179, v48
	s_waitcnt lgkmcnt(5)
	v_mfma_f32_32x32x16_bf16 v[4:19], v[36:39], v[44:47], v[4:19]
	v_add_f32_e32 v3, v71, v3
	v_add_f32_e32 v3, v87, v3
	v_add_f32_e32 v3, v69, v3
	v_add_f32_e64 v64, v76, v78
	v_add_f32_e64 v65, v77, v79
	v_add_f32_e32 v3, v84, v3
	v_add_f32_e32 v64, v80, v64
	v_add_f32_e32 v65, v81, v65
	v_add_f32_e32 v3, v70, v3
	s_waitcnt lgkmcnt(4)
	v_mfma_f32_32x32x16_bf16 v[20:35], v[40:43], v[44:47], v[20:35]
	v_fma_f32 v36, v82, 0.5, v64
	v_fma_f32 v37, v83, 0.5, v65
	s_waitcnt lgkmcnt(0)
	v_cndmask_b32_e64 v38, v48, v49, s[10:11]
	v_cndmask_b32_e64 v39, v49, v98, s[10:11]
	v_add_f32_e32 v3, v86, v3
	v_add_f32_e32 v38, v38, v36
	v_add_f32_e32 v39, v39, v37
	v_cndmask_b32_e64 v37, v66, v48, s[10:11]
	v_cndmask_b32_e64 v36, v67, v66, s[10:11]
	v_add_f32_e32 v36, v50, v36
	v_add_f32_e32 v37, v51, v37
	v_add_f32_e32 v3, v68, v3
.LBB0_1313:
	ds_bpermute_b32 v40, v179, v3
	s_cmp_lt_i32 s48, 16
	s_waitcnt lgkmcnt(0)
	v_add_f32_e32 v3, v3, v40
	v_max_f32_e32 v3, 0xda24260, v3
	v_div_scale_f32 v40, s[0:1], v3, v3, 1.0
	v_rcp_f32_e32 v41, v40
	v_div_scale_f32 v42, vcc, 1.0, v3, 1.0
	s_mov_b64 s[0:1], -1
	v_fma_f32 v43, -v40, v41, 1.0
	v_fmac_f32_e32 v41, v43, v41
	v_mul_f32_e32 v43, v42, v41
	v_fma_f32 v44, -v40, v43, v42
	v_fmac_f32_e32 v43, v44, v41
	v_fma_f32 v40, -v40, v43, v42
	v_div_fmas_f32 v40, v40, v41, v43
	v_div_fixup_f32 v40, v40, v3, 1.0
	v_mul_f32_e32 v41, v54, v40
	v_mul_f32_e32 v4, v4, v40
	v_mul_f32_e32 v5, v5, v40
	v_mul_f32_e32 v6, v6, v40
	v_mul_f32_e32 v7, v7, v40
	v_mul_f32_e32 v20, v20, v40
	v_mul_f32_e32 v21, v21, v40
	v_mul_f32_e32 v22, v22, v40
	v_mul_f32_e32 v23, v23, v40
	v_mul_f32_e32 v6, v132, v6
	v_mul_f32_e32 v7, v132, v7
	v_mul_f32_e32 v4, v132, v4
	v_mul_f32_e32 v5, v132, v5
	v_mul_f32_e32 v8, v8, v40
	v_mul_f32_e32 v9, v9, v40
	v_mul_f32_e32 v10, v10, v40
	v_mul_f32_e32 v11, v11, v40
	ds_write_b128 v193, v[4:7]
	v_mul_f32_e32 v6, v132, v22
	v_mul_f32_e32 v7, v132, v23
	v_mul_f32_e32 v4, v132, v20
	v_mul_f32_e32 v5, v132, v21
	v_mul_f32_e32 v24, v24, v40
	v_mul_f32_e32 v25, v25, v40
	v_mul_f32_e32 v26, v26, v40
	v_mul_f32_e32 v27, v27, v40
	ds_write_b128 v193, v[4:7] offset:128
	v_mul_f32_e32 v6, v132, v10
	v_mul_f32_e32 v7, v132, v11
	v_mul_f32_e32 v4, v132, v8
	v_mul_f32_e32 v5, v132, v9
	v_mul_f32_e32 v12, v12, v40
	v_mul_f32_e32 v13, v13, v40
	v_mul_f32_e32 v14, v14, v40
	v_mul_f32_e32 v15, v15, v40
	ds_write_b128 v193, v[4:7] offset:32
	v_mul_f32_e32 v6, v132, v26
	v_mul_f32_e32 v7, v132, v27
	v_mul_f32_e32 v4, v132, v24
	v_mul_f32_e32 v5, v132, v25
	v_mul_f32_e32 v28, v28, v40
	v_mul_f32_e32 v29, v29, v40
	v_mul_f32_e32 v30, v30, v40
	v_mul_f32_e32 v31, v31, v40
	ds_write_b128 v193, v[4:7] offset:160
	v_mul_f32_e32 v6, v132, v14
	v_mul_f32_e32 v7, v132, v15
	v_mul_f32_e32 v4, v132, v12
	v_mul_f32_e32 v5, v132, v13
	v_mul_f32_e32 v16, v16, v40
	v_mul_f32_e32 v17, v17, v40
	v_mul_f32_e32 v18, v18, v40
	v_mul_f32_e32 v19, v19, v40
	ds_write_b128 v193, v[4:7] offset:64
	v_mul_f32_e32 v6, v132, v30
	v_mul_f32_e32 v7, v132, v31
	v_mul_f32_e32 v4, v132, v28
	v_mul_f32_e32 v5, v132, v29
	v_mul_f32_e32 v32, v32, v40
	v_mul_f32_e32 v33, v33, v40
	v_mul_f32_e32 v34, v34, v40
	v_mul_f32_e32 v35, v35, v40
	ds_write_b128 v193, v[4:7] offset:192
	v_mul_f32_e32 v6, v132, v18
	v_mul_f32_e32 v7, v132, v19
	v_mul_f32_e32 v4, v132, v16
	v_mul_f32_e32 v5, v132, v17
	ds_write_b128 v193, v[4:7] offset:96
	v_mul_f32_e32 v6, v132, v34
	v_mul_f32_e32 v7, v132, v35
	v_mul_f32_e32 v4, v132, v32
	v_mul_f32_e32 v5, v132, v33
	v_mul_f32_e32 v3, v55, v40
	ds_write_b128 v193, v[4:7] offset:224
	v_add_u32_e32 v4, 0x8c00, v198
	v_mul_f32_e32 v42, v53, v40
	v_mul_f32_e32 v43, v52, v40
	v_mul_f32_e32 v44, v59, v40
	v_mul_f32_e32 v45, v58, v40
	v_mul_f32_e32 v46, v57, v40
	v_mul_f32_e32 v47, v56, v40
	v_mul_f32_e32 v48, v63, v40
	v_mul_f32_e32 v49, v62, v40
	v_mul_f32_e32 v50, v61, v40
	v_mul_f32_e32 v51, v60, v40
	v_mul_f32_e32 v39, v39, v40
	v_mul_f32_e32 v38, v38, v40
	v_mul_f32_e32 v37, v37, v40
	v_mul_f32_e32 v36, v36, v40
	ds_write2_b32 v4, v3, v41 offset1:2
	ds_write2_b32 v4, v42, v43 offset0:4 offset1:6
	ds_write2_b32 v4, v44, v45 offset0:8 offset1:10
	ds_write2_b32 v4, v46, v47 offset0:12 offset1:14
	ds_write2_b32 v4, v48, v49 offset0:16 offset1:18
	ds_write2_b32 v4, v50, v51 offset0:20 offset1:22
	ds_write2_b32 v4, v39, v38 offset0:24 offset1:26
	ds_write2_b32 v4, v37, v36 offset0:28 offset1:30
	s_waitcnt lgkmcnt(0)
	s_barrier
	s_cbranch_scc0 .LBB0_1315
	s_lshl_b32 s0, 2, s48
	s_add_i32 s44, s0, -1
	s_mov_b64 s[0:1], 0

.LBB0_1374:
	v_cndmask_b32_e64 v3, v133, v134, s[28:29]
	v_div_scale_f32 v37, s[2:3], v36, v36, v3
	v_rcp_f32_e32 v42, v37
	v_div_scale_f32 v38, vcc, v3, v36, v3
	s_xor_b64 s[0:1], s[18:19], -1
	v_fma_f32 v39, -v37, v42, 1.0
	v_fmac_f32_e32 v42, v39, v42
	v_mul_f32_e32 v43, v38, v42
	v_fma_f32 v39, -v37, v43, v38
	v_fmac_f32_e32 v43, v39, v42
	v_fma_f32 v37, -v37, v43, v38
	ds_read_b128 v[38:41], v193
	v_div_fmas_f32 v37, v37, v42, v43
	v_div_fixup_f32 v50, v37, v36, v3
	ds_read_b128 v[42:45], v193 offset:128
	ds_read_b128 v[46:49], v193 offset:32
	s_mov_b64 s[18:19], 0
	s_waitcnt lgkmcnt(2)
	v_fma_f32 v20, v20, v50, v38
	v_fma_f32 v21, v21, v50, v39
	ds_read_b128 v[36:39], v193 offset:160
	v_fma_f32 v22, v22, v50, v40
	v_fma_f32 v23, v23, v50, v41
	s_waitcnt lgkmcnt(2)
	v_fma_f32 v6, v6, v50, v44
	v_fma_f32 v7, v7, v50, v45
	v_fma_f32 v4, v4, v50, v42
	v_fma_f32 v5, v5, v50, v43
	ds_write_b128 v193, v[20:23]
	ds_write_b128 v193, v[4:7] offset:128
	s_waitcnt lgkmcnt(3)
	v_fma_f32 v6, v26, v50, v48
	v_fma_f32 v7, v27, v50, v49
	v_fma_f32 v4, v24, v50, v46
	v_fma_f32 v5, v25, v50, v47
	s_waitcnt lgkmcnt(2)
	v_fma_f32 v10, v10, v50, v38
	v_fma_f32 v11, v11, v50, v39
	v_fma_f32 v8, v8, v50, v36
	v_fma_f32 v9, v9, v50, v37
	ds_read_b128 v[20:23], v193 offset:64
	ds_write_b128 v193, v[4:7] offset:32
	ds_write_b128 v193, v[8:11] offset:160
	ds_read_b128 v[4:7], v193 offset:192
	ds_read_b128 v[8:11], v193 offset:96
	ds_read_b128 v[24:27], v193 offset:224
	s_andn2_b64 vcc, exec, s[0:1]
	s_waitcnt lgkmcnt(5)
	v_fma_f32 v22, v30, v50, v22
	v_fma_f32 v23, v31, v50, v23
	v_fma_f32 v20, v28, v50, v20
	v_fma_f32 v21, v29, v50, v21
	s_waitcnt lgkmcnt(2)
	v_fma_f32 v6, v14, v50, v6
	v_fma_f32 v7, v15, v50, v7
	v_fma_f32 v4, v12, v50, v4
	v_fma_f32 v5, v13, v50, v5
	ds_write_b128 v193, v[20:23] offset:64
	ds_write_b128 v193, v[4:7] offset:192
	s_waitcnt lgkmcnt(3)
	v_fma_f32 v6, v34, v50, v10
	v_fma_f32 v7, v35, v50, v11
	v_fma_f32 v4, v32, v50, v8
	v_fma_f32 v5, v33, v50, v9
	s_mov_b64 s[28:29], -1
	s_waitcnt lgkmcnt(2)
	v_fma_f32 v10, v18, v50, v26
	v_fma_f32 v11, v19, v50, v27
	v_fma_f32 v8, v16, v50, v24
	v_fma_f32 v9, v17, v50, v25
	ds_write_b128 v193, v[4:7] offset:96
	ds_write_b128 v193, v[8:11] offset:224
	s_waitcnt lgkmcnt(0)
	s_barrier
	s_cbranch_vccz .LBB0_1276

.LBB0_1416:
	v_lshrrev_b32_e32 v3, s42, v159
	v_and_b32_e32 v3, 1, v3
	v_cmp_eq_u32_e64 s[2:3], 1, v3
	s_or_b64 s[8:9], s[28:29], s[2:3]
	v_cndmask_b32_e64 v3, 0, 1, s[8:9]
	v_cmp_ne_u32_e32 vcc, 0, v3
	s_cbranch_vccz .LBB0_1443
	s_cmp_lt_i32 s42, s48
	s_cselect_b64 s[24:25], -1, 0
	s_cmp_ge_i32 s42, s48
	s_cselect_b64 s[30:31], -1, 0
	s_mov_b64 s[26:27], -1
	s_and_b64 vcc, exec, s[20:21]
	v_lshl_or_b32 v165, s42, 6, v136
	s_cbranch_vccz .LBB0_1426
	v_sub_u32_e32 v68, v161, v165
	v_cvt_f32_i32_e32 v221, v68
	v_add_u32_e32 v219, s38, v176
	s_and_b64 vcc, exec, s[30:31]
	v_add_u32_e32 v69, v219, v177
	v_add_u32_e32 v220, v219, v178
	s_cbranch_vccz .LBB0_1422
	v_mov_b32_e32 v3, v157
	ds_read_b128 v[52:55], v69
	ds_read_b128 v[56:59], v69 offset:32
	v_mul_f32_e64 v36, v221, -v3
	v_cndmask_b32_e64 v66, v214, v36, s[2:3]
	v_mov_b32_e32 v74, v3
	v_fma_f32 v38, 0, v3, v66
	v_fmamk_f32 v42, v3, 0x41000000, v66
	v_fmamk_f32 v46, v3, 0x41800000, v66
	v_fmamk_f32 v50, v3, 0x41c00000, v66
	v_add_f32_e32 v36, v2, v38
	v_add_f32_e32 v37, v3, v38
	v_fma_f32 v39, v74, s65, v38
	v_fma_f32 v38, v74, s64, v38
	v_add_f32_e32 v40, v2, v42
	v_add_f32_e32 v41, v3, v42
	v_fma_f32 v43, v74, s65, v42
	v_fma_f32 v42, v74, s64, v42
	v_add_f32_e32 v44, v2, v46
	v_add_f32_e32 v45, v3, v46
	v_fma_f32 v47, v74, s65, v46
	v_fma_f32 v46, v74, s64, v46
	v_add_f32_e32 v48, v2, v50
	v_add_f32_e32 v49, v3, v50
	v_fma_f32 v51, v74, s65, v50
	v_fma_f32 v50, v74, s64, v50
	v_fmamk_f32 v62, v3, 0x42200000, v66
	v_fmamk_f32 v64, v3, 0x42400000, v66
	s_waitcnt lgkmcnt(1)
	v_mfma_f32_32x32x16_bf16 v[36:51], v[52:55], v[100:103], v[36:51]
	v_cmp_lt_i32_e32 vcc, -1, v68
	s_waitcnt lgkmcnt(0)
	v_mfma_f32_32x32x16_bf16 v[36:51], v[56:59], v[104:107], v[36:51]
	ds_read_b128 v[52:55], v69 offset:64
	ds_read_b128 v[58:61], v69 offset:96
	ds_read_b128 v[70:73], v220
	v_add_f32_e64 v56, v2, v62
	v_add_f32_e64 v57, v3, v62
	s_waitcnt lgkmcnt(2)
	v_mfma_f32_32x32x16_bf16 v[36:51], v[52:55], v[108:111], v[36:51]
	v_fmamk_f32 v54, v3, 0x42000000, v66
	v_fmac_f32_e32 v66, 0x42600000, v3
	v_add_f32_e64 v52, v2, v54
	v_add_f32_e64 v53, v3, v54
	v_fma_f32 v55, v74, s65, v54
	v_fma_f32 v54, v74, s64, v54
	s_waitcnt lgkmcnt(1)
	v_mfma_f32_32x32x16_bf16 v[36:51], v[58:61], v[112:115], v[36:51]
	v_fma_f32 v58, v74, s64, v62
	v_fma_f32 v59, v74, s65, v62
	v_add_f32_e64 v60, v2, v64
	v_add_f32_e64 v61, v3, v64
	v_fma_f32 v62, v74, s64, v64
	v_fma_f32 v63, v74, s65, v64
	v_add_f32_e32 v64, v2, v66
	v_add_f32_e32 v65, v3, v66
	v_fma_f32 v67, v74, s65, v66
	v_fma_f32 v66, v74, s64, v66
	ds_read_b128 v[74:77], v220 offset:32
	s_nop 2
	v_cndmask_b32_e32 v86, v214, v36, vcc
	s_waitcnt lgkmcnt(1)
	v_mfma_f32_32x32x16_bf16 v[52:67], v[70:73], v[100:103], v[52:67]
	ds_read_b128 v[70:73], v220 offset:64
	ds_read_b128 v[78:81], v220 offset:96
	v_cmp_lt_i32_e32 vcc, 0, v68
	s_nop 1
	v_cndmask_b32_e32 v87, v214, v37, vcc
	v_cmp_lt_i32_e32 vcc, 1, v68
	v_max3_f32 v3, v86, s97, v87
	s_waitcnt lgkmcnt(2)
	v_mfma_f32_32x32x16_bf16 v[52:67], v[74:77], v[104:107], v[52:67]
	v_cndmask_b32_e32 v94, v214, v38, vcc
	v_cmp_lt_i32_e32 vcc, 2, v68
	s_nop 1
	v_cndmask_b32_e32 v95, v214, v39, vcc
	v_cmp_lt_i32_e32 vcc, 7, v68
	v_max3_f32 v3, v3, v94, v95
	s_waitcnt lgkmcnt(1)
	v_mfma_f32_32x32x16_bf16 v[52:67], v[70:73], v[108:111], v[52:67]
	v_cndmask_b32_e32 v98, v214, v40, vcc
	v_cmp_lt_i32_e32 vcc, 8, v68
	s_nop 1
	v_cndmask_b32_e32 v99, v214, v41, vcc
	v_cmp_lt_i32_e32 vcc, 9, v68
	v_max3_f32 v3, v3, v98, v99
	s_waitcnt lgkmcnt(0)
	v_mfma_f32_32x32x16_bf16 v[52:67], v[78:81], v[112:115], v[52:67]
	v_cndmask_b32_e32 v96, v214, v42, vcc
	v_cmp_lt_i32_e32 vcc, 10, v68
	s_nop 1
	v_cndmask_b32_e32 v97, v214, v43, vcc
	v_cmp_lt_i32_e32 vcc, 15, v68
	v_max3_f32 v3, v3, v96, v97
	s_nop 0
	v_cndmask_b32_e32 v170, v214, v44, vcc
	v_cmp_lt_i32_e32 vcc, 16, v68
	s_nop 1
	v_cndmask_b32_e32 v171, v214, v45, vcc
	v_cmp_lt_i32_e32 vcc, 17, v68
	v_max3_f32 v3, v3, v170, v171
	s_nop 0
	v_cndmask_b32_e32 v90, v214, v46, vcc
	v_cmp_lt_i32_e32 vcc, 18, v68
	s_nop 1
	v_cndmask_b32_e32 v91, v214, v47, vcc
	v_cmp_lt_i32_e32 vcc, 23, v68
	v_max3_f32 v3, v3, v90, v91
	s_nop 0
	v_cndmask_b32_e32 v92, v214, v48, vcc
	v_cmp_lt_i32_e32 vcc, 24, v68
	s_nop 1
	v_cndmask_b32_e32 v93, v214, v49, vcc
	v_cmp_lt_i32_e32 vcc, 25, v68
	v_max3_f32 v3, v3, v92, v93
	s_nop 0
	v_cndmask_b32_e32 v88, v214, v50, vcc
	v_cmp_lt_i32_e32 vcc, 26, v68
	s_nop 1
	v_cndmask_b32_e32 v89, v214, v51, vcc
	v_cmp_lt_i32_e32 vcc, 31, v68
	v_max3_f32 v3, v3, v88, v89
	s_nop 0
	v_cndmask_b32_e32 v84, v214, v52, vcc
	v_cmp_lt_i32_e32 vcc, 32, v68
	s_nop 1
	v_cndmask_b32_e32 v85, v214, v53, vcc
	v_cmp_lt_i32_e32 vcc, 33, v68
	v_max3_f32 v3, v3, v84, v85
	s_nop 0
	v_cndmask_b32_e32 v82, v214, v54, vcc
	v_cmp_lt_i32_e32 vcc, 34, v68
	s_nop 1
	v_cndmask_b32_e32 v83, v214, v55, vcc
	v_cmp_lt_i32_e32 vcc, 39, v68
	v_max3_f32 v3, v3, v82, v83
	s_nop 0
	v_cndmask_b32_e32 v80, v214, v56, vcc
	v_cmp_lt_i32_e32 vcc, 40, v68
	s_nop 1
	v_cndmask_b32_e32 v81, v214, v57, vcc
	v_cmp_lt_i32_e32 vcc, 41, v68
	v_max3_f32 v3, v3, v80, v81
	s_nop 0
	v_cndmask_b32_e32 v78, v214, v58, vcc
	v_cmp_lt_i32_e32 vcc, 42, v68
	s_nop 1
	v_cndmask_b32_e32 v79, v214, v59, vcc
	v_cmp_lt_i32_e32 vcc, 47, v68
	v_max3_f32 v3, v3, v78, v79
	s_nop 0
	v_cndmask_b32_e32 v76, v214, v60, vcc
	v_cmp_lt_i32_e32 vcc, 48, v68
	s_nop 1
	v_cndmask_b32_e32 v77, v214, v61, vcc
	v_cmp_lt_i32_e32 vcc, 49, v68
	v_max3_f32 v3, v3, v76, v77
	s_nop 0
	v_cndmask_b32_e32 v74, v214, v62, vcc
	v_cmp_lt_i32_e32 vcc, 50, v68
	s_nop 1
	v_cndmask_b32_e32 v75, v214, v63, vcc
	v_cmp_lt_i32_e32 vcc, 55, v68
	v_max3_f32 v3, v3, v74, v75
	s_nop 0
	v_cndmask_b32_e32 v70, v214, v64, vcc
	v_cmp_lt_i32_e32 vcc, 56, v68
	s_nop 1
	v_cndmask_b32_e32 v71, v214, v65, vcc
	v_cmp_lt_i32_e32 vcc, 57, v68
	v_max3_f32 v3, v3, v70, v71
	s_nop 0
	v_cndmask_b32_e32 v72, v214, v66, vcc
	v_cmp_lt_i32_e32 vcc, 58, v68
	s_nop 1
	v_cndmask_b32_e32 v73, v214, v67, vcc
	v_max3_f32 v3, v3, v72, v73
	ds_bpermute_b32 v36, v179, v3
	v_mov_b64_e32 v[66:67], v[18:19]
	v_mov_b64_e32 v[64:65], v[16:17]
	v_mov_b64_e32 v[62:63], v[14:15]
	v_mov_b64_e32 v[60:61], v[12:13]
	s_waitcnt lgkmcnt(0)
	v_max_f32_e32 v36, v36, v36
	v_max_f32_e32 v3, v3, v36
	v_max3_f32 v132, v218, v3, s46
	v_sub_f32_e32 v3, v218, v132
	v_exp_f32_e32 v68, v3
	v_mov_b64_e32 v[50:51], v[34:35]
	v_mov_b64_e32 v[48:49], v[32:33]
	v_mov_b64_e32 v[46:47], v[30:31]
	v_cmp_eq_f32_e32 vcc, 1.0, v68
	s_cmp_eq_u64 vcc, exec
	v_mov_b64_e32 v[44:45], v[28:29]
	v_mov_b64_e32 v[42:43], v[26:27]
	v_mov_b64_e32 v[40:41], v[24:25]
	v_mov_b64_e32 v[38:39], v[22:23]
	v_mov_b64_e32 v[36:37], v[20:21]
	v_mov_b64_e32 v[58:59], v[10:11]
	v_mov_b64_e32 v[56:57], v[8:9]
	v_mov_b64_e32 v[54:55], v[6:7]
	v_mov_b64_e32 v[52:53], v[4:5]
	s_cbranch_scc1 .LBB0_1421
	v_mul_f32_e32 v50, v34, v68
	v_mul_f32_e32 v51, v35, v68
	v_mul_f32_e32 v48, v32, v68
	v_mul_f32_e32 v49, v33, v68
	v_mul_f32_e32 v46, v30, v68
	v_mul_f32_e32 v47, v31, v68
	v_mul_f32_e32 v44, v28, v68
	v_mul_f32_e32 v45, v29, v68
	v_mul_f32_e32 v42, v26, v68
	v_mul_f32_e32 v43, v27, v68
	v_mul_f32_e32 v40, v24, v68
	v_mul_f32_e32 v41, v25, v68
	v_mul_f32_e32 v38, v22, v68
	v_mul_f32_e32 v39, v23, v68
	v_mul_f32_e32 v36, v20, v68
	v_mul_f32_e32 v37, v21, v68
	v_mul_f32_e32 v66, v18, v68
	v_mul_f32_e32 v67, v19, v68
	v_mul_f32_e32 v64, v16, v68
	v_mul_f32_e32 v65, v17, v68
	v_mul_f32_e32 v62, v14, v68
	v_mul_f32_e32 v63, v15, v68
	v_mul_f32_e32 v60, v12, v68
	v_mul_f32_e32 v61, v13, v68
	v_mul_f32_e32 v58, v10, v68
	v_mul_f32_e32 v59, v11, v68
	v_mul_f32_e32 v56, v8, v68
	v_mul_f32_e32 v57, v9, v68
	v_mul_f32_e32 v54, v6, v68
	v_mul_f32_e32 v55, v7, v68
	v_mul_f32_e32 v52, v4, v68
	v_mul_f32_e32 v53, v5, v68
.LBB0_1421:
	v_sub_f32_e32 v94, v94, v132
	v_sub_f32_e32 v95, v95, v132
	v_lshl_add_u32 v3, v136, 1, s38
	v_exp_f32_e32 v230, v94
	v_exp_f32_e32 v231, v95
	v_sub_f32_e32 v94, v98, v132
	v_sub_f32_e32 v95, v99, v132
	v_sub_f32_e32 v86, v86, v132
	v_sub_f32_e32 v87, v87, v132
	v_exp_f32_e32 v98, v94
	v_exp_f32_e32 v99, v95
	v_sub_f32_e32 v94, v96, v132
	v_sub_f32_e32 v95, v97, v132
	v_exp_f32_e32 v86, v86
	v_exp_f32_e32 v232, v94
	v_add_u32_e32 v94, v3, v190
	v_add_u32_e32 v186, 0x2000, v94
	v_exp_f32_e32 v233, v95
	ds_read2_b64 v[94:97], v186 offset0:128 offset1:130
	v_add_u32_e32 v3, v3, v191
	v_add_u32_e32 v3, 0x2000, v3
	ds_read2_b64 v[226:229], v3 offset0:128 offset1:130
	v_exp_f32_e32 v87, v87
	v_sub_f32_e32 v90, v90, v132
	v_sub_f32_e32 v91, v91, v132
	v_cvt_pk_bf16_f32 v223, v230, v231
	v_exp_f32_e32 v234, v90
	v_exp_f32_e32 v235, v91
	v_sub_f32_e32 v90, v92, v132
	v_sub_f32_e32 v91, v93, v132
	v_cvt_pk_bf16_f32 v222, v86, v87
	v_cvt_pk_bf16_f32 v224, v98, v99
	v_cvt_pk_bf16_f32 v225, v232, v233
	v_exp_f32_e32 v236, v90
	v_exp_f32_e32 v237, v91
	ds_read2_b64 v[90:93], v186 offset0:132 offset1:134
	s_waitcnt lgkmcnt(2)
	v_mfma_f32_32x32x16_bf16 v[36:51], v[94:97], v[222:225], v[36:51]
	v_add_f32_e64 v170, v170, -v132
	v_add_f32_e64 v171, v171, -v132
	v_add_f32_e64 v88, v88, -v132
	v_add_f32_e64 v89, v89, -v132
	v_exp_f32_e32 v170, v170
	v_exp_f32_e32 v171, v171
	v_cvt_pk_bf16_f32 v95, v234, v235
	v_cvt_pk_bf16_f32 v96, v236, v237
	v_cvt_pk_bf16_f32 v94, v170, v171
	s_waitcnt lgkmcnt(1)
	v_mfma_f32_32x32x16_bf16 v[52:67], v[226:229], v[222:225], v[52:67]
	v_exp_f32_e32 v222, v88
	v_exp_f32_e32 v223, v89
	s_nop 0
	v_cvt_pk_bf16_f32 v97, v222, v223
	s_waitcnt lgkmcnt(0)
	s_nop 0
	v_mfma_f32_32x32x16_bf16 v[36:51], v[90:93], v[94:97], v[36:51]
	ds_read2_b64 v[88:91], v3 offset0:132 offset1:134
	s_waitcnt lgkmcnt(0)
	v_mfma_f32_32x32x16_bf16 v[52:67], v[88:91], v[94:97], v[52:67]
	v_add_f32_e64 v80, v80, -v132
	v_add_f32_e64 v81, v81, -v132
	v_add_f32_e64 v78, v78, -v132
	v_add_f32_e64 v79, v79, -v132
	v_exp_f32_e32 v94, v80
	v_exp_f32_e32 v95, v81
	v_exp_f32_e32 v96, v78
	v_exp_f32_e32 v97, v79
	v_sub_f32_e32 v80, v76, v132
	v_sub_f32_e32 v81, v77, v132
	ds_read2_b64 v[76:79], v186 offset0:136 offset1:138
	v_sub_f32_e32 v84, v84, v132
	v_sub_f32_e32 v85, v85, v132
	v_sub_f32_e32 v82, v82, v132
	v_sub_f32_e32 v83, v83, v132
	ds_read2_b64 v[88:91], v3 offset0:136 offset1:138
	v_exp_f32_e32 v84, v84
	v_exp_f32_e32 v85, v85
	v_exp_f32_e32 v92, v82
	v_exp_f32_e32 v93, v83
	v_sub_f32_e32 v74, v74, v132
	v_sub_f32_e32 v75, v75, v132
	v_sub_f32_e32 v70, v70, v132
	v_sub_f32_e32 v71, v71, v132
	v_exp_f32_e32 v224, v80
	v_exp_f32_e32 v225, v81
	v_cvt_pk_bf16_f32 v80, v84, v85
	v_cvt_pk_bf16_f32 v81, v92, v93
	v_cvt_pk_bf16_f32 v82, v94, v95
	v_cvt_pk_bf16_f32 v83, v96, v97
	v_exp_f32_e32 v226, v74
	v_exp_f32_e32 v227, v75
	v_exp_f32_e32 v228, v70
	v_exp_f32_e32 v229, v71
	v_sub_f32_e32 v74, v72, v132
	v_sub_f32_e32 v75, v73, v132
	ds_read2_b64 v[70:73], v186 offset0:140 offset1:142
	s_waitcnt lgkmcnt(2)
	v_mfma_f32_32x32x16_bf16 v[36:51], v[76:79], v[80:83], v[36:51]
	v_cvt_pk_bf16_f32 v78, v224, v225
	v_cvt_pk_bf16_f32 v79, v226, v227
	s_mov_b64 s[26:27], 0
	s_waitcnt lgkmcnt(1)
	v_mfma_f32_32x32x16_bf16 v[52:67], v[88:91], v[80:83], v[52:67]
	v_exp_f32_e32 v82, v74
	v_exp_f32_e32 v83, v75
	v_cvt_pk_bf16_f32 v80, v228, v229
	ds_read2_b64 v[74:77], v3 offset0:140 offset1:142
	v_cvt_pk_bf16_f32 v81, v82, v83
	s_waitcnt lgkmcnt(1)
	s_nop 0
	v_mfma_f32_32x32x16_bf16 v[36:51], v[70:73], v[78:81], v[36:51]
	v_add_f32_e64 v70, v86, 0
	v_add_f32_e64 v71, v87, 0
	v_add_f32_e64 v70, v230, v70
	v_add_f32_e64 v71, v231, v71
	v_add_f32_e64 v70, v98, v70
	v_add_f32_e64 v71, v99, v71
	v_add_f32_e32 v70, v232, v70
	v_add_f32_e32 v71, v233, v71
	s_waitcnt lgkmcnt(0)
	v_mfma_f32_32x32x16_bf16 v[52:67], v[74:77], v[78:81], v[52:67]
	v_add_f32_e64 v70, v170, v70
	v_add_f32_e64 v71, v171, v71
	v_add_f32_e64 v70, v234, v70
	v_add_f32_e64 v71, v235, v71
	v_add_f32_e64 v70, v236, v70
	v_add_f32_e64 v71, v237, v71
	v_add_f32_e32 v70, v222, v70
	v_add_f32_e32 v71, v223, v71
	s_nop 0
	v_add_f32_e32 v70, v84, v70
	v_add_f32_e32 v71, v85, v71
	s_nop 0
	v_add_f32_e32 v70, v92, v70
	v_add_f32_e32 v71, v93, v71
	s_nop 0
	v_add_f32_e32 v70, v94, v70
	v_add_f32_e32 v71, v95, v71
	s_nop 0
	v_add_f32_e32 v70, v96, v70
	v_add_f32_e32 v71, v97, v71
	s_nop 0
	v_add_f32_e32 v70, v224, v70
	v_add_f32_e32 v71, v225, v71
	s_nop 0
	v_add_f32_e32 v70, v226, v70
	v_add_f32_e32 v71, v227, v71
	s_nop 0
	v_add_f32_e32 v70, v228, v70
	v_add_f32_e32 v71, v229, v71
	s_nop 0
	v_add_f32_e32 v70, v82, v70
	v_add_f32_e32 v71, v83, v71
	s_nop 0
	v_add_f32_e32 v3, v70, v71
	ds_bpermute_b32 v70, v179, v3
	s_waitcnt lgkmcnt(0)
	v_add_f32_e32 v3, v3, v70
	v_fmac_f32_e32 v3, v217, v68
.LBB0_1422:
	s_and_b64 vcc, exec, s[26:27]
	s_cbranch_vccz .LBB0_1441
	v_mov_b32_e32 v3, v157
	s_nop 0
	v_mul_f32_e64 v36, v221, -v3
	v_cndmask_b32_e64 v44, v214, v36, s[2:3]
	v_mov_b32_e32 v46, v3
	v_fma_f32 v36, 0, v3, v44
	v_add_f32_e32 v84, v2, v36
	v_add_f32_e32 v85, v3, v36
	v_fma_f32 v86, v46, s64, v36
	v_fma_f32 v87, v46, s65, v36
	ds_read_b128 v[36:39], v69
	v_fmamk_f32 v40, v3, 0x41000000, v44
	v_add_f32_e32 v88, v2, v40
	v_add_f32_e32 v89, v3, v40
	v_fma_f32 v90, v46, s64, v40
	v_fma_f32 v91, v46, s65, v40
	v_fmamk_f32 v40, v3, 0x41800000, v44
	v_add_f32_e32 v92, v2, v40
	v_add_f32_e32 v93, v3, v40
	v_fma_f32 v94, v46, s64, v40
	v_fma_f32 v95, v46, s65, v40
	v_fmamk_f32 v40, v3, 0x41c00000, v44
	v_add_f32_e32 v96, v2, v40
	v_add_f32_e32 v97, v3, v40
	v_fma_f32 v98, v46, s64, v40
	v_fma_f32 v99, v46, s65, v40
	ds_read_b128 v[40:43], v69 offset:32
	v_fmamk_f32 v48, v3, 0x42000000, v44
	s_waitcnt lgkmcnt(1)
	v_mfma_f32_32x32x16_bf16 v[84:99], v[36:39], v[100:103], v[84:99]
	v_fmamk_f32 v50, v3, 0x42200000, v44
	v_fmamk_f32 v52, v3, 0x42400000, v44
	v_fmac_f32_e32 v44, 0x42600000, v3
	v_fma_f32 v70, v46, s64, v48
	v_fma_f32 v71, v46, s65, v48
	v_add_f32_e32 v72, v2, v50
	v_add_f32_e32 v73, v3, v50
	v_fma_f32 v74, v46, s64, v50
	v_fma_f32 v75, v46, s65, v50
	v_add_f32_e32 v76, v2, v52
	v_add_f32_e32 v77, v3, v52
	s_waitcnt lgkmcnt(0)
	v_mfma_f32_32x32x16_bf16 v[84:99], v[40:43], v[104:107], v[84:99]
	ds_read_b128 v[36:39], v69 offset:64
	ds_read_b128 v[40:43], v69 offset:96
	v_add_f32_e64 v68, v2, v48
	v_add_f32_e64 v69, v3, v48
	v_fma_f32 v78, v46, s64, v52
	v_fma_f32 v79, v46, s65, v52
	v_add_f32_e32 v80, v2, v44
	v_add_f32_e32 v81, v3, v44
	v_fma_f32 v82, v46, s64, v44
	v_fma_f32 v83, v46, s65, v44
	v_mov_b64_e32 v[66:67], v[18:19]
	v_mov_b64_e32 v[64:65], v[16:17]
	s_waitcnt lgkmcnt(1)
	v_mfma_f32_32x32x16_bf16 v[84:99], v[36:39], v[108:111], v[84:99]
	ds_read_b128 v[36:39], v220
	v_mov_b64_e32 v[62:63], v[14:15]
	v_mov_b64_e32 v[60:61], v[12:13]
	v_mov_b64_e32 v[58:59], v[10:11]
	v_mov_b64_e32 v[56:57], v[8:9]
	v_mov_b64_e32 v[54:55], v[6:7]
	v_mov_b64_e32 v[52:53], v[4:5]
	s_waitcnt lgkmcnt(1)
	v_mfma_f32_32x32x16_bf16 v[84:99], v[40:43], v[112:115], v[84:99]
	ds_read_b128 v[40:43], v220 offset:32
	s_waitcnt lgkmcnt(1)
	v_mfma_f32_32x32x16_bf16 v[68:83], v[36:39], v[100:103], v[68:83]
	s_nop 8
	v_max3_f32 v3, v84, s97, v85
	v_max3_f32 v3, v3, v86, v87
	v_max3_f32 v3, v3, v88, v89
	v_max3_f32 v3, v3, v90, v91
	v_max3_f32 v3, v3, v92, v93
	v_max3_f32 v3, v3, v94, v95
	v_max3_f32 v3, v3, v96, v97
	s_waitcnt lgkmcnt(0)
	v_mfma_f32_32x32x16_bf16 v[68:83], v[40:43], v[104:107], v[68:83]
	ds_read_b128 v[36:39], v220 offset:64
	ds_read_b128 v[40:43], v220 offset:96
	v_max3_f32 v3, v3, v98, v99
	s_waitcnt lgkmcnt(1)
	v_mfma_f32_32x32x16_bf16 v[68:83], v[36:39], v[108:111], v[68:83]
	s_waitcnt lgkmcnt(0)
	v_mfma_f32_32x32x16_bf16 v[68:83], v[40:43], v[112:115], v[68:83]
	s_nop 11
	v_max3_f32 v3, v3, v68, v69
	v_max3_f32 v3, v3, v70, v71
	v_max3_f32 v3, v3, v72, v73
	v_max3_f32 v3, v3, v74, v75
	v_max3_f32 v3, v3, v76, v77
	v_max3_f32 v3, v3, v78, v79
	v_max3_f32 v3, v3, v80, v81
	v_max3_f32 v3, v3, v82, v83
	ds_bpermute_b32 v36, v179, v3
	s_waitcnt lgkmcnt(0)
	v_max_f32_e32 v36, v36, v36
	v_max_f32_e32 v3, v3, v36
	v_max3_f32 v132, v218, v3, s46
	v_sub_f32_e32 v3, v218, v132
	v_exp_f32_e32 v170, v3
	v_mov_b64_e32 v[50:51], v[34:35]
	v_mov_b64_e32 v[48:49], v[32:33]
	v_mov_b64_e32 v[46:47], v[30:31]
	v_cmp_eq_f32_e32 vcc, 1.0, v170
	s_cmp_eq_u64 vcc, exec
	v_mov_b64_e32 v[44:45], v[28:29]
	v_mov_b64_e32 v[42:43], v[26:27]
	v_mov_b64_e32 v[40:41], v[24:25]
	v_mov_b64_e32 v[38:39], v[22:23]
	v_mov_b64_e32 v[36:37], v[20:21]
	s_cbranch_scc1 .LBB0_1425
	v_mul_f32_e32 v50, v34, v170
	v_mul_f32_e32 v51, v35, v170
	v_mul_f32_e32 v48, v32, v170
	v_mul_f32_e32 v49, v33, v170
	v_mul_f32_e32 v46, v30, v170
	v_mul_f32_e32 v47, v31, v170
	v_mul_f32_e32 v44, v28, v170
	v_mul_f32_e32 v45, v29, v170
	v_mul_f32_e32 v42, v26, v170
	v_mul_f32_e32 v43, v27, v170
	v_mul_f32_e32 v40, v24, v170
	v_mul_f32_e32 v41, v25, v170
	v_mul_f32_e32 v38, v22, v170
	v_mul_f32_e32 v39, v23, v170
	v_mul_f32_e32 v36, v20, v170
	v_mul_f32_e32 v37, v21, v170
	v_mul_f32_e32 v66, v18, v170
	v_mul_f32_e32 v67, v19, v170
	v_mul_f32_e32 v64, v16, v170
	v_mul_f32_e32 v65, v17, v170
	v_mul_f32_e32 v62, v14, v170
	v_mul_f32_e32 v63, v15, v170
	v_mul_f32_e32 v60, v12, v170
	v_mul_f32_e32 v61, v13, v170
	v_mul_f32_e32 v58, v10, v170
	v_mul_f32_e32 v59, v11, v170
	v_mul_f32_e32 v56, v8, v170
	v_mul_f32_e32 v57, v9, v170
	v_mul_f32_e32 v54, v6, v170
	v_mul_f32_e32 v55, v7, v170
	v_mul_f32_e32 v52, v4, v170
	v_mul_f32_e32 v53, v5, v170
.LBB0_1425:
	v_add_u32_e32 v3, v219, v196
	v_sub_f32_e32 v84, v84, v132
	v_sub_f32_e32 v85, v85, v132
	v_sub_f32_e32 v86, v86, v132
	v_sub_f32_e32 v87, v87, v132
	v_sub_f32_e32 v88, v88, v132
	v_sub_f32_e32 v89, v89, v132
	v_sub_f32_e32 v90, v90, v132
	v_sub_f32_e32 v91, v91, v132
	v_add_u32_e32 v171, v3, v190
	v_exp_f32_e32 v84, v84
	v_exp_f32_e32 v85, v85
	v_exp_f32_e32 v86, v86
	v_exp_f32_e32 v87, v87
	v_exp_f32_e32 v88, v88
	v_exp_f32_e32 v89, v89
	v_exp_f32_e32 v90, v90
	v_exp_f32_e32 v91, v91
	v_add_u32_e32 v171, 0x2000, v171
	ds_read2_b64 v[224:227], v171 offset0:128 offset1:130
	ds_read2_b64 v[228:231], v171 offset0:132 offset1:134
	v_add_u32_e32 v3, v3, v191
	v_cvt_pk_bf16_f32 v220, v84, v85
	v_cvt_pk_bf16_f32 v221, v86, v87
	v_cvt_pk_bf16_f32 v222, v88, v89
	v_cvt_pk_bf16_f32 v223, v90, v91
	v_add_u32_e32 v3, 0x2000, v3
	v_sub_f32_e32 v92, v92, v132
	v_sub_f32_e32 v93, v93, v132
	s_waitcnt lgkmcnt(1)
	v_mfma_f32_32x32x16_bf16 v[36:51], v[224:227], v[220:223], v[36:51]
	ds_read2_b64 v[224:227], v3 offset0:128 offset1:130
	ds_read2_b64 v[232:235], v3 offset0:132 offset1:134
	v_add_f32_e64 v94, v94, -v132
	v_add_f32_e64 v95, v95, -v132
	v_add_f32_e64 v96, v96, -v132
	v_add_f32_e64 v97, v97, -v132
	v_sub_f32_e32 v98, v98, v132
	v_sub_f32_e32 v99, v99, v132
	v_exp_f32_e32 v92, v92
	v_exp_f32_e32 v93, v93
	v_exp_f32_e32 v94, v94
	s_waitcnt lgkmcnt(1)
	v_mfma_f32_32x32x16_bf16 v[52:67], v[224:227], v[220:223], v[52:67]
	v_exp_f32_e32 v95, v95
	v_exp_f32_e32 v96, v96
	v_exp_f32_e32 v97, v97
	v_exp_f32_e32 v98, v98
	v_exp_f32_e32 v99, v99
	v_cvt_pk_bf16_f32 v220, v92, v93
	v_cvt_pk_bf16_f32 v221, v94, v95
	v_cvt_pk_bf16_f32 v222, v96, v97
	v_cvt_pk_bf16_f32 v223, v98, v99
	s_nop 1
	v_mfma_f32_32x32x16_bf16 v[36:51], v[228:231], v[220:223], v[36:51]
	s_waitcnt lgkmcnt(0)
	v_mfma_f32_32x32x16_bf16 v[52:67], v[232:235], v[220:223], v[52:67]
	v_add_f32_e64 v74, v74, -v132
	v_add_f32_e64 v75, v75, -v132
	v_add_f32_e64 v68, v68, -v132
	v_add_f32_e64 v69, v69, -v132
	v_add_f32_e64 v70, v70, -v132
	v_add_f32_e64 v71, v71, -v132
	v_sub_f32_e32 v72, v72, v132
	v_sub_f32_e32 v73, v73, v132
	v_exp_f32_e32 v228, v74
	v_exp_f32_e32 v229, v75
	v_sub_f32_e32 v74, v76, v132
	v_sub_f32_e32 v75, v77, v132
	v_exp_f32_e32 v68, v68
	v_exp_f32_e32 v69, v69
	v_exp_f32_e32 v70, v70
	v_exp_f32_e32 v71, v71
	v_exp_f32_e32 v72, v72
	v_exp_f32_e32 v73, v73
	v_exp_f32_e32 v230, v74
	v_exp_f32_e32 v231, v75
	v_sub_f32_e32 v74, v78, v132
	v_sub_f32_e32 v75, v79, v132
	v_cvt_pk_bf16_f32 v76, v72, v73
	v_exp_f32_e32 v232, v74
	v_exp_f32_e32 v233, v75
	v_sub_f32_e32 v74, v80, v132
	v_sub_f32_e32 v75, v81, v132
	ds_read2_b64 v[78:81], v171 offset0:136 offset1:138
	ds_read2_b64 v[220:223], v171 offset0:140 offset1:142
	v_exp_f32_e32 v234, v74
	v_exp_f32_e32 v235, v75
	v_sub_f32_e32 v74, v82, v132
	v_sub_f32_e32 v75, v83, v132
	v_cvt_pk_bf16_f32 v77, v228, v229
	v_exp_f32_e32 v82, v74
	v_exp_f32_e32 v83, v75
	v_cvt_pk_bf16_f32 v74, v68, v69
	v_cvt_pk_bf16_f32 v75, v70, v71
	s_mov_b64 s[26:27], 0
	s_waitcnt lgkmcnt(1)
	v_mfma_f32_32x32x16_bf16 v[36:51], v[78:81], v[74:77], v[36:51]
	ds_read2_b64 v[78:81], v3 offset0:136 offset1:138
	ds_read2_b64 v[224:227], v3 offset0:140 offset1:142
	s_waitcnt lgkmcnt(1)
	v_mfma_f32_32x32x16_bf16 v[52:67], v[78:81], v[74:77], v[52:67]
	v_cvt_pk_bf16_f32 v74, v230, v231
	v_cvt_pk_bf16_f32 v75, v232, v233
	v_cvt_pk_bf16_f32 v76, v234, v235
	v_cvt_pk_bf16_f32 v77, v82, v83
	s_nop 1
	v_mfma_f32_32x32x16_bf16 v[36:51], v[220:223], v[74:77], v[36:51]
	s_waitcnt lgkmcnt(0)
	v_mfma_f32_32x32x16_bf16 v[52:67], v[224:227], v[74:77], v[52:67]
	v_add_f32_e64 v74, v84, 0
	v_add_f32_e64 v75, v85, 0
	v_add_f32_e64 v74, v86, v74
	v_add_f32_e64 v75, v87, v75
	v_add_f32_e64 v74, v88, v74
	v_add_f32_e64 v75, v89, v75
	v_add_f32_e32 v74, v90, v74
	v_add_f32_e32 v75, v91, v75
	s_nop 0
	v_add_f32_e32 v74, v92, v74
	v_add_f32_e32 v75, v93, v75
	s_nop 0
	v_add_f32_e32 v74, v94, v74
	v_add_f32_e32 v75, v95, v75
	s_nop 0
	v_add_f32_e32 v74, v96, v74
	v_add_f32_e32 v75, v97, v75
	s_nop 0
	v_add_f32_e32 v74, v98, v74
	v_add_f32_e32 v75, v99, v75
	s_nop 0
	v_add_f32_e32 v68, v68, v74
	v_add_f32_e32 v69, v69, v75
	s_nop 0
	v_add_f32_e32 v68, v70, v68
	v_add_f32_e32 v69, v71, v69
	s_nop 0
	v_add_f32_e32 v68, v72, v68
	v_add_f32_e32 v69, v73, v69
	s_nop 0
	v_add_f32_e32 v68, v228, v68
	v_add_f32_e32 v69, v229, v69
	s_nop 0
	v_add_f32_e32 v68, v230, v68
	v_add_f32_e32 v69, v231, v69
	s_nop 0
	v_add_f32_e32 v68, v232, v68
	v_add_f32_e32 v69, v233, v69
	s_nop 0
	v_add_f32_e32 v68, v234, v68
	v_add_f32_e32 v69, v235, v69
	s_nop 0
	v_add_f32_e32 v68, v82, v68
	v_add_f32_e32 v69, v83, v69
	s_nop 0
	v_add_f32_e32 v3, v68, v69
	ds_bpermute_b32 v68, v179, v3
	s_waitcnt lgkmcnt(0)
	v_add_f32_e32 v3, v3, v68
	v_fmac_f32_e32 v3, v217, v170

.LBB0_1427:
	v_sub_u32_e32 v68, v161, v165
	s_cmp_gt_i32 s42, s76
	v_cvt_f32_i32_e32 v220, v68
	s_cselect_b64 s[2:3], -1, 0
	s_and_b64 s[8:9], s[24:25], s[2:3]
	v_add_u32_e32 v69, s38, v176
	s_mov_b64 s[2:3], -1
	s_andn2_b64 vcc, exec, s[8:9]
	v_add_u32_e32 v219, v69, v177
	v_add_u32_e32 v165, v69, v178
	s_cbranch_vccz .LBB0_1431
	v_mov_b32_e32 v3, v157
	ds_read_b128 v[52:55], v219
	ds_read_b128 v[56:59], v219 offset:32
	v_mul_f32_e64 v66, v220, -v3
	v_mov_b32_e32 v78, v3
	v_fma_f32 v38, 0, v3, v66
	v_fmamk_f32 v42, v3, 0x41000000, v66
	v_fmamk_f32 v46, v3, 0x41800000, v66
	v_fmamk_f32 v50, v3, 0x41c00000, v66
	v_add_f32_e32 v36, v2, v38
	v_add_f32_e32 v37, v3, v38
	v_fma_f32 v39, v78, s65, v38
	v_fma_f32 v38, v78, s64, v38
	v_add_f32_e32 v40, v2, v42
	v_add_f32_e32 v41, v3, v42
	v_fma_f32 v43, v78, s65, v42
	v_fma_f32 v42, v78, s64, v42
	v_add_f32_e32 v44, v2, v46
	v_add_f32_e32 v45, v3, v46
	v_fma_f32 v47, v78, s65, v46
	v_fma_f32 v46, v78, s64, v46
	v_add_f32_e32 v48, v2, v50
	v_add_f32_e32 v49, v3, v50
	v_fma_f32 v51, v78, s65, v50
	v_fma_f32 v50, v78, s64, v50
	v_fmamk_f32 v60, v3, 0x42200000, v66
	v_fmamk_f32 v62, v3, 0x42400000, v66
	s_waitcnt lgkmcnt(1)
	v_mfma_f32_32x32x16_bf16 v[36:51], v[52:55], v[100:103], v[36:51]
	v_cmp_gt_u32_e32 vcc, s47, v68
	s_waitcnt lgkmcnt(0)
	v_mfma_f32_32x32x16_bf16 v[36:51], v[56:59], v[104:107], v[36:51]
	ds_read_b128 v[52:55], v219 offset:64
	ds_read_b128 v[56:59], v219 offset:96
	ds_read_b128 v[70:73], v165
	ds_read_b128 v[74:77], v165 offset:32
	s_waitcnt lgkmcnt(3)
	v_mfma_f32_32x32x16_bf16 v[36:51], v[52:55], v[108:111], v[36:51]
	v_fmamk_f32 v54, v3, 0x42000000, v66
	v_fmac_f32_e32 v66, 0x42600000, v3
	v_add_f32_e64 v52, v2, v54
	v_add_f32_e64 v53, v3, v54
	v_fma_f32 v55, v78, s65, v54
	v_fma_f32 v54, v78, s64, v54
	v_add_f32_e32 v64, v2, v66
	v_add_f32_e32 v65, v3, v66
	v_fma_f32 v67, v78, s65, v66
	v_fma_f32 v66, v78, s64, v66
	s_waitcnt lgkmcnt(2)
	v_mfma_f32_32x32x16_bf16 v[36:51], v[56:59], v[112:115], v[36:51]
	v_add_f32_e64 v56, v2, v60
	v_add_f32_e64 v57, v3, v60
	v_fma_f32 v58, v78, s64, v60
	v_fma_f32 v59, v78, s65, v60
	v_add_f32_e64 v60, v2, v62
	v_add_f32_e64 v61, v3, v62
	v_fma_f32 v63, v78, s65, v62
	v_fma_f32 v62, v78, s64, v62
	v_add_u32_e32 v3, -1, v68
	s_nop 3
	v_cndmask_b32_e32 v88, v214, v36, vcc
	s_waitcnt lgkmcnt(1)
	v_mfma_f32_32x32x16_bf16 v[52:67], v[70:73], v[100:103], v[52:67]
	ds_read_b128 v[70:73], v165 offset:64
	ds_read_b128 v[78:81], v165 offset:96
	v_cmp_gt_u32_e32 vcc, s47, v3
	v_add_u32_e32 v36, -2, v68
	s_nop 0
	v_cndmask_b32_e32 v89, v214, v37, vcc
	v_cmp_gt_u32_e32 vcc, s47, v36
	v_add_u32_e32 v36, -3, v68
	s_waitcnt lgkmcnt(2)
	v_mfma_f32_32x32x16_bf16 v[52:67], v[74:77], v[104:107], v[52:67]
	v_cndmask_b32_e32 v94, v214, v38, vcc
	v_cmp_gt_u32_e32 vcc, s47, v36
	v_add_u32_e32 v36, -8, v68
	v_max3_f32 v3, v88, s97, v89
	v_cndmask_b32_e32 v95, v214, v39, vcc
	v_cmp_gt_u32_e32 vcc, s47, v36
	v_add_u32_e32 v36, -9, v68
	s_waitcnt lgkmcnt(1)
	v_mfma_f32_32x32x16_bf16 v[52:67], v[70:73], v[108:111], v[52:67]
	v_cndmask_b32_e32 v96, v214, v40, vcc
	v_cmp_gt_u32_e32 vcc, s47, v36
	v_add_u32_e32 v36, -10, v68
	v_max3_f32 v3, v3, v94, v95
	v_cndmask_b32_e32 v97, v214, v41, vcc
	v_cmp_gt_u32_e32 vcc, s47, v36
	v_add_u32_e32 v36, -11, v68
	s_waitcnt lgkmcnt(0)
	v_mfma_f32_32x32x16_bf16 v[52:67], v[78:81], v[112:115], v[52:67]
	v_cndmask_b32_e32 v98, v214, v42, vcc
	v_cmp_gt_u32_e32 vcc, s47, v36
	v_add_u32_e32 v36, -16, v68
	v_max3_f32 v3, v3, v96, v97
	v_cndmask_b32_e32 v99, v214, v43, vcc
	v_cmp_gt_u32_e32 vcc, s47, v36
	v_subrev_u32_e32 v36, 17, v68
	v_max3_f32 v3, v3, v98, v99
	v_cndmask_b32_e32 v170, v214, v44, vcc
	v_cmp_gt_u32_e32 vcc, s47, v36
	v_subrev_u32_e32 v36, 18, v68
	s_nop 0
	v_cndmask_b32_e32 v171, v214, v45, vcc
	v_cmp_gt_u32_e32 vcc, s47, v36
	v_subrev_u32_e32 v36, 19, v68
	v_max3_f32 v3, v3, v170, v171
	v_cndmask_b32_e32 v90, v214, v46, vcc
	v_cmp_gt_u32_e32 vcc, s47, v36
	v_subrev_u32_e32 v36, 24, v68
	s_nop 0
	v_cndmask_b32_e32 v91, v214, v47, vcc
	v_cmp_gt_u32_e32 vcc, s47, v36
	v_subrev_u32_e32 v36, 25, v68
	v_max3_f32 v3, v3, v90, v91
	v_cndmask_b32_e32 v92, v214, v48, vcc
	v_cmp_gt_u32_e32 vcc, s47, v36
	v_subrev_u32_e32 v36, 26, v68
	s_nop 0
	v_cndmask_b32_e32 v93, v214, v49, vcc
	v_cmp_gt_u32_e32 vcc, s47, v36
	v_subrev_u32_e32 v36, 27, v68
	v_max3_f32 v3, v3, v92, v93
	v_cndmask_b32_e32 v86, v214, v50, vcc
	v_cmp_gt_u32_e32 vcc, s47, v36
	v_subrev_u32_e32 v36, 32, v68
	s_nop 0
	v_cndmask_b32_e32 v87, v214, v51, vcc
	v_cmp_gt_u32_e32 vcc, s47, v36
	v_subrev_u32_e32 v36, 33, v68
	v_max3_f32 v3, v3, v86, v87
	v_cndmask_b32_e32 v76, v214, v52, vcc
	v_cmp_gt_u32_e32 vcc, s47, v36
	v_subrev_u32_e32 v36, 34, v68
	s_nop 0
	v_cndmask_b32_e32 v77, v214, v53, vcc
	v_cmp_gt_u32_e32 vcc, s47, v36
	v_subrev_u32_e32 v36, 35, v68
	v_max3_f32 v3, v3, v76, v77
	v_cndmask_b32_e32 v78, v214, v54, vcc
	v_cmp_gt_u32_e32 vcc, s47, v36
	v_subrev_u32_e32 v36, 40, v68
	s_nop 0
	v_cndmask_b32_e32 v79, v214, v55, vcc
	v_cmp_gt_u32_e32 vcc, s47, v36
	v_subrev_u32_e32 v36, 41, v68
	v_max3_f32 v3, v3, v78, v79
	v_cndmask_b32_e32 v80, v214, v56, vcc
	v_cmp_gt_u32_e32 vcc, s47, v36
	v_subrev_u32_e32 v36, 42, v68
	s_nop 0
	v_cndmask_b32_e32 v81, v214, v57, vcc
	v_cmp_gt_u32_e32 vcc, s47, v36
	v_subrev_u32_e32 v36, 43, v68
	v_max3_f32 v3, v3, v80, v81
	v_cndmask_b32_e32 v82, v214, v58, vcc
	v_cmp_gt_u32_e32 vcc, s47, v36
	v_subrev_u32_e32 v36, 48, v68
	s_nop 0
	v_cndmask_b32_e32 v83, v214, v59, vcc
	v_cmp_gt_u32_e32 vcc, s47, v36
	v_subrev_u32_e32 v36, 49, v68
	v_max3_f32 v3, v3, v82, v83
	v_cndmask_b32_e32 v84, v214, v60, vcc
	v_cmp_gt_u32_e32 vcc, s47, v36
	v_subrev_u32_e32 v36, 50, v68
	s_nop 0
	v_cndmask_b32_e32 v85, v214, v61, vcc
	v_cmp_gt_u32_e32 vcc, s47, v36
	v_subrev_u32_e32 v36, 51, v68
	v_max3_f32 v3, v3, v84, v85
	v_cndmask_b32_e32 v74, v214, v62, vcc
	v_cmp_gt_u32_e32 vcc, s47, v36
	v_subrev_u32_e32 v36, 56, v68
	s_nop 0
	v_cndmask_b32_e32 v75, v214, v63, vcc
	v_cmp_gt_u32_e32 vcc, s47, v36
	v_subrev_u32_e32 v36, 57, v68
	v_max3_f32 v3, v3, v74, v75
	v_cndmask_b32_e32 v70, v214, v64, vcc
	v_cmp_gt_u32_e32 vcc, s47, v36
	v_subrev_u32_e32 v36, 58, v68
	s_nop 0
	v_cndmask_b32_e32 v71, v214, v65, vcc
	v_cmp_gt_u32_e32 vcc, s47, v36
	v_subrev_u32_e32 v36, 59, v68
	v_max3_f32 v3, v3, v70, v71
	v_cndmask_b32_e32 v72, v214, v66, vcc
	v_cmp_gt_u32_e32 vcc, s47, v36
	s_nop 1
	v_cndmask_b32_e32 v73, v214, v67, vcc
	v_max3_f32 v3, v3, v72, v73
	ds_bpermute_b32 v36, v179, v3
	v_mov_b64_e32 v[66:67], v[18:19]
	v_mov_b64_e32 v[64:65], v[16:17]
	v_mov_b64_e32 v[62:63], v[14:15]
	v_mov_b64_e32 v[60:61], v[12:13]
	s_waitcnt lgkmcnt(0)
	v_max_f32_e32 v36, v36, v36
	v_max_f32_e32 v3, v3, v36
	v_max3_f32 v132, v218, v3, s46
	v_sub_f32_e32 v3, v218, v132
	v_exp_f32_e32 v68, v3
	v_mov_b64_e32 v[50:51], v[34:35]
	v_mov_b64_e32 v[48:49], v[32:33]
	v_mov_b64_e32 v[46:47], v[30:31]
	v_cmp_eq_f32_e32 vcc, 1.0, v68
	s_cmp_eq_u64 vcc, exec
	v_mov_b64_e32 v[44:45], v[28:29]
	v_mov_b64_e32 v[42:43], v[26:27]
	v_mov_b64_e32 v[40:41], v[24:25]
	v_mov_b64_e32 v[38:39], v[22:23]
	v_mov_b64_e32 v[36:37], v[20:21]
	v_mov_b64_e32 v[58:59], v[10:11]
	v_mov_b64_e32 v[56:57], v[8:9]
	v_mov_b64_e32 v[54:55], v[6:7]
	v_mov_b64_e32 v[52:53], v[4:5]
	s_cbranch_scc1 .LBB0_1430
	v_mul_f32_e32 v50, v34, v68
	v_mul_f32_e32 v51, v35, v68
	v_mul_f32_e32 v48, v32, v68
	v_mul_f32_e32 v49, v33, v68
	v_mul_f32_e32 v46, v30, v68
	v_mul_f32_e32 v47, v31, v68
	v_mul_f32_e32 v44, v28, v68
	v_mul_f32_e32 v45, v29, v68
	v_mul_f32_e32 v42, v26, v68
	v_mul_f32_e32 v43, v27, v68
	v_mul_f32_e32 v40, v24, v68
	v_mul_f32_e32 v41, v25, v68
	v_mul_f32_e32 v38, v22, v68
	v_mul_f32_e32 v39, v23, v68
	v_mul_f32_e32 v36, v20, v68
	v_mul_f32_e32 v37, v21, v68
	v_mul_f32_e32 v66, v18, v68
	v_mul_f32_e32 v67, v19, v68
	v_mul_f32_e32 v64, v16, v68
	v_mul_f32_e32 v65, v17, v68
	v_mul_f32_e32 v62, v14, v68
	v_mul_f32_e32 v63, v15, v68
	v_mul_f32_e32 v60, v12, v68
	v_mul_f32_e32 v61, v13, v68
	v_mul_f32_e32 v58, v10, v68
	v_mul_f32_e32 v59, v11, v68
	v_mul_f32_e32 v56, v8, v68
	v_mul_f32_e32 v57, v9, v68
	v_mul_f32_e32 v54, v6, v68
	v_mul_f32_e32 v55, v7, v68
	v_mul_f32_e32 v52, v4, v68
	v_mul_f32_e32 v53, v5, v68
.LBB0_1430:
	v_sub_f32_e32 v94, v94, v132
	v_sub_f32_e32 v95, v95, v132
	v_lshl_add_u32 v3, v136, 1, s38
	v_exp_f32_e32 v230, v94
	v_exp_f32_e32 v231, v95
	v_sub_f32_e32 v94, v96, v132
	v_sub_f32_e32 v95, v97, v132
	v_sub_f32_e32 v88, v88, v132
	v_sub_f32_e32 v89, v89, v132
	v_exp_f32_e32 v232, v94
	v_exp_f32_e32 v233, v95
	v_sub_f32_e32 v94, v98, v132
	v_sub_f32_e32 v95, v99, v132
	v_exp_f32_e32 v88, v88
	v_exp_f32_e32 v98, v94
	v_add_u32_e32 v94, v3, v190
	v_add_u32_e32 v186, 0x2000, v94
	v_exp_f32_e32 v99, v95
	ds_read2_b64 v[94:97], v186 offset0:128 offset1:130
	v_add_u32_e32 v3, v3, v191
	v_add_u32_e32 v3, 0x2000, v3
	ds_read2_b64 v[226:229], v3 offset0:128 offset1:130
	v_exp_f32_e32 v89, v89
	v_sub_f32_e32 v90, v90, v132
	v_sub_f32_e32 v91, v91, v132
	v_cvt_pk_bf16_f32 v223, v230, v231
	v_exp_f32_e32 v234, v90
	v_exp_f32_e32 v235, v91
	v_sub_f32_e32 v90, v92, v132
	v_sub_f32_e32 v91, v93, v132
	v_cvt_pk_bf16_f32 v222, v88, v89
	v_cvt_pk_bf16_f32 v224, v232, v233
	v_cvt_pk_bf16_f32 v225, v98, v99
	v_exp_f32_e32 v236, v90
	v_exp_f32_e32 v237, v91
	ds_read2_b64 v[90:93], v186 offset0:132 offset1:134
	s_waitcnt lgkmcnt(2)
	v_mfma_f32_32x32x16_bf16 v[36:51], v[94:97], v[222:225], v[36:51]
	v_add_f32_e64 v170, v170, -v132
	v_add_f32_e64 v171, v171, -v132
	v_add_f32_e64 v86, v86, -v132
	v_add_f32_e64 v87, v87, -v132
	v_exp_f32_e32 v170, v170
	v_exp_f32_e32 v171, v171
	v_cvt_pk_bf16_f32 v95, v234, v235
	v_cvt_pk_bf16_f32 v96, v236, v237
	v_cvt_pk_bf16_f32 v94, v170, v171
	s_waitcnt lgkmcnt(1)
	v_mfma_f32_32x32x16_bf16 v[52:67], v[226:229], v[222:225], v[52:67]
	v_exp_f32_e32 v222, v86
	v_exp_f32_e32 v223, v87
	s_nop 0
	v_cvt_pk_bf16_f32 v97, v222, v223
	s_waitcnt lgkmcnt(0)
	s_nop 0
	v_mfma_f32_32x32x16_bf16 v[36:51], v[90:93], v[94:97], v[36:51]
	ds_read2_b64 v[90:93], v3 offset0:132 offset1:134
	s_waitcnt lgkmcnt(0)
	v_mfma_f32_32x32x16_bf16 v[52:67], v[90:93], v[94:97], v[52:67]
	v_add_f32_e64 v76, v76, -v132
	v_add_f32_e64 v77, v77, -v132
	v_add_f32_e64 v74, v74, -v132
	v_add_f32_e64 v75, v75, -v132
	v_exp_f32_e32 v90, v76
	v_exp_f32_e32 v91, v77
	v_sub_f32_e32 v76, v78, v132
	v_sub_f32_e32 v77, v79, v132
	v_sub_f32_e32 v70, v70, v132
	v_sub_f32_e32 v71, v71, v132
	v_exp_f32_e32 v92, v76
	v_exp_f32_e32 v93, v77
	v_sub_f32_e32 v76, v80, v132
	v_sub_f32_e32 v77, v81, v132
	v_sub_f32_e32 v80, v84, v132
	v_sub_f32_e32 v81, v85, v132
	v_exp_f32_e32 v94, v76
	v_exp_f32_e32 v95, v77
	v_sub_f32_e32 v76, v82, v132
	v_sub_f32_e32 v77, v83, v132
	ds_read2_b64 v[84:87], v3 offset0:136 offset1:138
	v_exp_f32_e32 v96, v76
	v_exp_f32_e32 v97, v77
	ds_read2_b64 v[76:79], v186 offset0:136 offset1:138
	v_exp_f32_e32 v224, v80
	v_exp_f32_e32 v225, v81
	v_cvt_pk_bf16_f32 v80, v90, v91
	v_cvt_pk_bf16_f32 v81, v92, v93
	v_cvt_pk_bf16_f32 v82, v94, v95
	v_cvt_pk_bf16_f32 v83, v96, v97
	v_exp_f32_e32 v226, v74
	v_exp_f32_e32 v227, v75
	v_exp_f32_e32 v228, v70
	v_exp_f32_e32 v229, v71
	v_sub_f32_e32 v74, v72, v132
	v_sub_f32_e32 v75, v73, v132
	ds_read2_b64 v[70:73], v186 offset0:140 offset1:142
	s_waitcnt lgkmcnt(1)
	v_mfma_f32_32x32x16_bf16 v[36:51], v[76:79], v[80:83], v[36:51]
	v_cvt_pk_bf16_f32 v78, v224, v225
	v_cvt_pk_bf16_f32 v79, v226, v227
	s_mov_b64 s[2:3], 0
	v_mfma_f32_32x32x16_bf16 v[52:67], v[84:87], v[80:83], v[52:67]
	v_exp_f32_e32 v82, v74
	v_exp_f32_e32 v83, v75
	v_cvt_pk_bf16_f32 v80, v228, v229
	ds_read2_b64 v[74:77], v3 offset0:140 offset1:142
	v_cvt_pk_bf16_f32 v81, v82, v83
	s_waitcnt lgkmcnt(1)
	s_nop 0
	v_mfma_f32_32x32x16_bf16 v[36:51], v[70:73], v[78:81], v[36:51]
	v_add_f32_e64 v70, v88, 0
	v_add_f32_e64 v71, v89, 0
	v_add_f32_e64 v70, v230, v70
	v_add_f32_e64 v71, v231, v71
	v_add_f32_e64 v70, v232, v70
	v_add_f32_e64 v71, v233, v71
	v_add_f32_e32 v70, v98, v70
	v_add_f32_e32 v71, v99, v71
	s_waitcnt lgkmcnt(0)
	v_mfma_f32_32x32x16_bf16 v[52:67], v[74:77], v[78:81], v[52:67]
	v_add_f32_e64 v70, v170, v70
	v_add_f32_e64 v71, v171, v71
	v_add_f32_e64 v70, v234, v70
	v_add_f32_e64 v71, v235, v71
	v_add_f32_e64 v70, v236, v70
	v_add_f32_e64 v71, v237, v71
	v_add_f32_e32 v70, v222, v70
	v_add_f32_e32 v71, v223, v71
	s_nop 0
	v_add_f32_e32 v70, v90, v70
	v_add_f32_e32 v71, v91, v71
	s_nop 0
	v_add_f32_e32 v70, v92, v70
	v_add_f32_e32 v71, v93, v71
	s_nop 0
	v_add_f32_e32 v70, v94, v70
	v_add_f32_e32 v71, v95, v71
	s_nop 0
	v_add_f32_e32 v70, v96, v70
	v_add_f32_e32 v71, v97, v71
	s_nop 0
	v_add_f32_e32 v70, v224, v70
	v_add_f32_e32 v71, v225, v71
	s_nop 0
	v_add_f32_e32 v70, v226, v70
	v_add_f32_e32 v71, v227, v71
	s_nop 0
	v_add_f32_e32 v70, v228, v70
	v_add_f32_e32 v71, v229, v71
	s_nop 0
	v_add_f32_e32 v70, v82, v70
	v_add_f32_e32 v71, v83, v71
	s_nop 0
	v_add_f32_e32 v3, v70, v71
	ds_bpermute_b32 v70, v179, v3
	s_waitcnt lgkmcnt(0)
	v_add_f32_e32 v3, v3, v70
	v_fmac_f32_e32 v3, v217, v68
.LBB0_1431:
	s_and_b64 vcc, exec, s[2:3]
	s_cbranch_vccz .LBB0_1442
	v_mov_b32_e32 v3, v157
	s_nop 0
	v_mul_f32_e64 v50, v220, -v3
	v_mov_b32_e32 v68, v3
	v_fma_f32 v36, 0, v3, v50
	v_add_f32_e32 v52, v2, v36
	v_add_f32_e32 v53, v3, v36
	v_fma_f32 v54, v68, s64, v36
	v_fma_f32 v55, v68, s65, v36
	v_fmamk_f32 v36, v3, 0x41000000, v50
	v_add_f32_e32 v56, v2, v36
	v_add_f32_e32 v57, v3, v36
	v_fma_f32 v58, v68, s64, v36
	v_fma_f32 v59, v68, s65, v36
	v_fmamk_f32 v36, v3, 0x41800000, v50
	v_add_f32_e32 v60, v2, v36
	v_add_f32_e32 v61, v3, v36
	v_fma_f32 v62, v68, s64, v36
	v_fma_f32 v63, v68, s65, v36
	v_fmamk_f32 v36, v3, 0x41c00000, v50
	v_add_f32_e32 v64, v2, v36
	v_add_f32_e32 v65, v3, v36
	v_fma_f32 v66, v68, s64, v36
	v_fma_f32 v67, v68, s65, v36
	ds_read_b128 v[36:39], v219
	ds_read_b128 v[40:43], v219 offset:32
	s_waitcnt lgkmcnt(1)
	v_mfma_f32_32x32x16_bf16 v[52:67], v[36:39], v[100:103], v[52:67]
	ds_read_b128 v[36:39], v219 offset:64
	v_fmamk_f32 v46, v3, 0x42400000, v50
	v_add_f32_e64 v44, v2, v46
	v_add_f32_e64 v45, v3, v46
	v_fma_f32 v47, v68, s65, v46
	v_fma_f32 v46, v68, s64, v46
	s_waitcnt lgkmcnt(1)
	v_mfma_f32_32x32x16_bf16 v[52:67], v[40:43], v[104:107], v[52:67]
	v_fmamk_f32 v42, v3, 0x42200000, v50
	v_add_f32_e64 v40, v2, v42
	v_add_f32_e64 v41, v3, v42
	v_fma_f32 v43, v68, s65, v42
	v_fma_f32 v42, v68, s64, v42
	s_waitcnt lgkmcnt(0)
	v_mfma_f32_32x32x16_bf16 v[52:67], v[36:39], v[108:111], v[52:67]
	ds_read_b128 v[36:39], v219 offset:96
	ds_read_b128 v[70:73], v165
	ds_read_b128 v[74:77], v165 offset:32
	s_waitcnt lgkmcnt(2)
	v_mfma_f32_32x32x16_bf16 v[52:67], v[36:39], v[112:115], v[52:67]
	v_fmamk_f32 v38, v3, 0x42000000, v50
	v_fmac_f32_e32 v50, 0x42600000, v3
	v_add_f32_e64 v36, v2, v38
	v_add_f32_e64 v37, v3, v38
	v_fma_f32 v39, v68, s65, v38
	v_fma_f32 v38, v68, s64, v38
	v_add_f32_e32 v48, v2, v50
	v_add_f32_e32 v49, v3, v50
	v_fma_f32 v51, v68, s65, v50
	v_fma_f32 v50, v68, s64, v50
	s_nop 4
	v_max3_f32 v3, v52, s97, v53
	s_waitcnt lgkmcnt(1)
	v_mfma_f32_32x32x16_bf16 v[36:51], v[70:73], v[100:103], v[36:51]
	ds_read_b128 v[70:73], v165 offset:64
	v_max3_f32 v3, v3, v54, v55
	v_max3_f32 v3, v3, v56, v57
	v_max3_f32 v3, v3, v58, v59
	v_max3_f32 v3, v3, v60, v61
	v_max3_f32 v3, v3, v62, v63
	v_max3_f32 v3, v3, v64, v65
	s_waitcnt lgkmcnt(1)
	v_mfma_f32_32x32x16_bf16 v[36:51], v[74:77], v[104:107], v[36:51]
	v_max3_f32 v3, v3, v66, v67
	s_waitcnt lgkmcnt(0)
	v_mfma_f32_32x32x16_bf16 v[36:51], v[70:73], v[108:111], v[36:51]
	ds_read_b128 v[70:73], v165 offset:96
	s_waitcnt lgkmcnt(0)
	v_mfma_f32_32x32x16_bf16 v[36:51], v[70:73], v[112:115], v[36:51]
	s_nop 11
	v_max3_f32 v3, v3, v36, v37
	v_max3_f32 v3, v3, v38, v39
	v_max3_f32 v3, v3, v40, v41
	v_max3_f32 v3, v3, v42, v43
	v_max3_f32 v3, v3, v44, v45
	v_max3_f32 v3, v3, v46, v47
	v_max3_f32 v3, v3, v48, v49
	v_max3_f32 v3, v3, v50, v51
	ds_bpermute_b32 v68, v179, v3
	s_waitcnt lgkmcnt(0)
	v_max_f32_e32 v68, v68, v68
	v_max_f32_e32 v3, v3, v68
	v_max3_f32 v132, v218, v3, s46
	v_sub_f32_e32 v3, v218, v132
	v_exp_f32_e32 v68, v3
	s_nop 0
	v_cmp_eq_f32_e32 vcc, 1.0, v68
	s_cmp_eq_u64 vcc, exec
	s_cbranch_scc1 .LBB0_1434
	v_mul_f32_e32 v34, v34, v68
	v_mul_f32_e32 v35, v35, v68
	v_mul_f32_e32 v32, v32, v68
	v_mul_f32_e32 v33, v33, v68
	v_mul_f32_e32 v30, v30, v68
	v_mul_f32_e32 v31, v31, v68
	v_mul_f32_e32 v28, v28, v68
	v_mul_f32_e32 v29, v29, v68
	v_mul_f32_e32 v26, v26, v68
	v_mul_f32_e32 v27, v27, v68
	v_mul_f32_e32 v24, v24, v68
	v_mul_f32_e32 v25, v25, v68
	v_mul_f32_e32 v22, v22, v68
	v_mul_f32_e32 v23, v23, v68
	v_mul_f32_e32 v20, v20, v68
	v_mul_f32_e32 v21, v21, v68
	v_mul_f32_e32 v18, v18, v68
	v_mul_f32_e32 v19, v19, v68
	v_mul_f32_e32 v16, v16, v68
	v_mul_f32_e32 v17, v17, v68
	v_mul_f32_e32 v14, v14, v68
	v_mul_f32_e32 v15, v15, v68
	v_mul_f32_e32 v12, v12, v68
	v_mul_f32_e32 v13, v13, v68
	v_mul_f32_e32 v10, v10, v68
	v_mul_f32_e32 v11, v11, v68
	v_mul_f32_e32 v8, v8, v68
	v_mul_f32_e32 v9, v9, v68
	v_mul_f32_e32 v6, v6, v68
	v_mul_f32_e32 v7, v7, v68
	v_mul_f32_e32 v4, v4, v68
	v_mul_f32_e32 v5, v5, v68
.LBB0_1434:
	v_add_u32_e32 v3, v69, v196
	v_sub_f32_e32 v52, v52, v132
	v_sub_f32_e32 v53, v53, v132
	v_sub_f32_e32 v54, v54, v132
	v_sub_f32_e32 v55, v55, v132
	v_sub_f32_e32 v56, v56, v132
	v_sub_f32_e32 v57, v57, v132
	v_sub_f32_e32 v58, v58, v132
	v_sub_f32_e32 v59, v59, v132
	v_add_u32_e32 v69, v3, v190
	v_exp_f32_e32 v52, v52
	v_exp_f32_e32 v53, v53
	v_exp_f32_e32 v54, v54
	v_exp_f32_e32 v55, v55
	v_exp_f32_e32 v56, v56
	v_exp_f32_e32 v57, v57
	v_exp_f32_e32 v58, v58
	v_exp_f32_e32 v59, v59
	v_add_u32_e32 v69, 0x2000, v69
	ds_read2_b64 v[74:77], v69 offset0:128 offset1:130
	ds_read2_b64 v[78:81], v69 offset0:132 offset1:134
	v_add_u32_e32 v3, v3, v191
	v_cvt_pk_bf16_f32 v70, v52, v53
	v_cvt_pk_bf16_f32 v71, v54, v55
	v_cvt_pk_bf16_f32 v72, v56, v57
	v_cvt_pk_bf16_f32 v73, v58, v59
	v_add_u32_e32 v3, 0x2000, v3
	v_sub_f32_e32 v60, v60, v132
	v_sub_f32_e32 v61, v61, v132
	s_waitcnt lgkmcnt(1)
	v_mfma_f32_32x32x16_bf16 v[20:35], v[74:77], v[70:73], v[20:35]
	ds_read2_b64 v[74:77], v3 offset0:128 offset1:130
	ds_read2_b64 v[82:85], v3 offset0:132 offset1:134
	v_add_f32_e64 v62, v62, -v132
	v_add_f32_e64 v63, v63, -v132
	v_add_f32_e64 v64, v64, -v132
	v_add_f32_e64 v65, v65, -v132
	v_sub_f32_e32 v66, v66, v132
	v_sub_f32_e32 v67, v67, v132
	v_exp_f32_e32 v60, v60
	v_exp_f32_e32 v61, v61
	v_exp_f32_e32 v62, v62
	s_waitcnt lgkmcnt(1)
	v_mfma_f32_32x32x16_bf16 v[4:19], v[74:77], v[70:73], v[4:19]
	v_exp_f32_e32 v63, v63
	v_exp_f32_e32 v64, v64
	v_exp_f32_e32 v65, v65
	v_exp_f32_e32 v66, v66
	v_exp_f32_e32 v67, v67
	v_cvt_pk_bf16_f32 v70, v60, v61
	v_cvt_pk_bf16_f32 v71, v62, v63
	v_cvt_pk_bf16_f32 v72, v64, v65
	v_cvt_pk_bf16_f32 v73, v66, v67
	s_nop 1
	v_mfma_f32_32x32x16_bf16 v[20:35], v[78:81], v[70:73], v[20:35]
	s_waitcnt lgkmcnt(0)
	v_mfma_f32_32x32x16_bf16 v[4:19], v[82:85], v[70:73], v[4:19]
	v_add_f32_e64 v42, v42, -v132
	v_add_f32_e64 v43, v43, -v132
	v_add_f32_e64 v36, v36, -v132
	v_add_f32_e64 v37, v37, -v132
	v_add_f32_e64 v38, v38, -v132
	v_add_f32_e64 v39, v39, -v132
	v_sub_f32_e32 v40, v40, v132
	v_sub_f32_e32 v41, v41, v132
	v_exp_f32_e32 v78, v42
	v_exp_f32_e32 v79, v43
	v_sub_f32_e32 v42, v44, v132
	v_sub_f32_e32 v43, v45, v132
	v_exp_f32_e32 v36, v36
	v_exp_f32_e32 v37, v37
	v_exp_f32_e32 v38, v38
	v_exp_f32_e32 v39, v39
	v_exp_f32_e32 v40, v40
	v_exp_f32_e32 v41, v41
	v_exp_f32_e32 v80, v42
	v_exp_f32_e32 v81, v43
	v_sub_f32_e32 v42, v46, v132
	v_sub_f32_e32 v43, v47, v132
	v_cvt_pk_bf16_f32 v44, v40, v41
	v_exp_f32_e32 v82, v42
	v_exp_f32_e32 v83, v43
	v_sub_f32_e32 v42, v48, v132
	v_sub_f32_e32 v43, v49, v132
	ds_read2_b64 v[46:49], v69 offset0:136 offset1:138
	ds_read2_b64 v[70:73], v69 offset0:140 offset1:142
	v_exp_f32_e32 v84, v42
	v_exp_f32_e32 v85, v43
	v_sub_f32_e32 v42, v50, v132
	v_sub_f32_e32 v43, v51, v132
	v_cvt_pk_bf16_f32 v45, v78, v79
	v_exp_f32_e32 v50, v42
	v_exp_f32_e32 v51, v43
	v_cvt_pk_bf16_f32 v42, v36, v37
	v_cvt_pk_bf16_f32 v43, v38, v39
	s_waitcnt lgkmcnt(1)
	s_nop 0
	v_mfma_f32_32x32x16_bf16 v[20:35], v[46:49], v[42:45], v[20:35]
	ds_read2_b64 v[46:49], v3 offset0:136 offset1:138
	ds_read2_b64 v[74:77], v3 offset0:140 offset1:142
	s_waitcnt lgkmcnt(1)
	v_mfma_f32_32x32x16_bf16 v[4:19], v[46:49], v[42:45], v[4:19]
	v_cvt_pk_bf16_f32 v42, v80, v81
	v_cvt_pk_bf16_f32 v43, v82, v83
	v_cvt_pk_bf16_f32 v44, v84, v85
	v_cvt_pk_bf16_f32 v45, v50, v51
	s_nop 1
	v_mfma_f32_32x32x16_bf16 v[20:35], v[70:73], v[42:45], v[20:35]
	s_waitcnt lgkmcnt(0)
	v_mfma_f32_32x32x16_bf16 v[4:19], v[74:77], v[42:45], v[4:19]
	v_add_f32_e64 v42, v52, 0
	v_add_f32_e64 v43, v53, 0
	v_add_f32_e64 v42, v54, v42
	v_add_f32_e64 v43, v55, v43
	v_add_f32_e64 v42, v56, v42
	v_add_f32_e64 v43, v57, v43
	v_add_f32_e32 v42, v58, v42
	v_add_f32_e32 v43, v59, v43
	s_nop 0
	v_add_f32_e32 v42, v60, v42
	v_add_f32_e32 v43, v61, v43
	s_nop 0
	v_add_f32_e32 v42, v62, v42
	v_add_f32_e32 v43, v63, v43
	s_nop 0
	v_add_f32_e32 v42, v64, v42
	v_add_f32_e32 v43, v65, v43
	s_nop 0
	v_add_f32_e32 v42, v66, v42
	v_add_f32_e32 v43, v67, v43
	v_mov_b64_e32 v[66:67], v[18:19]
	v_add_f32_e32 v36, v36, v42
	v_add_f32_e32 v37, v37, v43
	v_mov_b64_e32 v[64:65], v[16:17]
	v_add_f32_e32 v36, v38, v36
	v_add_f32_e32 v37, v39, v37
	v_mov_b64_e32 v[62:63], v[14:15]
	v_add_f32_e32 v36, v40, v36
	v_add_f32_e32 v37, v41, v37
	v_mov_b64_e32 v[60:61], v[12:13]
	v_add_f32_e32 v36, v78, v36
	v_add_f32_e32 v37, v79, v37
	v_mov_b64_e32 v[58:59], v[10:11]
	v_add_f32_e32 v36, v80, v36
	v_add_f32_e32 v37, v81, v37
	v_mov_b64_e32 v[56:57], v[8:9]
	v_add_f32_e32 v36, v82, v36
	v_add_f32_e32 v37, v83, v37
	v_mov_b64_e32 v[54:55], v[6:7]
	v_add_f32_e32 v36, v84, v36
	v_add_f32_e32 v37, v85, v37
	v_mov_b64_e32 v[52:53], v[4:5]
	v_add_f32_e32 v36, v50, v36
	v_add_f32_e32 v37, v51, v37
	s_nop 0
	v_add_f32_e32 v3, v36, v37
	ds_bpermute_b32 v36, v179, v3
	s_waitcnt lgkmcnt(0)
	v_add_f32_e32 v3, v3, v36
	v_mov_b64_e32 v[50:51], v[34:35]
	v_fmac_f32_e32 v3, v217, v68
	v_mov_b64_e32 v[48:49], v[32:33]
	v_mov_b64_e32 v[46:47], v[30:31]
	v_mov_b64_e32 v[44:45], v[28:29]
	v_mov_b64_e32 v[42:43], v[26:27]
	v_mov_b64_e32 v[40:41], v[24:25]
	v_mov_b64_e32 v[38:39], v[22:23]
	v_mov_b64_e32 v[36:37], v[20:21]
	s_branch .LBB0_1442

.LBB0_1443:
	s_and_b64 vcc, exec, s[0:1]
	s_cbranch_vccnz .LBB0_1465
	v_lshrrev_b32_e32 v3, s39, v159
	v_and_b32_e32 v3, 1, v3
	v_cmp_eq_u32_e64 s[0:1], 1, v3
	s_or_b64 s[2:3], s[28:29], s[0:1]
	v_cndmask_b32_e64 v3, 0, 1, s[2:3]
	v_cmp_ne_u32_e32 vcc, 0, v3
	s_cbranch_vccz .LBB0_1465
	s_cmp_lt_i32 s39, s48
	s_cselect_b64 s[2:3], -1, 0
	s_cmp_ge_i32 s39, s48
	v_add_u32_e32 v165, s38, v176
	s_cselect_b64 s[26:27], -1, 0
	s_mov_b64 s[24:25], -1
	s_and_b64 vcc, exec, s[20:21]
	v_lshl_or_b32 v221, s39, 6, v136
	v_add_u32_e32 v220, v165, v177
	v_add_u32_e32 v219, v165, v178
	s_cbranch_vccz .LBB0_1454
	v_sub_u32_e32 v68, v161, v221
	v_cvt_f32_i32_e32 v69, v68
	s_and_b64 vcc, exec, s[26:27]
	s_cbranch_vccz .LBB0_1450
	v_mov_b32_e32 v3, v157
	ds_read_b128 v[52:55], v220 offset:17920
	ds_read_b128 v[56:59], v220 offset:17952
	v_mul_f32_e64 v36, v69, -v3
	v_cndmask_b32_e64 v66, v214, v36, s[0:1]
	v_mov_b32_e32 v74, v3
	v_fma_f32 v38, 0, v3, v66
	v_fmamk_f32 v42, v3, 0x41000000, v66
	v_fmamk_f32 v46, v3, 0x41800000, v66
	v_fmamk_f32 v50, v3, 0x41c00000, v66
	v_add_f32_e32 v36, v2, v38
	v_add_f32_e32 v37, v3, v38
	v_fma_f32 v39, v74, s65, v38
	v_fma_f32 v38, v74, s64, v38
	v_add_f32_e32 v40, v2, v42
	v_add_f32_e32 v41, v3, v42
	v_fma_f32 v43, v74, s65, v42
	v_fma_f32 v42, v74, s64, v42
	v_add_f32_e32 v44, v2, v46
	v_add_f32_e32 v45, v3, v46
	v_fma_f32 v47, v74, s65, v46
	v_fma_f32 v46, v74, s64, v46
	v_add_f32_e32 v48, v2, v50
	v_add_f32_e32 v49, v3, v50
	v_fma_f32 v51, v74, s65, v50
	v_fma_f32 v50, v74, s64, v50
	v_fmamk_f32 v62, v3, 0x42200000, v66
	v_fmamk_f32 v64, v3, 0x42400000, v66
	s_waitcnt lgkmcnt(1)
	v_mfma_f32_32x32x16_bf16 v[36:51], v[52:55], v[100:103], v[36:51]
	v_cmp_lt_i32_e32 vcc, -1, v68
	s_waitcnt lgkmcnt(0)
	v_mfma_f32_32x32x16_bf16 v[36:51], v[56:59], v[104:107], v[36:51]
	ds_read_b128 v[52:55], v220 offset:17984
	ds_read_b128 v[58:61], v220 offset:18016
	ds_read_b128 v[70:73], v219 offset:17920
	v_add_f32_e64 v56, v2, v62
	v_add_f32_e64 v57, v3, v62
	s_waitcnt lgkmcnt(2)
	v_mfma_f32_32x32x16_bf16 v[36:51], v[52:55], v[108:111], v[36:51]
	v_fmamk_f32 v54, v3, 0x42000000, v66
	v_fmac_f32_e32 v66, 0x42600000, v3
	v_add_f32_e64 v52, v2, v54
	v_add_f32_e64 v53, v3, v54
	v_fma_f32 v55, v74, s65, v54
	v_fma_f32 v54, v74, s64, v54
	s_waitcnt lgkmcnt(1)
	v_mfma_f32_32x32x16_bf16 v[36:51], v[58:61], v[112:115], v[36:51]
	v_fma_f32 v58, v74, s64, v62
	v_fma_f32 v59, v74, s65, v62
	v_add_f32_e64 v60, v2, v64
	v_add_f32_e64 v61, v3, v64
	v_fma_f32 v62, v74, s64, v64
	v_fma_f32 v63, v74, s65, v64
	v_add_f32_e32 v64, v2, v66
	v_add_f32_e32 v65, v3, v66
	v_fma_f32 v67, v74, s65, v66
	v_fma_f32 v66, v74, s64, v66
	ds_read_b128 v[74:77], v219 offset:17952
	s_nop 2
	v_cndmask_b32_e32 v86, v214, v36, vcc
	s_waitcnt lgkmcnt(1)
	v_mfma_f32_32x32x16_bf16 v[52:67], v[70:73], v[100:103], v[52:67]
	ds_read_b128 v[70:73], v219 offset:17984
	ds_read_b128 v[78:81], v219 offset:18016
	v_cmp_lt_i32_e32 vcc, 0, v68
	s_nop 1
	v_cndmask_b32_e32 v87, v214, v37, vcc
	v_cmp_lt_i32_e32 vcc, 1, v68
	v_max3_f32 v3, v86, s97, v87
	s_waitcnt lgkmcnt(2)
	v_mfma_f32_32x32x16_bf16 v[52:67], v[74:77], v[104:107], v[52:67]
	v_cndmask_b32_e32 v94, v214, v38, vcc
	v_cmp_lt_i32_e32 vcc, 2, v68
	s_nop 1
	v_cndmask_b32_e32 v95, v214, v39, vcc
	v_cmp_lt_i32_e32 vcc, 7, v68
	v_max3_f32 v3, v3, v94, v95
	s_waitcnt lgkmcnt(1)
	v_mfma_f32_32x32x16_bf16 v[52:67], v[70:73], v[108:111], v[52:67]
	v_cndmask_b32_e32 v98, v214, v40, vcc
	v_cmp_lt_i32_e32 vcc, 8, v68
	s_nop 1
	v_cndmask_b32_e32 v99, v214, v41, vcc
	v_cmp_lt_i32_e32 vcc, 9, v68
	v_max3_f32 v3, v3, v98, v99
	s_waitcnt lgkmcnt(0)
	v_mfma_f32_32x32x16_bf16 v[52:67], v[78:81], v[112:115], v[52:67]
	v_cndmask_b32_e32 v96, v214, v42, vcc
	v_cmp_lt_i32_e32 vcc, 10, v68
	s_nop 1
	v_cndmask_b32_e32 v97, v214, v43, vcc
	v_cmp_lt_i32_e32 vcc, 15, v68
	v_max3_f32 v3, v3, v96, v97
	s_nop 0
	v_cndmask_b32_e32 v170, v214, v44, vcc
	v_cmp_lt_i32_e32 vcc, 16, v68
	s_nop 1
	v_cndmask_b32_e32 v171, v214, v45, vcc
	v_cmp_lt_i32_e32 vcc, 17, v68
	v_max3_f32 v3, v3, v170, v171
	s_nop 0
	v_cndmask_b32_e32 v90, v214, v46, vcc
	v_cmp_lt_i32_e32 vcc, 18, v68
	s_nop 1
	v_cndmask_b32_e32 v91, v214, v47, vcc
	v_cmp_lt_i32_e32 vcc, 23, v68
	v_max3_f32 v3, v3, v90, v91
	s_nop 0
	v_cndmask_b32_e32 v92, v214, v48, vcc
	v_cmp_lt_i32_e32 vcc, 24, v68
	s_nop 1
	v_cndmask_b32_e32 v93, v214, v49, vcc
	v_cmp_lt_i32_e32 vcc, 25, v68
	v_max3_f32 v3, v3, v92, v93
	s_nop 0
	v_cndmask_b32_e32 v88, v214, v50, vcc
	v_cmp_lt_i32_e32 vcc, 26, v68
	s_nop 1
	v_cndmask_b32_e32 v89, v214, v51, vcc
	v_cmp_lt_i32_e32 vcc, 31, v68
	v_max3_f32 v3, v3, v88, v89
	s_nop 0
	v_cndmask_b32_e32 v84, v214, v52, vcc
	v_cmp_lt_i32_e32 vcc, 32, v68
	s_nop 1
	v_cndmask_b32_e32 v85, v214, v53, vcc
	v_cmp_lt_i32_e32 vcc, 33, v68
	v_max3_f32 v3, v3, v84, v85
	s_nop 0
	v_cndmask_b32_e32 v82, v214, v54, vcc
	v_cmp_lt_i32_e32 vcc, 34, v68
	s_nop 1
	v_cndmask_b32_e32 v83, v214, v55, vcc
	v_cmp_lt_i32_e32 vcc, 39, v68
	v_max3_f32 v3, v3, v82, v83
	s_nop 0
	v_cndmask_b32_e32 v80, v214, v56, vcc
	v_cmp_lt_i32_e32 vcc, 40, v68
	s_nop 1
	v_cndmask_b32_e32 v81, v214, v57, vcc
	v_cmp_lt_i32_e32 vcc, 41, v68
	v_max3_f32 v3, v3, v80, v81
	s_nop 0
	v_cndmask_b32_e32 v78, v214, v58, vcc
	v_cmp_lt_i32_e32 vcc, 42, v68
	s_nop 1
	v_cndmask_b32_e32 v79, v214, v59, vcc
	v_cmp_lt_i32_e32 vcc, 47, v68
	v_max3_f32 v3, v3, v78, v79
	s_nop 0
	v_cndmask_b32_e32 v76, v214, v60, vcc
	v_cmp_lt_i32_e32 vcc, 48, v68
	s_nop 1
	v_cndmask_b32_e32 v77, v214, v61, vcc
	v_cmp_lt_i32_e32 vcc, 49, v68
	v_max3_f32 v3, v3, v76, v77
	s_nop 0
	v_cndmask_b32_e32 v74, v214, v62, vcc
	v_cmp_lt_i32_e32 vcc, 50, v68
	s_nop 1
	v_cndmask_b32_e32 v75, v214, v63, vcc
	v_cmp_lt_i32_e32 vcc, 55, v68
	v_max3_f32 v3, v3, v74, v75
	s_nop 0
	v_cndmask_b32_e32 v70, v214, v64, vcc
	v_cmp_lt_i32_e32 vcc, 56, v68
	s_nop 1
	v_cndmask_b32_e32 v71, v214, v65, vcc
	v_cmp_lt_i32_e32 vcc, 57, v68
	v_max3_f32 v3, v3, v70, v71
	s_nop 0
	v_cndmask_b32_e32 v72, v214, v66, vcc
	v_cmp_lt_i32_e32 vcc, 58, v68
	s_nop 1
	v_cndmask_b32_e32 v73, v214, v67, vcc
	v_max3_f32 v3, v3, v72, v73
	ds_bpermute_b32 v36, v179, v3
	v_mov_b64_e32 v[66:67], v[18:19]
	v_mov_b64_e32 v[64:65], v[16:17]
	v_mov_b64_e32 v[62:63], v[14:15]
	v_mov_b64_e32 v[60:61], v[12:13]
	s_waitcnt lgkmcnt(0)
	v_max_f32_e32 v36, v36, v36
	v_max_f32_e32 v3, v3, v36
	v_max3_f32 v132, v218, v3, s46
	v_sub_f32_e32 v3, v218, v132
	v_exp_f32_e32 v68, v3
	v_mov_b64_e32 v[50:51], v[34:35]
	v_mov_b64_e32 v[48:49], v[32:33]
	v_mov_b64_e32 v[46:47], v[30:31]
	v_cmp_eq_f32_e32 vcc, 1.0, v68
	s_cmp_eq_u64 vcc, exec
	v_mov_b64_e32 v[44:45], v[28:29]
	v_mov_b64_e32 v[42:43], v[26:27]
	v_mov_b64_e32 v[40:41], v[24:25]
	v_mov_b64_e32 v[38:39], v[22:23]
	v_mov_b64_e32 v[36:37], v[20:21]
	v_mov_b64_e32 v[58:59], v[10:11]
	v_mov_b64_e32 v[56:57], v[8:9]
	v_mov_b64_e32 v[54:55], v[6:7]
	v_mov_b64_e32 v[52:53], v[4:5]
	s_cbranch_scc1 .LBB0_1449
	v_mul_f32_e32 v50, v34, v68
	v_mul_f32_e32 v51, v35, v68
	v_mul_f32_e32 v48, v32, v68
	v_mul_f32_e32 v49, v33, v68
	v_mul_f32_e32 v46, v30, v68
	v_mul_f32_e32 v47, v31, v68
	v_mul_f32_e32 v44, v28, v68
	v_mul_f32_e32 v45, v29, v68
	v_mul_f32_e32 v42, v26, v68
	v_mul_f32_e32 v43, v27, v68
	v_mul_f32_e32 v40, v24, v68
	v_mul_f32_e32 v41, v25, v68
	v_mul_f32_e32 v38, v22, v68
	v_mul_f32_e32 v39, v23, v68
	v_mul_f32_e32 v36, v20, v68
	v_mul_f32_e32 v37, v21, v68
	v_mul_f32_e32 v66, v18, v68
	v_mul_f32_e32 v67, v19, v68
	v_mul_f32_e32 v64, v16, v68
	v_mul_f32_e32 v65, v17, v68
	v_mul_f32_e32 v62, v14, v68
	v_mul_f32_e32 v63, v15, v68
	v_mul_f32_e32 v60, v12, v68
	v_mul_f32_e32 v61, v13, v68
	v_mul_f32_e32 v58, v10, v68
	v_mul_f32_e32 v59, v11, v68
	v_mul_f32_e32 v56, v8, v68
	v_mul_f32_e32 v57, v9, v68
	v_mul_f32_e32 v54, v6, v68
	v_mul_f32_e32 v55, v7, v68
	v_mul_f32_e32 v52, v4, v68
	v_mul_f32_e32 v53, v5, v68
.LBB0_1449:
	v_sub_f32_e32 v94, v94, v132
	v_sub_f32_e32 v95, v95, v132
	v_lshl_add_u32 v3, v136, 1, s38
	v_exp_f32_e32 v230, v94
	v_exp_f32_e32 v231, v95
	v_sub_f32_e32 v94, v98, v132
	v_sub_f32_e32 v95, v99, v132
	v_sub_f32_e32 v86, v86, v132
	v_sub_f32_e32 v87, v87, v132
	v_exp_f32_e32 v98, v94
	v_exp_f32_e32 v99, v95
	v_sub_f32_e32 v94, v96, v132
	v_sub_f32_e32 v95, v97, v132
	v_exp_f32_e32 v86, v86
	v_exp_f32_e32 v232, v94
	v_add_u32_e32 v94, v3, v190
	v_add_u32_e32 v186, 0x6800, v94
	v_exp_f32_e32 v233, v95
	ds_read2_b64 v[94:97], v186 offset0:64 offset1:66
	v_add_u32_e32 v3, v3, v191
	v_add_u32_e32 v3, 0x6800, v3
	ds_read2_b64 v[226:229], v3 offset0:64 offset1:66
	v_exp_f32_e32 v87, v87
	v_sub_f32_e32 v90, v90, v132
	v_sub_f32_e32 v91, v91, v132
	v_cvt_pk_bf16_f32 v223, v230, v231
	v_exp_f32_e32 v234, v90
	v_exp_f32_e32 v235, v91
	v_sub_f32_e32 v90, v92, v132
	v_sub_f32_e32 v91, v93, v132
	v_cvt_pk_bf16_f32 v222, v86, v87
	v_cvt_pk_bf16_f32 v224, v98, v99
	v_cvt_pk_bf16_f32 v225, v232, v233
	v_exp_f32_e32 v236, v90
	v_exp_f32_e32 v237, v91
	ds_read2_b64 v[90:93], v186 offset0:68 offset1:70
	s_waitcnt lgkmcnt(2)
	v_mfma_f32_32x32x16_bf16 v[36:51], v[94:97], v[222:225], v[36:51]
	v_add_f32_e64 v170, v170, -v132
	v_add_f32_e64 v171, v171, -v132
	v_add_f32_e64 v88, v88, -v132
	v_add_f32_e64 v89, v89, -v132
	v_exp_f32_e32 v170, v170
	v_exp_f32_e32 v171, v171
	v_cvt_pk_bf16_f32 v95, v234, v235
	v_cvt_pk_bf16_f32 v96, v236, v237
	v_cvt_pk_bf16_f32 v94, v170, v171
	s_waitcnt lgkmcnt(1)
	v_mfma_f32_32x32x16_bf16 v[52:67], v[226:229], v[222:225], v[52:67]
	v_exp_f32_e32 v222, v88
	v_exp_f32_e32 v223, v89
	s_nop 0
	v_cvt_pk_bf16_f32 v97, v222, v223
	s_waitcnt lgkmcnt(0)
	s_nop 0
	v_mfma_f32_32x32x16_bf16 v[36:51], v[90:93], v[94:97], v[36:51]
	ds_read2_b64 v[88:91], v3 offset0:68 offset1:70
	s_waitcnt lgkmcnt(0)
	v_mfma_f32_32x32x16_bf16 v[52:67], v[88:91], v[94:97], v[52:67]
	v_add_f32_e64 v80, v80, -v132
	v_add_f32_e64 v81, v81, -v132
	v_add_f32_e64 v78, v78, -v132
	v_add_f32_e64 v79, v79, -v132
	v_exp_f32_e32 v94, v80
	v_exp_f32_e32 v95, v81
	v_exp_f32_e32 v96, v78
	v_exp_f32_e32 v97, v79
	v_sub_f32_e32 v80, v76, v132
	v_sub_f32_e32 v81, v77, v132
	ds_read2_b64 v[76:79], v186 offset0:72 offset1:74
	v_sub_f32_e32 v84, v84, v132
	v_sub_f32_e32 v85, v85, v132
	v_sub_f32_e32 v82, v82, v132
	v_sub_f32_e32 v83, v83, v132
	ds_read2_b64 v[88:91], v3 offset0:72 offset1:74
	v_exp_f32_e32 v84, v84
	v_exp_f32_e32 v85, v85
	v_exp_f32_e32 v92, v82
	v_exp_f32_e32 v93, v83
	v_sub_f32_e32 v74, v74, v132
	v_sub_f32_e32 v75, v75, v132
	v_sub_f32_e32 v70, v70, v132
	v_sub_f32_e32 v71, v71, v132
	v_exp_f32_e32 v224, v80
	v_exp_f32_e32 v225, v81
	v_cvt_pk_bf16_f32 v80, v84, v85
	v_cvt_pk_bf16_f32 v81, v92, v93
	v_cvt_pk_bf16_f32 v82, v94, v95
	v_cvt_pk_bf16_f32 v83, v96, v97
	v_exp_f32_e32 v226, v74
	v_exp_f32_e32 v227, v75
	v_exp_f32_e32 v228, v70
	v_exp_f32_e32 v229, v71
	v_sub_f32_e32 v74, v72, v132
	v_sub_f32_e32 v75, v73, v132
	ds_read2_b64 v[70:73], v186 offset0:76 offset1:78
	s_waitcnt lgkmcnt(2)
	v_mfma_f32_32x32x16_bf16 v[36:51], v[76:79], v[80:83], v[36:51]
	v_cvt_pk_bf16_f32 v78, v224, v225
	v_cvt_pk_bf16_f32 v79, v226, v227
	s_mov_b64 s[24:25], 0
	s_waitcnt lgkmcnt(1)
	v_mfma_f32_32x32x16_bf16 v[52:67], v[88:91], v[80:83], v[52:67]
	v_exp_f32_e32 v82, v74
	v_exp_f32_e32 v83, v75
	v_cvt_pk_bf16_f32 v80, v228, v229
	ds_read2_b64 v[74:77], v3 offset0:76 offset1:78
	v_cvt_pk_bf16_f32 v81, v82, v83
	s_waitcnt lgkmcnt(1)
	s_nop 0
	v_mfma_f32_32x32x16_bf16 v[36:51], v[70:73], v[78:81], v[36:51]
	v_add_f32_e64 v70, v86, 0
	v_add_f32_e64 v71, v87, 0
	v_add_f32_e64 v70, v230, v70
	v_add_f32_e64 v71, v231, v71
	v_add_f32_e64 v70, v98, v70
	v_add_f32_e64 v71, v99, v71
	v_add_f32_e32 v70, v232, v70
	v_add_f32_e32 v71, v233, v71
	s_waitcnt lgkmcnt(0)
	v_mfma_f32_32x32x16_bf16 v[52:67], v[74:77], v[78:81], v[52:67]
	v_add_f32_e64 v70, v170, v70
	v_add_f32_e64 v71, v171, v71
	v_add_f32_e64 v70, v234, v70
	v_add_f32_e64 v71, v235, v71
	v_add_f32_e64 v70, v236, v70
	v_add_f32_e64 v71, v237, v71
	v_add_f32_e32 v70, v222, v70
	v_add_f32_e32 v71, v223, v71
	s_nop 0
	v_add_f32_e32 v70, v84, v70
	v_add_f32_e32 v71, v85, v71
	s_nop 0
	v_add_f32_e32 v70, v92, v70
	v_add_f32_e32 v71, v93, v71
	s_nop 0
	v_add_f32_e32 v70, v94, v70
	v_add_f32_e32 v71, v95, v71
	s_nop 0
	v_add_f32_e32 v70, v96, v70
	v_add_f32_e32 v71, v97, v71
	s_nop 0
	v_add_f32_e32 v70, v224, v70
	v_add_f32_e32 v71, v225, v71
	s_nop 0
	v_add_f32_e32 v70, v226, v70
	v_add_f32_e32 v71, v227, v71
	s_nop 0
	v_add_f32_e32 v70, v228, v70
	v_add_f32_e32 v71, v229, v71
	s_nop 0
	v_add_f32_e32 v70, v82, v70
	v_add_f32_e32 v71, v83, v71
	s_nop 0
	v_add_f32_e32 v3, v70, v71
	ds_bpermute_b32 v70, v179, v3
	s_waitcnt lgkmcnt(0)
	v_add_f32_e32 v3, v3, v70
	v_fmac_f32_e32 v3, v217, v68
.LBB0_1450:
	s_and_b64 vcc, exec, s[24:25]
	s_cbranch_vccz .LBB0_1463
	v_mov_b32_e32 v3, v157
	s_nop 0
	v_mul_f32_e64 v36, v69, -v3
	v_cndmask_b32_e64 v44, v214, v36, s[0:1]
	v_mov_b32_e32 v46, v3
	v_fma_f32 v36, 0, v3, v44
	v_add_f32_e32 v84, v2, v36
	v_add_f32_e32 v85, v3, v36
	v_fma_f32 v86, v46, s64, v36
	v_fma_f32 v87, v46, s65, v36
	ds_read_b128 v[36:39], v220 offset:17920
	v_fmamk_f32 v40, v3, 0x41000000, v44
	v_add_f32_e32 v88, v2, v40
	v_add_f32_e32 v89, v3, v40
	v_fma_f32 v90, v46, s64, v40
	v_fma_f32 v91, v46, s65, v40
	v_fmamk_f32 v40, v3, 0x41800000, v44
	v_add_f32_e32 v92, v2, v40
	v_add_f32_e32 v93, v3, v40
	v_fma_f32 v94, v46, s64, v40
	v_fma_f32 v95, v46, s65, v40
	v_fmamk_f32 v40, v3, 0x41c00000, v44
	v_add_f32_e32 v96, v2, v40
	v_add_f32_e32 v97, v3, v40
	v_fma_f32 v98, v46, s64, v40
	v_fma_f32 v99, v46, s65, v40
	ds_read_b128 v[40:43], v220 offset:17952
	v_fmamk_f32 v48, v3, 0x42000000, v44
	s_waitcnt lgkmcnt(1)
	v_mfma_f32_32x32x16_bf16 v[84:99], v[36:39], v[100:103], v[84:99]
	v_fmamk_f32 v50, v3, 0x42200000, v44
	v_fmamk_f32 v52, v3, 0x42400000, v44
	v_fmac_f32_e32 v44, 0x42600000, v3
	v_add_f32_e64 v68, v2, v48
	v_add_f32_e64 v69, v3, v48
	v_fma_f32 v70, v46, s64, v48
	v_fma_f32 v71, v46, s65, v48
	v_add_f32_e32 v72, v2, v50
	v_add_f32_e32 v73, v3, v50
	v_fma_f32 v74, v46, s64, v50
	v_fma_f32 v75, v46, s65, v50
	s_waitcnt lgkmcnt(0)
	v_mfma_f32_32x32x16_bf16 v[84:99], v[40:43], v[104:107], v[84:99]
	ds_read_b128 v[36:39], v220 offset:17984
	ds_read_b128 v[40:43], v220 offset:18016
	v_add_f32_e64 v76, v2, v52
	v_add_f32_e64 v77, v3, v52
	v_fma_f32 v78, v46, s64, v52
	v_fma_f32 v79, v46, s65, v52
	v_add_f32_e32 v80, v2, v44
	v_add_f32_e32 v81, v3, v44
	v_fma_f32 v82, v46, s64, v44
	v_fma_f32 v83, v46, s65, v44
	v_mov_b64_e32 v[66:67], v[18:19]
	v_mov_b64_e32 v[64:65], v[16:17]
	s_waitcnt lgkmcnt(1)
	v_mfma_f32_32x32x16_bf16 v[84:99], v[36:39], v[108:111], v[84:99]
	ds_read_b128 v[36:39], v219 offset:17920
	v_mov_b64_e32 v[62:63], v[14:15]
	v_mov_b64_e32 v[60:61], v[12:13]
	v_mov_b64_e32 v[58:59], v[10:11]
	v_mov_b64_e32 v[56:57], v[8:9]
	v_mov_b64_e32 v[54:55], v[6:7]
	v_mov_b64_e32 v[52:53], v[4:5]
	s_waitcnt lgkmcnt(1)
	v_mfma_f32_32x32x16_bf16 v[84:99], v[40:43], v[112:115], v[84:99]
	ds_read_b128 v[40:43], v219 offset:17952
	s_waitcnt lgkmcnt(1)
	v_mfma_f32_32x32x16_bf16 v[68:83], v[36:39], v[100:103], v[68:83]
	s_nop 8
	v_max3_f32 v3, v84, s97, v85
	v_max3_f32 v3, v3, v86, v87
	v_max3_f32 v3, v3, v88, v89
	v_max3_f32 v3, v3, v90, v91
	v_max3_f32 v3, v3, v92, v93
	v_max3_f32 v3, v3, v94, v95
	v_max3_f32 v3, v3, v96, v97
	s_waitcnt lgkmcnt(0)
	v_mfma_f32_32x32x16_bf16 v[68:83], v[40:43], v[104:107], v[68:83]
	ds_read_b128 v[36:39], v219 offset:17984
	ds_read_b128 v[40:43], v219 offset:18016
	v_max3_f32 v3, v3, v98, v99
	s_waitcnt lgkmcnt(1)
	v_mfma_f32_32x32x16_bf16 v[68:83], v[36:39], v[108:111], v[68:83]
	s_waitcnt lgkmcnt(0)
	v_mfma_f32_32x32x16_bf16 v[68:83], v[40:43], v[112:115], v[68:83]
	s_nop 11
	v_max3_f32 v3, v3, v68, v69
	v_max3_f32 v3, v3, v70, v71
	v_max3_f32 v3, v3, v72, v73
	v_max3_f32 v3, v3, v74, v75
	v_max3_f32 v3, v3, v76, v77
	v_max3_f32 v3, v3, v78, v79
	v_max3_f32 v3, v3, v80, v81
	v_max3_f32 v3, v3, v82, v83
	ds_bpermute_b32 v36, v179, v3
	s_waitcnt lgkmcnt(0)
	v_max_f32_e32 v36, v36, v36
	v_max_f32_e32 v3, v3, v36
	v_max3_f32 v132, v218, v3, s46
	v_sub_f32_e32 v3, v218, v132
	v_exp_f32_e32 v170, v3
	v_mov_b64_e32 v[50:51], v[34:35]
	v_mov_b64_e32 v[48:49], v[32:33]
	v_mov_b64_e32 v[46:47], v[30:31]
	v_cmp_eq_f32_e32 vcc, 1.0, v170
	s_cmp_eq_u64 vcc, exec
	v_mov_b64_e32 v[44:45], v[28:29]
	v_mov_b64_e32 v[42:43], v[26:27]
	v_mov_b64_e32 v[40:41], v[24:25]
	v_mov_b64_e32 v[38:39], v[22:23]
	v_mov_b64_e32 v[36:37], v[20:21]
	s_cbranch_scc1 .LBB0_1453
	v_mul_f32_e32 v50, v34, v170
	v_mul_f32_e32 v51, v35, v170
	v_mul_f32_e32 v48, v32, v170
	v_mul_f32_e32 v49, v33, v170
	v_mul_f32_e32 v46, v30, v170
	v_mul_f32_e32 v47, v31, v170
	v_mul_f32_e32 v44, v28, v170
	v_mul_f32_e32 v45, v29, v170
	v_mul_f32_e32 v42, v26, v170
	v_mul_f32_e32 v43, v27, v170
	v_mul_f32_e32 v40, v24, v170
	v_mul_f32_e32 v41, v25, v170
	v_mul_f32_e32 v38, v22, v170
	v_mul_f32_e32 v39, v23, v170
	v_mul_f32_e32 v36, v20, v170
	v_mul_f32_e32 v37, v21, v170
	v_mul_f32_e32 v66, v18, v170
	v_mul_f32_e32 v67, v19, v170
	v_mul_f32_e32 v64, v16, v170
	v_mul_f32_e32 v65, v17, v170
	v_mul_f32_e32 v62, v14, v170
	v_mul_f32_e32 v63, v15, v170
	v_mul_f32_e32 v60, v12, v170
	v_mul_f32_e32 v61, v13, v170
	v_mul_f32_e32 v58, v10, v170
	v_mul_f32_e32 v59, v11, v170
	v_mul_f32_e32 v56, v8, v170
	v_mul_f32_e32 v57, v9, v170
	v_mul_f32_e32 v54, v6, v170
	v_mul_f32_e32 v55, v7, v170
	v_mul_f32_e32 v52, v4, v170
	v_mul_f32_e32 v53, v5, v170
.LBB0_1453:
	v_add_u32_e32 v3, v165, v196
	v_sub_f32_e32 v84, v84, v132
	v_sub_f32_e32 v85, v85, v132
	v_sub_f32_e32 v86, v86, v132
	v_sub_f32_e32 v87, v87, v132
	v_sub_f32_e32 v88, v88, v132
	v_sub_f32_e32 v89, v89, v132
	v_sub_f32_e32 v90, v90, v132
	v_sub_f32_e32 v91, v91, v132
	v_add_u32_e32 v171, v3, v190
	v_exp_f32_e32 v84, v84
	v_exp_f32_e32 v85, v85
	v_exp_f32_e32 v86, v86
	v_exp_f32_e32 v87, v87
	v_exp_f32_e32 v88, v88
	v_exp_f32_e32 v89, v89
	v_exp_f32_e32 v90, v90
	v_exp_f32_e32 v91, v91
	v_add_u32_e32 v171, 0x6800, v171
	ds_read2_b64 v[226:229], v171 offset0:64 offset1:66
	ds_read2_b64 v[230:233], v171 offset0:68 offset1:70
	v_add_u32_e32 v3, v3, v191
	v_cvt_pk_bf16_f32 v222, v84, v85
	v_cvt_pk_bf16_f32 v223, v86, v87
	v_cvt_pk_bf16_f32 v224, v88, v89
	v_cvt_pk_bf16_f32 v225, v90, v91
	v_add_u32_e32 v3, 0x6800, v3
	v_sub_f32_e32 v92, v92, v132
	v_sub_f32_e32 v93, v93, v132
	s_waitcnt lgkmcnt(1)
	v_mfma_f32_32x32x16_bf16 v[36:51], v[226:229], v[222:225], v[36:51]
	ds_read2_b64 v[226:229], v3 offset0:64 offset1:66
	ds_read2_b64 v[234:237], v3 offset0:68 offset1:70
	v_add_f32_e64 v94, v94, -v132
	v_add_f32_e64 v95, v95, -v132
	v_add_f32_e64 v96, v96, -v132
	v_add_f32_e64 v97, v97, -v132
	v_sub_f32_e32 v98, v98, v132
	v_sub_f32_e32 v99, v99, v132
	v_exp_f32_e32 v92, v92
	v_exp_f32_e32 v93, v93
	v_exp_f32_e32 v94, v94
	s_waitcnt lgkmcnt(1)
	v_mfma_f32_32x32x16_bf16 v[52:67], v[226:229], v[222:225], v[52:67]
	v_exp_f32_e32 v95, v95
	v_exp_f32_e32 v96, v96
	v_exp_f32_e32 v97, v97
	v_exp_f32_e32 v98, v98
	v_exp_f32_e32 v99, v99
	v_cvt_pk_bf16_f32 v222, v92, v93
	v_cvt_pk_bf16_f32 v223, v94, v95
	v_cvt_pk_bf16_f32 v224, v96, v97
	v_cvt_pk_bf16_f32 v225, v98, v99
	s_nop 1
	v_mfma_f32_32x32x16_bf16 v[36:51], v[230:233], v[222:225], v[36:51]
	s_waitcnt lgkmcnt(0)
	v_mfma_f32_32x32x16_bf16 v[52:67], v[234:237], v[222:225], v[52:67]
	v_add_f32_e64 v74, v74, -v132
	v_add_f32_e64 v75, v75, -v132
	v_add_f32_e64 v68, v68, -v132
	v_add_f32_e64 v69, v69, -v132
	v_add_f32_e64 v70, v70, -v132
	v_add_f32_e64 v71, v71, -v132
	v_sub_f32_e32 v72, v72, v132
	v_sub_f32_e32 v73, v73, v132
	v_exp_f32_e32 v230, v74
	v_exp_f32_e32 v231, v75
	v_sub_f32_e32 v74, v76, v132
	v_sub_f32_e32 v75, v77, v132
	v_exp_f32_e32 v68, v68
	v_exp_f32_e32 v69, v69
	v_exp_f32_e32 v70, v70
	v_exp_f32_e32 v71, v71
	v_exp_f32_e32 v72, v72
	v_exp_f32_e32 v73, v73
	v_exp_f32_e32 v232, v74
	v_exp_f32_e32 v233, v75
	v_sub_f32_e32 v74, v78, v132
	v_sub_f32_e32 v75, v79, v132
	v_cvt_pk_bf16_f32 v76, v72, v73
	v_exp_f32_e32 v234, v74
	v_exp_f32_e32 v235, v75
	v_sub_f32_e32 v74, v80, v132
	v_sub_f32_e32 v75, v81, v132
	ds_read2_b64 v[78:81], v171 offset0:72 offset1:74
	ds_read2_b64 v[222:225], v171 offset0:76 offset1:78
	v_exp_f32_e32 v236, v74
	v_exp_f32_e32 v237, v75
	v_sub_f32_e32 v74, v82, v132
	v_sub_f32_e32 v75, v83, v132
	v_cvt_pk_bf16_f32 v77, v230, v231
	v_exp_f32_e32 v82, v74
	v_exp_f32_e32 v83, v75
	v_cvt_pk_bf16_f32 v74, v68, v69
	v_cvt_pk_bf16_f32 v75, v70, v71
	s_mov_b64 s[24:25], 0
	s_waitcnt lgkmcnt(1)
	v_mfma_f32_32x32x16_bf16 v[36:51], v[78:81], v[74:77], v[36:51]
	ds_read2_b64 v[78:81], v3 offset0:72 offset1:74
	ds_read2_b64 v[226:229], v3 offset0:76 offset1:78
	s_waitcnt lgkmcnt(1)
	v_mfma_f32_32x32x16_bf16 v[52:67], v[78:81], v[74:77], v[52:67]
	v_cvt_pk_bf16_f32 v74, v232, v233
	v_cvt_pk_bf16_f32 v75, v234, v235
	v_cvt_pk_bf16_f32 v76, v236, v237
	v_cvt_pk_bf16_f32 v77, v82, v83
	s_nop 1
	v_mfma_f32_32x32x16_bf16 v[36:51], v[222:225], v[74:77], v[36:51]
	s_waitcnt lgkmcnt(0)
	v_mfma_f32_32x32x16_bf16 v[52:67], v[226:229], v[74:77], v[52:67]
	v_add_f32_e64 v74, v84, 0
	v_add_f32_e64 v75, v85, 0
	v_add_f32_e64 v74, v86, v74
	v_add_f32_e64 v75, v87, v75
	v_add_f32_e64 v74, v88, v74
	v_add_f32_e64 v75, v89, v75
	v_add_f32_e32 v74, v90, v74
	v_add_f32_e32 v75, v91, v75
	s_nop 0
	v_add_f32_e32 v74, v92, v74
	v_add_f32_e32 v75, v93, v75
	s_nop 0
	v_add_f32_e32 v74, v94, v74
	v_add_f32_e32 v75, v95, v75
	s_nop 0
	v_add_f32_e32 v74, v96, v74
	v_add_f32_e32 v75, v97, v75
	s_nop 0
	v_add_f32_e32 v74, v98, v74
	v_add_f32_e32 v75, v99, v75
	s_nop 0
	v_add_f32_e32 v68, v68, v74
	v_add_f32_e32 v69, v69, v75
	s_nop 0
	v_add_f32_e32 v68, v70, v68
	v_add_f32_e32 v69, v71, v69
	s_nop 0
	v_add_f32_e32 v68, v72, v68
	v_add_f32_e32 v69, v73, v69
	s_nop 0
	v_add_f32_e32 v68, v230, v68
	v_add_f32_e32 v69, v231, v69
	s_nop 0
	v_add_f32_e32 v68, v232, v68
	v_add_f32_e32 v69, v233, v69
	s_nop 0
	v_add_f32_e32 v68, v234, v68
	v_add_f32_e32 v69, v235, v69
	s_nop 0
	v_add_f32_e32 v68, v236, v68
	v_add_f32_e32 v69, v237, v69
	s_nop 0
	v_add_f32_e32 v68, v82, v68
	v_add_f32_e32 v69, v83, v69
	s_nop 0
	v_add_f32_e32 v3, v68, v69
	ds_bpermute_b32 v68, v179, v3
	s_waitcnt lgkmcnt(0)
	v_add_f32_e32 v3, v3, v68
	v_fmac_f32_e32 v3, v217, v170

.LBB0_1455:
	v_sub_u32_e32 v68, v161, v221
	s_cmp_gt_i32 s39, s76
	v_cvt_f32_i32_e32 v69, v68
	s_cselect_b64 s[0:1], -1, 0
	s_and_b64 s[0:1], s[2:3], s[0:1]
	s_andn2_b64 vcc, exec, s[0:1]
	s_mov_b64 s[0:1], -1
	s_cbranch_vccz .LBB0_1459
	v_mov_b32_e32 v3, v157
	ds_read_b128 v[52:55], v220 offset:17920
	ds_read_b128 v[56:59], v220 offset:17952
	v_mul_f32_e64 v66, v69, -v3
	v_mov_b32_e32 v78, v3
	v_fma_f32 v38, 0, v3, v66
	v_fmamk_f32 v42, v3, 0x41000000, v66
	v_fmamk_f32 v46, v3, 0x41800000, v66
	v_fmamk_f32 v50, v3, 0x41c00000, v66
	v_add_f32_e32 v36, v2, v38
	v_add_f32_e32 v37, v3, v38
	v_fma_f32 v39, v78, s65, v38
	v_fma_f32 v38, v78, s64, v38
	v_add_f32_e32 v40, v2, v42
	v_add_f32_e32 v41, v3, v42
	v_fma_f32 v43, v78, s65, v42
	v_fma_f32 v42, v78, s64, v42
	v_add_f32_e32 v44, v2, v46
	v_add_f32_e32 v45, v3, v46
	v_fma_f32 v47, v78, s65, v46
	v_fma_f32 v46, v78, s64, v46
	v_add_f32_e32 v48, v2, v50
	v_add_f32_e32 v49, v3, v50
	v_fma_f32 v51, v78, s65, v50
	v_fma_f32 v50, v78, s64, v50
	v_fmamk_f32 v60, v3, 0x42200000, v66
	v_fmamk_f32 v62, v3, 0x42400000, v66
	s_waitcnt lgkmcnt(1)
	v_mfma_f32_32x32x16_bf16 v[36:51], v[52:55], v[100:103], v[36:51]
	v_cmp_gt_u32_e32 vcc, s47, v68
	s_waitcnt lgkmcnt(0)
	v_mfma_f32_32x32x16_bf16 v[36:51], v[56:59], v[104:107], v[36:51]
	ds_read_b128 v[52:55], v220 offset:17984
	ds_read_b128 v[56:59], v220 offset:18016
	ds_read_b128 v[70:73], v219 offset:17920
	ds_read_b128 v[74:77], v219 offset:17952
	s_waitcnt lgkmcnt(3)
	v_mfma_f32_32x32x16_bf16 v[36:51], v[52:55], v[108:111], v[36:51]
	v_fmamk_f32 v54, v3, 0x42000000, v66
	v_fmac_f32_e32 v66, 0x42600000, v3
	v_add_f32_e64 v52, v2, v54
	v_add_f32_e64 v53, v3, v54
	v_fma_f32 v55, v78, s65, v54
	v_fma_f32 v54, v78, s64, v54
	v_add_f32_e32 v64, v2, v66
	v_add_f32_e32 v65, v3, v66
	v_fma_f32 v67, v78, s65, v66
	v_fma_f32 v66, v78, s64, v66
	s_waitcnt lgkmcnt(2)
	v_mfma_f32_32x32x16_bf16 v[36:51], v[56:59], v[112:115], v[36:51]
	v_add_f32_e64 v56, v2, v60
	v_add_f32_e64 v57, v3, v60
	v_fma_f32 v58, v78, s64, v60
	v_fma_f32 v59, v78, s65, v60
	v_add_f32_e64 v60, v2, v62
	v_add_f32_e64 v61, v3, v62
	v_fma_f32 v63, v78, s65, v62
	v_fma_f32 v62, v78, s64, v62
	v_add_u32_e32 v3, -1, v68
	s_nop 3
	v_cndmask_b32_e32 v88, v214, v36, vcc
	s_waitcnt lgkmcnt(1)
	v_mfma_f32_32x32x16_bf16 v[52:67], v[70:73], v[100:103], v[52:67]
	ds_read_b128 v[70:73], v219 offset:17984
	ds_read_b128 v[78:81], v219 offset:18016
	v_cmp_gt_u32_e32 vcc, s47, v3
	v_add_u32_e32 v36, -2, v68
	s_nop 0
	v_cndmask_b32_e32 v89, v214, v37, vcc
	v_cmp_gt_u32_e32 vcc, s47, v36
	v_add_u32_e32 v36, -3, v68
	s_waitcnt lgkmcnt(2)
	v_mfma_f32_32x32x16_bf16 v[52:67], v[74:77], v[104:107], v[52:67]
	v_cndmask_b32_e32 v94, v214, v38, vcc
	v_cmp_gt_u32_e32 vcc, s47, v36
	v_add_u32_e32 v36, -8, v68
	v_max3_f32 v3, v88, s97, v89
	v_cndmask_b32_e32 v95, v214, v39, vcc
	v_cmp_gt_u32_e32 vcc, s47, v36
	v_add_u32_e32 v36, -9, v68
	s_waitcnt lgkmcnt(1)
	v_mfma_f32_32x32x16_bf16 v[52:67], v[70:73], v[108:111], v[52:67]
	v_cndmask_b32_e32 v96, v214, v40, vcc
	v_cmp_gt_u32_e32 vcc, s47, v36
	v_add_u32_e32 v36, -10, v68
	v_max3_f32 v3, v3, v94, v95
	v_cndmask_b32_e32 v97, v214, v41, vcc
	v_cmp_gt_u32_e32 vcc, s47, v36
	v_add_u32_e32 v36, -11, v68
	s_waitcnt lgkmcnt(0)
	v_mfma_f32_32x32x16_bf16 v[52:67], v[78:81], v[112:115], v[52:67]
	v_cndmask_b32_e32 v98, v214, v42, vcc
	v_cmp_gt_u32_e32 vcc, s47, v36
	v_add_u32_e32 v36, -16, v68
	v_max3_f32 v3, v3, v96, v97
	v_cndmask_b32_e32 v99, v214, v43, vcc
	v_cmp_gt_u32_e32 vcc, s47, v36
	v_subrev_u32_e32 v36, 17, v68
	v_max3_f32 v3, v3, v98, v99
	v_cndmask_b32_e32 v170, v214, v44, vcc
	v_cmp_gt_u32_e32 vcc, s47, v36
	v_subrev_u32_e32 v36, 18, v68
	s_nop 0
	v_cndmask_b32_e32 v171, v214, v45, vcc
	v_cmp_gt_u32_e32 vcc, s47, v36
	v_subrev_u32_e32 v36, 19, v68
	v_max3_f32 v3, v3, v170, v171
	v_cndmask_b32_e32 v90, v214, v46, vcc
	v_cmp_gt_u32_e32 vcc, s47, v36
	v_subrev_u32_e32 v36, 24, v68
	s_nop 0
	v_cndmask_b32_e32 v91, v214, v47, vcc
	v_cmp_gt_u32_e32 vcc, s47, v36
	v_subrev_u32_e32 v36, 25, v68
	v_max3_f32 v3, v3, v90, v91
	v_cndmask_b32_e32 v92, v214, v48, vcc
	v_cmp_gt_u32_e32 vcc, s47, v36
	v_subrev_u32_e32 v36, 26, v68
	s_nop 0
	v_cndmask_b32_e32 v93, v214, v49, vcc
	v_cmp_gt_u32_e32 vcc, s47, v36
	v_subrev_u32_e32 v36, 27, v68
	v_max3_f32 v3, v3, v92, v93
	v_cndmask_b32_e32 v86, v214, v50, vcc
	v_cmp_gt_u32_e32 vcc, s47, v36
	v_subrev_u32_e32 v36, 32, v68
	s_nop 0
	v_cndmask_b32_e32 v87, v214, v51, vcc
	v_cmp_gt_u32_e32 vcc, s47, v36
	v_subrev_u32_e32 v36, 33, v68
	v_max3_f32 v3, v3, v86, v87
	v_cndmask_b32_e32 v76, v214, v52, vcc
	v_cmp_gt_u32_e32 vcc, s47, v36
	v_subrev_u32_e32 v36, 34, v68
	s_nop 0
	v_cndmask_b32_e32 v77, v214, v53, vcc
	v_cmp_gt_u32_e32 vcc, s47, v36
	v_subrev_u32_e32 v36, 35, v68
	v_max3_f32 v3, v3, v76, v77
	v_cndmask_b32_e32 v78, v214, v54, vcc
	v_cmp_gt_u32_e32 vcc, s47, v36
	v_subrev_u32_e32 v36, 40, v68
	s_nop 0
	v_cndmask_b32_e32 v79, v214, v55, vcc
	v_cmp_gt_u32_e32 vcc, s47, v36
	v_subrev_u32_e32 v36, 41, v68
	v_max3_f32 v3, v3, v78, v79
	v_cndmask_b32_e32 v80, v214, v56, vcc
	v_cmp_gt_u32_e32 vcc, s47, v36
	v_subrev_u32_e32 v36, 42, v68
	s_nop 0
	v_cndmask_b32_e32 v81, v214, v57, vcc
	v_cmp_gt_u32_e32 vcc, s47, v36
	v_subrev_u32_e32 v36, 43, v68
	v_max3_f32 v3, v3, v80, v81
	v_cndmask_b32_e32 v82, v214, v58, vcc
	v_cmp_gt_u32_e32 vcc, s47, v36
	v_subrev_u32_e32 v36, 48, v68
	s_nop 0
	v_cndmask_b32_e32 v83, v214, v59, vcc
	v_cmp_gt_u32_e32 vcc, s47, v36
	v_subrev_u32_e32 v36, 49, v68
	v_max3_f32 v3, v3, v82, v83
	v_cndmask_b32_e32 v84, v214, v60, vcc
	v_cmp_gt_u32_e32 vcc, s47, v36
	v_subrev_u32_e32 v36, 50, v68
	s_nop 0
	v_cndmask_b32_e32 v85, v214, v61, vcc
	v_cmp_gt_u32_e32 vcc, s47, v36
	v_subrev_u32_e32 v36, 51, v68
	v_max3_f32 v3, v3, v84, v85
	v_cndmask_b32_e32 v74, v214, v62, vcc
	v_cmp_gt_u32_e32 vcc, s47, v36
	v_subrev_u32_e32 v36, 56, v68
	s_nop 0
	v_cndmask_b32_e32 v75, v214, v63, vcc
	v_cmp_gt_u32_e32 vcc, s47, v36
	v_subrev_u32_e32 v36, 57, v68
	v_max3_f32 v3, v3, v74, v75
	v_cndmask_b32_e32 v70, v214, v64, vcc
	v_cmp_gt_u32_e32 vcc, s47, v36
	v_subrev_u32_e32 v36, 58, v68
	s_nop 0
	v_cndmask_b32_e32 v71, v214, v65, vcc
	v_cmp_gt_u32_e32 vcc, s47, v36
	v_subrev_u32_e32 v36, 59, v68
	v_max3_f32 v3, v3, v70, v71
	v_cndmask_b32_e32 v72, v214, v66, vcc
	v_cmp_gt_u32_e32 vcc, s47, v36
	s_nop 1
	v_cndmask_b32_e32 v73, v214, v67, vcc
	v_max3_f32 v3, v3, v72, v73
	ds_bpermute_b32 v36, v179, v3
	v_mov_b64_e32 v[66:67], v[18:19]
	v_mov_b64_e32 v[64:65], v[16:17]
	v_mov_b64_e32 v[62:63], v[14:15]
	v_mov_b64_e32 v[60:61], v[12:13]
	s_waitcnt lgkmcnt(0)
	v_max_f32_e32 v36, v36, v36
	v_max_f32_e32 v3, v3, v36
	v_max3_f32 v132, v218, v3, s46
	v_sub_f32_e32 v3, v218, v132
	v_exp_f32_e32 v68, v3
	v_mov_b64_e32 v[50:51], v[34:35]
	v_mov_b64_e32 v[48:49], v[32:33]
	v_mov_b64_e32 v[46:47], v[30:31]
	v_cmp_eq_f32_e32 vcc, 1.0, v68
	s_cmp_eq_u64 vcc, exec
	v_mov_b64_e32 v[44:45], v[28:29]
	v_mov_b64_e32 v[42:43], v[26:27]
	v_mov_b64_e32 v[40:41], v[24:25]
	v_mov_b64_e32 v[38:39], v[22:23]
	v_mov_b64_e32 v[36:37], v[20:21]
	v_mov_b64_e32 v[58:59], v[10:11]
	v_mov_b64_e32 v[56:57], v[8:9]
	v_mov_b64_e32 v[54:55], v[6:7]
	v_mov_b64_e32 v[52:53], v[4:5]
	s_cbranch_scc1 .LBB0_1458
	v_mul_f32_e32 v50, v34, v68
	v_mul_f32_e32 v51, v35, v68
	v_mul_f32_e32 v48, v32, v68
	v_mul_f32_e32 v49, v33, v68
	v_mul_f32_e32 v46, v30, v68
	v_mul_f32_e32 v47, v31, v68
	v_mul_f32_e32 v44, v28, v68
	v_mul_f32_e32 v45, v29, v68
	v_mul_f32_e32 v42, v26, v68
	v_mul_f32_e32 v43, v27, v68
	v_mul_f32_e32 v40, v24, v68
	v_mul_f32_e32 v41, v25, v68
	v_mul_f32_e32 v38, v22, v68
	v_mul_f32_e32 v39, v23, v68
	v_mul_f32_e32 v36, v20, v68
	v_mul_f32_e32 v37, v21, v68
	v_mul_f32_e32 v66, v18, v68
	v_mul_f32_e32 v67, v19, v68
	v_mul_f32_e32 v64, v16, v68
	v_mul_f32_e32 v65, v17, v68
	v_mul_f32_e32 v62, v14, v68
	v_mul_f32_e32 v63, v15, v68
	v_mul_f32_e32 v60, v12, v68
	v_mul_f32_e32 v61, v13, v68
	v_mul_f32_e32 v58, v10, v68
	v_mul_f32_e32 v59, v11, v68
	v_mul_f32_e32 v56, v8, v68
	v_mul_f32_e32 v57, v9, v68
	v_mul_f32_e32 v54, v6, v68
	v_mul_f32_e32 v55, v7, v68
	v_mul_f32_e32 v52, v4, v68
	v_mul_f32_e32 v53, v5, v68
.LBB0_1458:
	v_sub_f32_e32 v94, v94, v132
	v_sub_f32_e32 v95, v95, v132
	v_lshl_add_u32 v3, v136, 1, s38
	v_exp_f32_e32 v230, v94
	v_exp_f32_e32 v231, v95
	v_sub_f32_e32 v94, v96, v132
	v_sub_f32_e32 v95, v97, v132
	v_sub_f32_e32 v88, v88, v132
	v_sub_f32_e32 v89, v89, v132
	v_exp_f32_e32 v232, v94
	v_exp_f32_e32 v233, v95
	v_sub_f32_e32 v94, v98, v132
	v_sub_f32_e32 v95, v99, v132
	v_exp_f32_e32 v88, v88
	v_exp_f32_e32 v98, v94
	v_add_u32_e32 v94, v3, v190
	v_add_u32_e32 v186, 0x6800, v94
	v_exp_f32_e32 v99, v95
	ds_read2_b64 v[94:97], v186 offset0:64 offset1:66
	v_add_u32_e32 v3, v3, v191
	v_add_u32_e32 v3, 0x6800, v3
	ds_read2_b64 v[226:229], v3 offset0:64 offset1:66
	v_exp_f32_e32 v89, v89
	v_sub_f32_e32 v90, v90, v132
	v_sub_f32_e32 v91, v91, v132
	v_cvt_pk_bf16_f32 v223, v230, v231
	v_exp_f32_e32 v234, v90
	v_exp_f32_e32 v235, v91
	v_sub_f32_e32 v90, v92, v132
	v_sub_f32_e32 v91, v93, v132
	v_cvt_pk_bf16_f32 v222, v88, v89
	v_cvt_pk_bf16_f32 v224, v232, v233
	v_cvt_pk_bf16_f32 v225, v98, v99
	v_exp_f32_e32 v236, v90
	v_exp_f32_e32 v237, v91
	ds_read2_b64 v[90:93], v186 offset0:68 offset1:70
	s_waitcnt lgkmcnt(2)
	v_mfma_f32_32x32x16_bf16 v[36:51], v[94:97], v[222:225], v[36:51]
	v_add_f32_e64 v170, v170, -v132
	v_add_f32_e64 v171, v171, -v132
	v_add_f32_e64 v86, v86, -v132
	v_add_f32_e64 v87, v87, -v132
	v_exp_f32_e32 v170, v170
	v_exp_f32_e32 v171, v171
	v_cvt_pk_bf16_f32 v95, v234, v235
	v_cvt_pk_bf16_f32 v96, v236, v237
	v_cvt_pk_bf16_f32 v94, v170, v171
	s_waitcnt lgkmcnt(1)
	v_mfma_f32_32x32x16_bf16 v[52:67], v[226:229], v[222:225], v[52:67]
	v_exp_f32_e32 v222, v86
	v_exp_f32_e32 v223, v87
	s_nop 0
	v_cvt_pk_bf16_f32 v97, v222, v223
	s_waitcnt lgkmcnt(0)
	s_nop 0
	v_mfma_f32_32x32x16_bf16 v[36:51], v[90:93], v[94:97], v[36:51]
	ds_read2_b64 v[90:93], v3 offset0:68 offset1:70
	s_waitcnt lgkmcnt(0)
	v_mfma_f32_32x32x16_bf16 v[52:67], v[90:93], v[94:97], v[52:67]
	v_add_f32_e64 v76, v76, -v132
	v_add_f32_e64 v77, v77, -v132
	v_add_f32_e64 v74, v74, -v132
	v_add_f32_e64 v75, v75, -v132
	v_exp_f32_e32 v90, v76
	v_exp_f32_e32 v91, v77
	v_sub_f32_e32 v76, v78, v132
	v_sub_f32_e32 v77, v79, v132
	v_sub_f32_e32 v70, v70, v132
	v_sub_f32_e32 v71, v71, v132
	v_exp_f32_e32 v92, v76
	v_exp_f32_e32 v93, v77
	v_sub_f32_e32 v76, v80, v132
	v_sub_f32_e32 v77, v81, v132
	v_sub_f32_e32 v80, v84, v132
	v_sub_f32_e32 v81, v85, v132
	v_exp_f32_e32 v94, v76
	v_exp_f32_e32 v95, v77
	v_sub_f32_e32 v76, v82, v132
	v_sub_f32_e32 v77, v83, v132
	ds_read2_b64 v[84:87], v3 offset0:72 offset1:74
	v_exp_f32_e32 v96, v76
	v_exp_f32_e32 v97, v77
	ds_read2_b64 v[76:79], v186 offset0:72 offset1:74
	v_exp_f32_e32 v224, v80
	v_exp_f32_e32 v225, v81
	v_cvt_pk_bf16_f32 v80, v90, v91
	v_cvt_pk_bf16_f32 v81, v92, v93
	v_cvt_pk_bf16_f32 v82, v94, v95
	v_cvt_pk_bf16_f32 v83, v96, v97
	v_exp_f32_e32 v226, v74
	v_exp_f32_e32 v227, v75
	v_exp_f32_e32 v228, v70
	v_exp_f32_e32 v229, v71
	v_sub_f32_e32 v74, v72, v132
	v_sub_f32_e32 v75, v73, v132
	ds_read2_b64 v[70:73], v186 offset0:76 offset1:78
	s_waitcnt lgkmcnt(1)
	v_mfma_f32_32x32x16_bf16 v[36:51], v[76:79], v[80:83], v[36:51]
	v_cvt_pk_bf16_f32 v78, v224, v225
	v_cvt_pk_bf16_f32 v79, v226, v227
	s_mov_b64 s[0:1], 0
	v_mfma_f32_32x32x16_bf16 v[52:67], v[84:87], v[80:83], v[52:67]
	v_exp_f32_e32 v82, v74
	v_exp_f32_e32 v83, v75
	v_cvt_pk_bf16_f32 v80, v228, v229
	ds_read2_b64 v[74:77], v3 offset0:76 offset1:78
	v_cvt_pk_bf16_f32 v81, v82, v83
	s_waitcnt lgkmcnt(1)
	s_nop 0
	v_mfma_f32_32x32x16_bf16 v[36:51], v[70:73], v[78:81], v[36:51]
	v_add_f32_e64 v70, v88, 0
	v_add_f32_e64 v71, v89, 0
	v_add_f32_e64 v70, v230, v70
	v_add_f32_e64 v71, v231, v71
	v_add_f32_e64 v70, v232, v70
	v_add_f32_e64 v71, v233, v71
	v_add_f32_e32 v70, v98, v70
	v_add_f32_e32 v71, v99, v71
	s_waitcnt lgkmcnt(0)
	v_mfma_f32_32x32x16_bf16 v[52:67], v[74:77], v[78:81], v[52:67]
	v_add_f32_e64 v70, v170, v70
	v_add_f32_e64 v71, v171, v71
	v_add_f32_e64 v70, v234, v70
	v_add_f32_e64 v71, v235, v71
	v_add_f32_e64 v70, v236, v70
	v_add_f32_e64 v71, v237, v71
	v_add_f32_e32 v70, v222, v70
	v_add_f32_e32 v71, v223, v71
	s_nop 0
	v_add_f32_e32 v70, v90, v70
	v_add_f32_e32 v71, v91, v71
	s_nop 0
	v_add_f32_e32 v70, v92, v70
	v_add_f32_e32 v71, v93, v71
	s_nop 0
	v_add_f32_e32 v70, v94, v70
	v_add_f32_e32 v71, v95, v71
	s_nop 0
	v_add_f32_e32 v70, v96, v70
	v_add_f32_e32 v71, v97, v71
	s_nop 0
	v_add_f32_e32 v70, v224, v70
	v_add_f32_e32 v71, v225, v71
	s_nop 0
	v_add_f32_e32 v70, v226, v70
	v_add_f32_e32 v71, v227, v71
	s_nop 0
	v_add_f32_e32 v70, v228, v70
	v_add_f32_e32 v71, v229, v71
	s_nop 0
	v_add_f32_e32 v70, v82, v70
	v_add_f32_e32 v71, v83, v71
	s_nop 0
	v_add_f32_e32 v3, v70, v71
	ds_bpermute_b32 v70, v179, v3
	s_waitcnt lgkmcnt(0)
	v_add_f32_e32 v3, v3, v70
	v_fmac_f32_e32 v3, v217, v68
.LBB0_1459:
	s_and_b64 vcc, exec, s[0:1]
	s_cbranch_vccz .LBB0_1464
	v_mov_b32_e32 v3, v157
	s_nop 0
	v_mul_f32_e64 v50, v69, -v3
	v_mov_b32_e32 v68, v3
	v_fma_f32 v36, 0, v3, v50
	v_add_f32_e32 v52, v2, v36
	v_add_f32_e32 v53, v3, v36
	v_fma_f32 v54, v68, s64, v36
	v_fma_f32 v55, v68, s65, v36
	v_fmamk_f32 v36, v3, 0x41000000, v50
	v_add_f32_e32 v56, v2, v36
	v_add_f32_e32 v57, v3, v36
	v_fma_f32 v58, v68, s64, v36
	v_fma_f32 v59, v68, s65, v36
	v_fmamk_f32 v36, v3, 0x41800000, v50
	v_add_f32_e32 v60, v2, v36
	v_add_f32_e32 v61, v3, v36
	v_fma_f32 v62, v68, s64, v36
	v_fma_f32 v63, v68, s65, v36
	v_fmamk_f32 v36, v3, 0x41c00000, v50
	v_add_f32_e32 v64, v2, v36
	v_add_f32_e32 v65, v3, v36
	v_fma_f32 v66, v68, s64, v36
	v_fma_f32 v67, v68, s65, v36
	ds_read_b128 v[36:39], v220 offset:17920
	ds_read_b128 v[40:43], v220 offset:17952
	s_waitcnt lgkmcnt(1)
	v_mfma_f32_32x32x16_bf16 v[52:67], v[36:39], v[100:103], v[52:67]
	ds_read_b128 v[36:39], v220 offset:17984
	v_fmamk_f32 v46, v3, 0x42400000, v50
	v_add_f32_e64 v44, v2, v46
	v_add_f32_e64 v45, v3, v46
	v_fma_f32 v47, v68, s65, v46
	v_fma_f32 v46, v68, s64, v46
	s_waitcnt lgkmcnt(1)
	v_mfma_f32_32x32x16_bf16 v[52:67], v[40:43], v[104:107], v[52:67]
	v_fmamk_f32 v42, v3, 0x42200000, v50
	v_add_f32_e64 v40, v2, v42
	v_add_f32_e64 v41, v3, v42
	v_fma_f32 v43, v68, s65, v42
	v_fma_f32 v42, v68, s64, v42
	s_waitcnt lgkmcnt(0)
	v_mfma_f32_32x32x16_bf16 v[52:67], v[36:39], v[108:111], v[52:67]
	ds_read_b128 v[36:39], v220 offset:18016
	s_waitcnt lgkmcnt(0)
	v_mfma_f32_32x32x16_bf16 v[52:67], v[36:39], v[112:115], v[52:67]
	v_fmamk_f32 v38, v3, 0x42000000, v50
	v_fmac_f32_e32 v50, 0x42600000, v3
	v_add_f32_e64 v36, v2, v38
	v_add_f32_e64 v37, v3, v38
	v_fma_f32 v39, v68, s65, v38
	v_fma_f32 v38, v68, s64, v38
	v_add_f32_e32 v48, v2, v50
	v_add_f32_e32 v49, v3, v50
	v_fma_f32 v51, v68, s65, v50
	v_fma_f32 v50, v68, s64, v50
	ds_read_b128 v[68:71], v219 offset:17920
	ds_read_b128 v[72:75], v219 offset:17952
	s_waitcnt lgkmcnt(1)
	v_mfma_f32_32x32x16_bf16 v[36:51], v[68:71], v[100:103], v[36:51]
	ds_read_b128 v[68:71], v219 offset:17984
	v_max3_f32 v3, v52, s97, v53
	v_max3_f32 v3, v3, v54, v55
	v_max3_f32 v3, v3, v56, v57
	v_max3_f32 v3, v3, v58, v59
	v_max3_f32 v3, v3, v60, v61
	v_max3_f32 v3, v3, v62, v63
	s_waitcnt lgkmcnt(1)
	v_mfma_f32_32x32x16_bf16 v[36:51], v[72:75], v[104:107], v[36:51]
	v_max3_f32 v3, v3, v64, v65
	v_max3_f32 v3, v3, v66, v67
	s_waitcnt lgkmcnt(0)
	v_mfma_f32_32x32x16_bf16 v[36:51], v[68:71], v[108:111], v[36:51]
	ds_read_b128 v[68:71], v219 offset:18016
	s_waitcnt lgkmcnt(0)
	v_mfma_f32_32x32x16_bf16 v[36:51], v[68:71], v[112:115], v[36:51]
	s_nop 11
	v_max3_f32 v3, v3, v36, v37
	v_max3_f32 v3, v3, v38, v39
	v_max3_f32 v3, v3, v40, v41
	v_max3_f32 v3, v3, v42, v43
	v_max3_f32 v3, v3, v44, v45
	v_max3_f32 v3, v3, v46, v47
	v_max3_f32 v3, v3, v48, v49
	v_max3_f32 v3, v3, v50, v51
	ds_bpermute_b32 v68, v179, v3
	s_waitcnt lgkmcnt(0)
	v_max_f32_e32 v68, v68, v68
	v_max_f32_e32 v3, v3, v68
	v_max3_f32 v132, v218, v3, s46
	v_sub_f32_e32 v3, v218, v132
	v_exp_f32_e32 v68, v3
	s_nop 0
	v_cmp_eq_f32_e32 vcc, 1.0, v68
	s_cmp_eq_u64 vcc, exec
	s_cbranch_scc1 .LBB0_1462
	v_mul_f32_e32 v34, v34, v68
	v_mul_f32_e32 v35, v35, v68
	v_mul_f32_e32 v32, v32, v68
	v_mul_f32_e32 v33, v33, v68
	v_mul_f32_e32 v30, v30, v68
	v_mul_f32_e32 v31, v31, v68
	v_mul_f32_e32 v28, v28, v68
	v_mul_f32_e32 v29, v29, v68
	v_mul_f32_e32 v26, v26, v68
	v_mul_f32_e32 v27, v27, v68
	v_mul_f32_e32 v24, v24, v68
	v_mul_f32_e32 v25, v25, v68
	v_mul_f32_e32 v22, v22, v68
	v_mul_f32_e32 v23, v23, v68
	v_mul_f32_e32 v20, v20, v68
	v_mul_f32_e32 v21, v21, v68
	v_mul_f32_e32 v18, v18, v68
	v_mul_f32_e32 v19, v19, v68
	v_mul_f32_e32 v16, v16, v68
	v_mul_f32_e32 v17, v17, v68
	v_mul_f32_e32 v14, v14, v68
	v_mul_f32_e32 v15, v15, v68
	v_mul_f32_e32 v12, v12, v68
	v_mul_f32_e32 v13, v13, v68
	v_mul_f32_e32 v10, v10, v68
	v_mul_f32_e32 v11, v11, v68
	v_mul_f32_e32 v8, v8, v68
	v_mul_f32_e32 v9, v9, v68
	v_mul_f32_e32 v6, v6, v68
	v_mul_f32_e32 v7, v7, v68
	v_mul_f32_e32 v4, v4, v68
	v_mul_f32_e32 v5, v5, v68
.LBB0_1462:
	v_add_u32_e32 v3, v165, v196
	v_sub_f32_e32 v52, v52, v132
	v_sub_f32_e32 v53, v53, v132
	v_sub_f32_e32 v54, v54, v132
	v_sub_f32_e32 v55, v55, v132
	v_sub_f32_e32 v56, v56, v132
	v_sub_f32_e32 v57, v57, v132
	v_sub_f32_e32 v58, v58, v132
	v_sub_f32_e32 v59, v59, v132
	v_add_u32_e32 v69, v3, v190
	v_exp_f32_e32 v52, v52
	v_exp_f32_e32 v53, v53
	v_exp_f32_e32 v54, v54
	v_exp_f32_e32 v55, v55
	v_exp_f32_e32 v56, v56
	v_exp_f32_e32 v57, v57
	v_exp_f32_e32 v58, v58
	v_exp_f32_e32 v59, v59
	v_add_u32_e32 v69, 0x6800, v69
	ds_read2_b64 v[74:77], v69 offset0:64 offset1:66
	ds_read2_b64 v[78:81], v69 offset0:68 offset1:70
	v_add_u32_e32 v3, v3, v191
	v_cvt_pk_bf16_f32 v70, v52, v53
	v_cvt_pk_bf16_f32 v71, v54, v55
	v_cvt_pk_bf16_f32 v72, v56, v57
	v_cvt_pk_bf16_f32 v73, v58, v59
	v_add_u32_e32 v3, 0x6800, v3
	v_sub_f32_e32 v60, v60, v132
	v_sub_f32_e32 v61, v61, v132
	s_waitcnt lgkmcnt(1)
	v_mfma_f32_32x32x16_bf16 v[20:35], v[74:77], v[70:73], v[20:35]
	ds_read2_b64 v[74:77], v3 offset0:64 offset1:66
	ds_read2_b64 v[82:85], v3 offset0:68 offset1:70
	v_add_f32_e64 v62, v62, -v132
	v_add_f32_e64 v63, v63, -v132
	v_add_f32_e64 v64, v64, -v132
	v_add_f32_e64 v65, v65, -v132
	v_sub_f32_e32 v66, v66, v132
	v_sub_f32_e32 v67, v67, v132
	v_exp_f32_e32 v60, v60
	v_exp_f32_e32 v61, v61
	v_exp_f32_e32 v62, v62
	s_waitcnt lgkmcnt(1)
	v_mfma_f32_32x32x16_bf16 v[4:19], v[74:77], v[70:73], v[4:19]
	v_exp_f32_e32 v63, v63
	v_exp_f32_e32 v64, v64
	v_exp_f32_e32 v65, v65
	v_exp_f32_e32 v66, v66
	v_exp_f32_e32 v67, v67
	v_cvt_pk_bf16_f32 v70, v60, v61
	v_cvt_pk_bf16_f32 v71, v62, v63
	v_cvt_pk_bf16_f32 v72, v64, v65
	v_cvt_pk_bf16_f32 v73, v66, v67
	s_nop 1
	v_mfma_f32_32x32x16_bf16 v[20:35], v[78:81], v[70:73], v[20:35]
	s_waitcnt lgkmcnt(0)
	v_mfma_f32_32x32x16_bf16 v[4:19], v[82:85], v[70:73], v[4:19]
	v_add_f32_e64 v42, v42, -v132
	v_add_f32_e64 v43, v43, -v132
	v_add_f32_e64 v36, v36, -v132
	v_add_f32_e64 v37, v37, -v132
	v_add_f32_e64 v38, v38, -v132
	v_add_f32_e64 v39, v39, -v132
	v_sub_f32_e32 v40, v40, v132
	v_sub_f32_e32 v41, v41, v132
	v_exp_f32_e32 v78, v42
	v_exp_f32_e32 v79, v43
	v_sub_f32_e32 v42, v44, v132
	v_sub_f32_e32 v43, v45, v132
	v_exp_f32_e32 v36, v36
	v_exp_f32_e32 v37, v37
	v_exp_f32_e32 v38, v38
	v_exp_f32_e32 v39, v39
	v_exp_f32_e32 v40, v40
	v_exp_f32_e32 v41, v41
	v_exp_f32_e32 v80, v42
	v_exp_f32_e32 v81, v43
	v_sub_f32_e32 v42, v46, v132
	v_sub_f32_e32 v43, v47, v132
	v_cvt_pk_bf16_f32 v44, v40, v41
	v_exp_f32_e32 v82, v42
	v_exp_f32_e32 v83, v43
	v_sub_f32_e32 v42, v48, v132
	v_sub_f32_e32 v43, v49, v132
	ds_read2_b64 v[46:49], v69 offset0:72 offset1:74
	ds_read2_b64 v[70:73], v69 offset0:76 offset1:78
	v_exp_f32_e32 v84, v42
	v_exp_f32_e32 v85, v43
	v_sub_f32_e32 v42, v50, v132
	v_sub_f32_e32 v43, v51, v132
	v_cvt_pk_bf16_f32 v45, v78, v79
	v_exp_f32_e32 v50, v42
	v_exp_f32_e32 v51, v43
	v_cvt_pk_bf16_f32 v42, v36, v37
	v_cvt_pk_bf16_f32 v43, v38, v39
	s_waitcnt lgkmcnt(1)
	s_nop 0
	v_mfma_f32_32x32x16_bf16 v[20:35], v[46:49], v[42:45], v[20:35]
	ds_read2_b64 v[46:49], v3 offset0:72 offset1:74
	ds_read2_b64 v[74:77], v3 offset0:76 offset1:78
	s_waitcnt lgkmcnt(1)
	v_mfma_f32_32x32x16_bf16 v[4:19], v[46:49], v[42:45], v[4:19]
	v_cvt_pk_bf16_f32 v42, v80, v81
	v_cvt_pk_bf16_f32 v43, v82, v83
	v_cvt_pk_bf16_f32 v44, v84, v85
	v_cvt_pk_bf16_f32 v45, v50, v51
	s_nop 1
	v_mfma_f32_32x32x16_bf16 v[20:35], v[70:73], v[42:45], v[20:35]
	s_waitcnt lgkmcnt(0)
	v_mfma_f32_32x32x16_bf16 v[4:19], v[74:77], v[42:45], v[4:19]
	v_add_f32_e64 v42, v52, 0
	v_add_f32_e64 v43, v53, 0
	v_add_f32_e64 v42, v54, v42
	v_add_f32_e64 v43, v55, v43
	v_add_f32_e64 v42, v56, v42
	v_add_f32_e64 v43, v57, v43
	v_add_f32_e32 v42, v58, v42
	v_add_f32_e32 v43, v59, v43
	s_nop 0
	v_add_f32_e32 v42, v60, v42
	v_add_f32_e32 v43, v61, v43
	s_nop 0
	v_add_f32_e32 v42, v62, v42
	v_add_f32_e32 v43, v63, v43
	s_nop 0
	v_add_f32_e32 v42, v64, v42
	v_add_f32_e32 v43, v65, v43
	s_nop 0
	v_add_f32_e32 v42, v66, v42
	v_add_f32_e32 v43, v67, v43
	v_mov_b64_e32 v[66:67], v[18:19]
	v_add_f32_e32 v36, v36, v42
	v_add_f32_e32 v37, v37, v43
	v_mov_b64_e32 v[64:65], v[16:17]
	v_add_f32_e32 v36, v38, v36
	v_add_f32_e32 v37, v39, v37
	v_mov_b64_e32 v[62:63], v[14:15]
	v_add_f32_e32 v36, v40, v36
	v_add_f32_e32 v37, v41, v37
	v_mov_b64_e32 v[60:61], v[12:13]
	v_add_f32_e32 v36, v78, v36
	v_add_f32_e32 v37, v79, v37
	v_mov_b64_e32 v[58:59], v[10:11]
	v_add_f32_e32 v36, v80, v36
	v_add_f32_e32 v37, v81, v37
	v_mov_b64_e32 v[56:57], v[8:9]
	v_add_f32_e32 v36, v82, v36
	v_add_f32_e32 v37, v83, v37
	v_mov_b64_e32 v[54:55], v[6:7]
	v_add_f32_e32 v36, v84, v36
	v_add_f32_e32 v37, v85, v37
	v_mov_b64_e32 v[52:53], v[4:5]
	v_add_f32_e32 v36, v50, v36
	v_add_f32_e32 v37, v51, v37
	s_nop 0
	v_add_f32_e32 v3, v36, v37
	ds_bpermute_b32 v36, v179, v3
	s_waitcnt lgkmcnt(0)
	v_add_f32_e32 v3, v3, v36
	v_mov_b64_e32 v[50:51], v[34:35]
	v_fmac_f32_e32 v3, v217, v68
	v_mov_b64_e32 v[48:49], v[32:33]
	v_mov_b64_e32 v[46:47], v[30:31]
	v_mov_b64_e32 v[44:45], v[28:29]
	v_mov_b64_e32 v[42:43], v[26:27]
	v_mov_b64_e32 v[40:41], v[24:25]
	v_mov_b64_e32 v[38:39], v[22:23]
	v_mov_b64_e32 v[36:37], v[20:21]
	s_branch .LBB0_1464

.LBB0_1475:
	s_or_b64 exec, exec, s[8:9]
	v_mov_b32_e32 v61, 0
	v_mov_b32_e32 v74, 0
	v_mov_b32_e32 v75, 0
	v_mov_b32_e32 v64, 0
	v_mov_b32_e32 v65, 0
	v_mov_b32_e32 v62, 0
	v_mov_b32_e32 v63, 0
	v_mov_b32_e32 v72, 0
	v_mov_b32_e32 v73, 0
	v_mov_b32_e32 v70, 0
	v_mov_b32_e32 v71, 0
	v_mov_b32_e32 v68, 0
	v_mov_b32_e32 v69, 0
	v_mov_b32_e32 v66, 0
	v_mov_b32_e32 v67, 0
	s_and_saveexec_b64 s[8:9], s[44:45]
	s_cbranch_execz .LBB0_1477
	s_waitcnt vmcnt(3)
	v_lshlrev_b32_e32 v60, 16, v56
	v_and_b32_e32 v61, 0xffff0000, v56
	s_waitcnt vmcnt(2)
	v_lshlrev_b32_e32 v62, 16, v52
	v_and_b32_e32 v63, 0xffff0000, v52
	v_lshlrev_b32_e32 v56, 16, v57
	v_and_b32_e32 v57, 0xffff0000, v57
	v_lshlrev_b32_e32 v52, 16, v53
	v_and_b32_e32 v53, 0xffff0000, v53
	s_waitcnt vmcnt(1)
	v_lshlrev_b32_e32 v64, 16, v48
	v_and_b32_e32 v65, 0xffff0000, v48
	s_waitcnt vmcnt(0)
	v_lshlrev_b32_e32 v74, 16, v44
	v_and_b32_e32 v75, 0xffff0000, v44
	v_lshlrev_b32_e32 v48, 16, v49
	v_and_b32_e32 v49, 0xffff0000, v49
	v_lshlrev_b32_e32 v44, 16, v45
	v_and_b32_e32 v45, 0xffff0000, v45
	v_lshlrev_b32_e32 v66, 16, v58
	v_and_b32_e32 v67, 0xffff0000, v58
	v_lshlrev_b32_e32 v68, 16, v54
	v_and_b32_e32 v69, 0xffff0000, v54
	v_lshlrev_b32_e32 v76, 16, v50
	v_and_b32_e32 v77, 0xffff0000, v50
	v_lshlrev_b32_e32 v78, 16, v46
	v_and_b32_e32 v79, 0xffff0000, v46
	v_lshlrev_b32_e32 v58, 16, v59
	v_lshlrev_b32_e32 v54, 16, v55
	v_and_b32_e32 v59, 0xffff0000, v59
	v_and_b32_e32 v55, 0xffff0000, v55
	v_add_f32_e32 v52, v52, v56
	v_add_f32_e32 v53, v53, v57
	v_lshlrev_b32_e32 v50, 16, v51
	v_lshlrev_b32_e32 v46, 16, v47
	v_and_b32_e32 v51, 0xffff0000, v51
	v_and_b32_e32 v47, 0xffff0000, v47
	v_add_f32_e32 v60, v62, v60
	v_add_f32_e32 v61, v63, v61
	v_add_f32_e32 v56, v68, v66
	v_add_f32_e32 v57, v69, v67
	v_add_f32_e32 v54, v54, v58
	v_add_f32_e32 v55, v55, v59
	v_add_f32_e32 v70, v22, v52
	v_add_f32_e32 v71, v23, v53
	v_add_f32_e32 v52, v74, v64
	v_add_f32_e32 v53, v75, v65
	v_add_f32_e32 v44, v44, v48
	v_add_f32_e32 v45, v45, v49
	v_add_f32_e32 v48, v78, v76
	v_add_f32_e32 v49, v79, v77
	v_add_f32_e32 v46, v46, v50
	v_add_f32_e32 v47, v47, v51
	v_add_f32_e32 v66, v26, v54
	v_add_f32_e32 v67, v27, v55
	v_add_f32_e32 v68, v24, v56
	v_add_f32_e32 v69, v25, v57
	v_add_f32_e32 v72, v20, v60
	v_add_f32_e32 v73, v21, v61
	v_add_f32_e32 v62, v18, v46
	v_add_f32_e32 v63, v19, v47
	v_add_f32_e32 v64, v16, v48
	v_add_f32_e32 v65, v17, v49
	v_add_f32_e32 v74, v14, v44
	v_add_f32_e32 v75, v15, v45
	v_add_f32_e32 v60, v12, v52
	v_add_f32_e32 v61, v13, v53
.LBB0_1477:
	s_or_b64 exec, exec, s[8:9]
	s_waitcnt vmcnt(1)
	v_mul_f32_e32 v50, v73, v73
	v_fmac_f32_e32 v50, v72, v72
	v_mul_f32_e32 v48, v70, v70
	v_mul_f32_e32 v49, v71, v71
	s_waitcnt vmcnt(0)
	v_mul_f32_e32 v46, v68, v68
	v_mul_f32_e32 v47, v69, v69
	v_add_f32_e32 v48, v48, v50
	v_add_f32_e32 v48, v49, v48
	v_add_f32_e32 v46, v46, v48
	v_mul_f32_e32 v44, v66, v66
	v_mul_f32_e32 v45, v67, v67
	v_add_f32_e32 v46, v47, v46
	v_add_f32_e32 v44, v44, v46
	v_add_f32_e32 v44, v45, v44
	ds_bpermute_b32 v45, v189, v44
	v_cvt_pk_bf16_f32 v54, v60, s0
	v_cvt_pk_bf16_f32 v55, v61, s0
	s_waitcnt lgkmcnt(0)
	v_add_f32_e32 v44, v44, v45
	ds_bpermute_b32 v45, v190, v44
	s_waitcnt lgkmcnt(0)
	v_add_f32_e32 v44, v44, v45
	ds_bpermute_b32 v45, v191, v44
	s_waitcnt lgkmcnt(0)
	v_add_f32_e32 v44, v44, v45
	v_fmamk_f32 v44, v44, 0x3c800000, v237
	v_rsq_f32_e32 v44, v44
	s_nop 0
	v_mul_f32_e32 v46, v72, v44
	v_mul_f32_e32 v47, v73, v44
	v_mul_f32_e32 v48, v68, v44
	v_mul_f32_e32 v49, v69, v44
	v_mul_f32_e32 v50, v70, v44
	v_mul_f32_e32 v51, v71, v44
	v_mul_f32_e32 v45, v67, v44
	v_mul_f32_e32 v44, v66, v44
	v_mul_f32_e32 v46, v8, v46
	v_mul_f32_e32 v47, v9, v47
	v_mul_f32_e32 v48, v4, v48
	v_mul_f32_e32 v49, v5, v49
	v_mul_f32_e32 v50, v10, v50
	v_mul_f32_e32 v51, v11, v51
	v_mul_f32_e32 v52, v6, v44
	v_mul_f32_e32 v53, v7, v45
	v_cvt_pk_bf16_f32 v44, v46, v47
	v_cvt_pk_bf16_f32 v46, v48, v49
	v_cvt_pk_bf16_f32 v45, v50, v51
	v_cvt_pk_bf16_f32 v47, v52, v53
	ds_write_b128 v244, v[44:47]
	ds_write_b16 v245, v54 offset:18432
	ds_write_b16 v245, v55 offset:18704
	v_cvt_pk_bf16_f32 v44, v74, s0
	ds_write_b16 v245, v44 offset:18976
	v_cvt_pk_bf16_f32 v44, v75, s0
	ds_write_b16 v245, v44 offset:19248
	v_cvt_pk_bf16_f32 v44, v64, s0
	ds_write_b16 v245, v44 offset:19520
	v_cvt_pk_bf16_f32 v44, v65, s0
	ds_write_b16 v245, v44 offset:19792
	v_cvt_pk_bf16_f32 v44, v62, s0
	ds_write_b16 v245, v44 offset:20064
	v_cvt_pk_bf16_f32 v44, v63, s0
	ds_write_b16 v245, v44 offset:20336
	s_mov_b64 s[20:21], exec
	v_readlane_b32 s4, v253, 36
	v_readlane_b32 s5, v253, 37
	s_and_b64 s[4:5], s[20:21], s[4:5]
	s_mov_b64 exec, s[4:5]
	s_cbranch_execz .LBB0_1481
	v_mov_b32_e32 v58, 0
	v_mov_b32_e32 v59, 0
	v_mov_b32_e32 v56, 0
	v_mov_b32_e32 v57, 0
	v_mov_b32_e32 v46, 0
	v_mov_b32_e32 v47, 0
	v_mov_b32_e32 v44, 0
	v_mov_b32_e32 v45, 0
	v_mov_b32_e32 v54, 0
	v_mov_b32_e32 v55, 0
	v_mov_b32_e32 v52, 0
	v_mov_b32_e32 v53, 0
	v_mov_b32_e32 v50, 0
	v_mov_b32_e32 v51, 0
	v_mov_b32_e32 v48, 0
	v_mov_b32_e32 v49, 0
	s_mov_b64 s[8:9], exec
	v_readlane_b32 s4, v253, 43
	v_readlane_b32 s5, v253, 44
	s_and_b64 s[4:5], s[8:9], s[4:5]
	s_mov_b64 exec, s[4:5]
	s_cbranch_execz .LBB0_1480
	v_lshlrev_b32_e32 v44, 16, v40
	v_and_b32_e32 v45, 0xffff0000, v40
	v_lshlrev_b32_e32 v46, 16, v36
	v_and_b32_e32 v47, 0xffff0000, v36
	v_lshlrev_b32_e32 v40, 16, v41
	v_and_b32_e32 v41, 0xffff0000, v41
	v_lshlrev_b32_e32 v36, 16, v37
	v_and_b32_e32 v37, 0xffff0000, v37
	v_lshlrev_b32_e32 v48, 16, v42
	v_and_b32_e32 v49, 0xffff0000, v42
	v_lshlrev_b32_e32 v50, 16, v38
	v_and_b32_e32 v51, 0xffff0000, v38
	v_lshlrev_b32_e32 v42, 16, v43
	v_lshlrev_b32_e32 v38, 16, v39
	v_and_b32_e32 v43, 0xffff0000, v43
	v_and_b32_e32 v39, 0xffff0000, v39
	v_add_f32_e32 v44, v46, v44
	v_add_f32_e32 v45, v47, v45
	v_add_f32_e32 v36, v36, v40
	v_add_f32_e32 v37, v37, v41
	v_lshlrev_b32_e32 v56, 16, v32
	v_and_b32_e32 v57, 0xffff0000, v32
	v_lshlrev_b32_e32 v58, 16, v28
	v_and_b32_e32 v59, 0xffff0000, v28
	v_lshlrev_b32_e32 v32, 16, v33
	v_and_b32_e32 v33, 0xffff0000, v33
	v_lshlrev_b32_e32 v28, 16, v29
	v_and_b32_e32 v29, 0xffff0000, v29
	v_lshlrev_b32_e32 v60, 16, v34
	v_and_b32_e32 v61, 0xffff0000, v34
	v_lshlrev_b32_e32 v62, 16, v30
	v_and_b32_e32 v63, 0xffff0000, v30
	v_add_f32_e32 v40, v50, v48
	v_add_f32_e32 v41, v51, v49
	v_add_f32_e32 v38, v38, v42
	v_add_f32_e32 v39, v39, v43
	v_add_f32_e32 v52, v22, v36
	v_add_f32_e32 v53, v23, v37
	v_add_f32_e32 v54, v20, v44
	v_add_f32_e32 v55, v21, v45
	v_lshlrev_b32_e32 v20, 16, v35
	v_lshlrev_b32_e32 v22, 16, v31
	v_and_b32_e32 v21, 0xffff0000, v35
	v_and_b32_e32 v23, 0xffff0000, v31
	v_add_f32_e32 v48, v26, v38
	v_add_f32_e32 v49, v27, v39
	v_add_f32_e32 v50, v24, v40
	v_add_f32_e32 v51, v25, v41
	v_add_f32_e32 v24, v58, v56
	v_add_f32_e32 v25, v59, v57
	v_add_f32_e32 v26, v28, v32
	v_add_f32_e32 v27, v29, v33
	v_add_f32_e32 v28, v62, v60
	v_add_f32_e32 v29, v63, v61
	v_add_f32_e32 v20, v22, v20
	v_add_f32_e32 v21, v23, v21
	v_add_f32_e32 v46, v16, v28
	v_add_f32_e32 v47, v17, v29
	v_add_f32_e32 v44, v18, v20
	v_add_f32_e32 v45, v19, v21
	v_add_f32_e32 v56, v14, v26
	v_add_f32_e32 v57, v15, v27
	v_add_f32_e32 v58, v12, v24
	v_add_f32_e32 v59, v13, v25
.LBB0_1480:
	s_or_b64 exec, exec, s[8:9]
	v_mul_f32_e32 v18, v55, v55
	v_fmac_f32_e32 v18, v54, v54
	v_mul_f32_e32 v16, v52, v52
	v_mul_f32_e32 v17, v53, v53
	v_mul_f32_e32 v14, v50, v50
	v_mul_f32_e32 v15, v51, v51
	v_add_f32_e32 v16, v16, v18
	v_add_f32_e32 v16, v17, v16
	v_add_f32_e32 v14, v14, v16
	v_mul_f32_e32 v12, v48, v48
	v_mul_f32_e32 v13, v49, v49
	v_add_f32_e32 v14, v15, v14
	v_add_f32_e32 v12, v12, v14
	v_add_f32_e32 v12, v13, v12
	ds_bpermute_b32 v13, v189, v12
	v_cvt_pk_bf16_f32 v20, v58, s0
	v_cvt_pk_bf16_f32 v21, v59, s0
	s_waitcnt lgkmcnt(0)
	v_add_f32_e32 v12, v12, v13
	ds_bpermute_b32 v13, v190, v12
	s_waitcnt lgkmcnt(0)
	v_add_f32_e32 v12, v12, v13
	ds_bpermute_b32 v13, v191, v12
	s_waitcnt lgkmcnt(0)
	v_add_f32_e32 v12, v12, v13
	v_fmamk_f32 v12, v12, 0x3c800000, v237
	v_rsq_f32_e32 v12, v12
	s_nop 0
	v_mul_f32_e32 v14, v54, v12
	v_mul_f32_e32 v15, v55, v12
	v_mul_f32_e32 v16, v50, v12
	v_mul_f32_e32 v17, v51, v12
	v_mul_f32_e32 v18, v52, v12
	v_mul_f32_e32 v19, v53, v12
	v_mul_f32_e32 v13, v49, v12
	v_mul_f32_e32 v12, v48, v12
	v_mul_f32_e32 v8, v8, v14
	v_mul_f32_e32 v9, v9, v15
	v_mul_f32_e32 v14, v4, v16
	v_mul_f32_e32 v15, v5, v17
	v_mul_f32_e32 v10, v10, v18
	v_mul_f32_e32 v11, v11, v19
	v_mul_f32_e32 v12, v6, v12
	v_mul_f32_e32 v13, v7, v13
	v_cvt_pk_bf16_f32 v4, v8, v9
	v_cvt_pk_bf16_f32 v6, v14, v15
	v_cvt_pk_bf16_f32 v5, v10, v11
	v_cvt_pk_bf16_f32 v7, v12, v13
	ds_write_b128 v244, v[4:7] offset:9216
	ds_write_b16 v245, v20 offset:18560
	ds_write_b16 v245, v21 offset:18832
	v_cvt_pk_bf16_f32 v4, v56, s0
	ds_write_b16 v245, v4 offset:19104
	v_cvt_pk_bf16_f32 v4, v57, s0
	ds_write_b16 v245, v4 offset:19376
	v_cvt_pk_bf16_f32 v4, v46, s0
	ds_write_b16 v245, v4 offset:19648
	v_cvt_pk_bf16_f32 v4, v47, s0
	ds_write_b16 v245, v4 offset:19920
	v_cvt_pk_bf16_f32 v4, v44, s0
	ds_write_b16 v245, v4 offset:20192
	v_cvt_pk_bf16_f32 v4, v45, s0
	ds_write_b16 v245, v4 offset:20464
.LBB0_1481:
	s_or_b64 exec, exec, s[20:21]
	v_add_u32_e32 v4, 1, v3
	v_cvt_f32_ubyte0_e32 v4, v4
	v_mul_f32_e32 v4, -0.5, v4
	v_exp_f32_e32 v4, v4
	v_lshlrev_b32_e32 v165, 6, v3
	s_lshl_b32 s3, s3, 6
	s_waitcnt lgkmcnt(0)
	v_mul_f32_e32 v152, 0x3fb8aa3b, v4
	s_barrier
	s_mov_b64 s[20:21], exec
	v_readlane_b32 s4, v253, 40
	v_readlane_b32 s5, v253, 41
	s_and_b64 s[4:5], s[20:21], s[4:5]
	s_mov_b64 exec, s[4:5]
	s_cbranch_execz .LBB0_1486
	v_add_u32_e32 v50, v234, v192
	ds_read_b128 v[4:7], v50
	ds_read_b128 v[8:11], v50 offset:32
	v_add_u32_e32 v51, v234, v193
	v_xor_b32_e32 v173, 0x80000000, v152
	v_mul_f32_e32 v36, v152, v172
	v_mul_f32_e32 v37, v153, v173
	s_waitcnt lgkmcnt(1)
	v_mfma_f32_32x32x16_bf16 v[20:35], v[4:7], v[114:117], 0
	ds_read_b128 v[4:7], v50 offset:64
	v_fma_f32 v52, 0, v36, v37
	v_add_f32_e32 v53, v36, v37
	v_fma_f32 v54, 2.0, v36, v37
	v_fmamk_f32 v55, v36, 0x40400000, v37
	v_fmamk_f32 v56, v36, 0x41000000, v37
	v_fmamk_f32 v57, v36, 0x41100000, v37
	s_waitcnt lgkmcnt(1)
	v_mfma_f32_32x32x16_bf16 v[20:35], v[8:11], v[118:121], v[20:35]
	ds_read_b128 v[38:41], v50 offset:96
	ds_read_b128 v[8:11], v51
	ds_read_b128 v[42:45], v51 offset:32
	ds_read_b128 v[46:49], v51 offset:64
	v_fmamk_f32 v58, v36, 0x41200000, v37
	v_fmamk_f32 v59, v36, 0x41300000, v37
	v_fmamk_f32 v60, v36, 0x41800000, v37
	v_fmamk_f32 v61, v36, 0x41880000, v37
	s_waitcnt lgkmcnt(4)
	v_mfma_f32_32x32x16_bf16 v[20:35], v[4:7], v[122:125], v[20:35]
	v_fmamk_f32 v62, v36, 0x41900000, v37
	v_fmamk_f32 v63, v36, 0x41980000, v37
	v_fmamk_f32 v64, v36, 0x42400000, v37
	v_add_u32_e32 v107, 0x4800, v239
	v_add_u32_e32 v108, 0x4800, v240
	s_waitcnt lgkmcnt(2)
	v_mfma_f32_32x32x16_bf16 v[4:19], v[8:11], v[114:117], 0
	v_mfma_f32_32x32x16_bf16 v[20:35], v[38:41], v[126:129], v[20:35]
	s_waitcnt lgkmcnt(1)
	v_mfma_f32_32x32x16_bf16 v[4:19], v[42:45], v[118:121], v[4:19]
	s_nop 9
	v_add_f32_e32 v38, v52, v20
	v_add_f32_e32 v39, v53, v21
	v_add_f32_e32 v40, v54, v22
	v_add_f32_e32 v41, v55, v23
	v_max3_f32 v20, v38, s33, v39
	v_add_f32_e32 v52, v56, v24
	v_add_f32_e32 v53, v57, v25
	v_max3_f32 v20, v20, v40, v41
	v_add_f32_e32 v54, v58, v26
	v_add_f32_e32 v55, v59, v27
	v_max3_f32 v20, v20, v52, v53
	v_add_f32_e32 v56, v60, v28
	v_add_f32_e32 v57, v61, v29
	v_max3_f32 v20, v20, v54, v55
	v_add_f32_e32 v58, v62, v30
	v_add_f32_e32 v59, v63, v31
	v_max3_f32 v20, v20, v56, v57
	v_fmamk_f32 v21, v36, 0x41c00000, v37
	v_max3_f32 v24, v20, v58, v59
	v_fmamk_f32 v20, v36, 0x41c80000, v37
	v_add_f32_e32 v42, v21, v32
	v_add_f32_e32 v43, v20, v33
	ds_read_b128 v[20:23], v51 offset:96
	s_waitcnt lgkmcnt(1)
	v_mfma_f32_32x32x16_bf16 v[4:19], v[46:49], v[122:125], v[4:19]
	v_fmamk_f32 v25, v36, 0x41d00000, v37
	v_add_f32_e32 v44, v25, v34
	v_fmamk_f32 v25, v36, 0x41d80000, v37
	v_add_f32_e32 v45, v25, v35
	v_fmamk_f32 v25, v36, 0x42000000, v37
	v_max3_f32 v24, v24, v42, v43
	v_max3_f32 v24, v24, v44, v45
	s_waitcnt lgkmcnt(0)
	v_mfma_f32_32x32x16_bf16 v[4:19], v[20:23], v[126:129], v[4:19]
	s_nop 11
	v_add_f32_e32 v46, v25, v4
	v_fmamk_f32 v4, v36, 0x42040000, v37
	v_add_f32_e32 v47, v4, v5
	v_fmamk_f32 v5, v36, 0x42080000, v37
	v_add_f32_e32 v48, v5, v6
	v_fmamk_f32 v5, v36, 0x420c0000, v37
	v_max3_f32 v4, v24, v46, v47
	v_add_f32_e32 v49, v5, v7
	v_max3_f32 v20, v4, v48, v49
	v_fmamk_f32 v4, v36, 0x42200000, v37
	v_add_f32_e32 v51, v4, v8
	v_fmamk_f32 v4, v36, 0x42240000, v37
	v_add_f32_e32 v60, v4, v9
	ds_read_b128 v[4:7], v50 offset:9216
	v_fmamk_f32 v9, v36, 0x42280000, v37
	v_add_f32_e32 v61, v9, v10
	v_fmamk_f32 v9, v36, 0x422c0000, v37
	v_max3_f32 v8, v20, v51, v60
	v_add_f32_e32 v62, v9, v11
	v_max3_f32 v63, v8, v61, v62
	ds_read_b128 v[8:11], v50 offset:9248
	s_waitcnt lgkmcnt(1)
	v_mfma_f32_32x32x16_bf16 v[20:35], v[4:7], v[114:117], 0
	v_fmamk_f32 v4, v36, 0x42440000, v37
	v_add_f32_e32 v64, v64, v12
	v_add_f32_e32 v65, v4, v13
	v_fmamk_f32 v4, v36, 0x42480000, v37
	v_max3_f32 v12, v63, v64, v65
	v_add_f32_e32 v63, v4, v14
	ds_read_b128 v[4:7], v50 offset:9280
	s_waitcnt lgkmcnt(1)
	v_mfma_f32_32x32x16_bf16 v[20:35], v[8:11], v[118:121], v[20:35]
	v_fmamk_f32 v8, v36, 0x424c0000, v37
	v_add_f32_e32 v66, v8, v15
	v_fmamk_f32 v8, v36, 0x42600000, v37
	v_add_f32_e32 v67, v8, v16
	ds_read_b128 v[8:11], v50 offset:9312
	v_fmamk_f32 v13, v36, 0x42640000, v37
	v_max3_f32 v12, v12, v63, v66
	s_waitcnt lgkmcnt(1)
	v_mfma_f32_32x32x16_bf16 v[20:35], v[4:7], v[122:125], v[20:35]
	v_fmamk_f32 v5, v36, 0x42680000, v37
	v_add_f32_e32 v68, v5, v18
	v_fmamk_f32 v5, v36, 0x426c0000, v37
	v_add_f32_e32 v69, v5, v19
	v_fmamk_f32 v5, v36, 0x42800000, v37
	v_add_f32_e32 v50, v13, v17
	v_max3_f32 v4, v12, v67, v50
	s_waitcnt lgkmcnt(0)
	v_mfma_f32_32x32x16_bf16 v[20:35], v[8:11], v[126:129], v[20:35]
	v_max3_f32 v4, v4, v68, v69
	v_fmamk_f32 v9, v36, 0x42940000, v37
	s_nop 9
	v_add_f32_e32 v70, v5, v20
	v_fmamk_f32 v5, v36, 0x42820000, v37
	v_add_f32_e32 v71, v5, v21
	v_fmamk_f32 v5, v36, 0x42840000, v37
	v_add_f32_e32 v72, v5, v22
	v_fmamk_f32 v5, v36, 0x42860000, v37
	v_max3_f32 v4, v4, v70, v71
	v_add_f32_e32 v73, v5, v23
	v_max3_f32 v8, v4, v72, v73
	v_fmamk_f32 v4, v36, 0x42900000, v37
	v_add_f32_e32 v74, v4, v24
	v_fmamk_f32 v4, v36, 0x42920000, v37
	v_add_f32_e32 v75, v4, v25
	ds_read_b128 v[4:7], v238
	ds_read_b128 v[20:23], v238 offset:32
	v_add_f32_e32 v76, v9, v26
	v_fmamk_f32 v9, v36, 0x42960000, v37
	v_max3_f32 v8, v8, v74, v75
	v_add_f32_e32 v81, v9, v27
	v_max3_f32 v24, v8, v76, v81
	s_waitcnt lgkmcnt(1)
	v_mfma_f32_32x32x16_bf16 v[4:19], v[4:7], v[114:117], 0
	v_fmamk_f32 v25, v36, 0x42a00000, v37
	v_add_f32_e32 v82, v25, v28
	v_fmamk_f32 v25, v36, 0x42a20000, v37
	v_add_f32_e32 v83, v25, v29
	v_max3_f32 v28, v24, v82, v83
	v_fmamk_f32 v24, v36, 0x42a40000, v37
	v_add_f32_e32 v84, v24, v30
	ds_read_b128 v[24:27], v238 offset:64
	s_waitcnt lgkmcnt(1)
	v_mfma_f32_32x32x16_bf16 v[4:19], v[20:23], v[118:121], v[4:19]
	v_fmamk_f32 v20, v36, 0x42a60000, v37
	v_add_f32_e32 v85, v20, v31
	v_fmamk_f32 v20, v36, 0x42b00000, v37
	v_add_f32_e32 v86, v20, v32
	ds_read_b128 v[20:23], v238 offset:96
	v_fmamk_f32 v29, v36, 0x42b20000, v37
	v_max3_f32 v28, v28, v84, v85
	s_waitcnt lgkmcnt(1)
	v_mfma_f32_32x32x16_bf16 v[4:19], v[24:27], v[122:125], v[4:19]
	v_fmamk_f32 v25, v36, 0x42b40000, v37
	v_add_f32_e32 v87, v29, v33
	v_add_f32_e32 v88, v25, v34
	v_fmamk_f32 v25, v36, 0x42b60000, v37
	v_max3_f32 v24, v28, v86, v87
	v_add_f32_e32 v89, v25, v35
	v_max3_f32 v24, v24, v88, v89
	s_waitcnt lgkmcnt(0)
	v_mfma_f32_32x32x16_bf16 v[4:19], v[20:23], v[126:129], v[4:19]
	v_fmamk_f32 v20, v36, 0x42c00000, v37
	ds_read2_b64 v[28:31], v107 offset0:4 offset1:6
	s_nop 9
	v_add_f32_e32 v90, v20, v4
	v_fmamk_f32 v4, v36, 0x42c20000, v37
	v_add_f32_e32 v91, v4, v5
	v_fmamk_f32 v5, v36, 0x42c40000, v37
	v_add_f32_e32 v92, v5, v6
	v_fmamk_f32 v5, v36, 0x42c60000, v37
	v_add_f32_e32 v93, v5, v7
	v_fmamk_f32 v5, v36, 0x42d00000, v37
	v_add_f32_e32 v94, v5, v8
	v_fmamk_f32 v5, v36, 0x42d20000, v37
	v_add_f32_e32 v95, v5, v9
	v_fmamk_f32 v5, v36, 0x42d40000, v37
	v_add_f32_e32 v96, v5, v10
	v_fmamk_f32 v5, v36, 0x42d60000, v37
	v_add_f32_e32 v97, v5, v11
	v_fmamk_f32 v5, v36, 0x42e00000, v37
	v_add_f32_e32 v98, v5, v12
	v_fmamk_f32 v5, v36, 0x42e20000, v37
	v_max3_f32 v4, v24, v90, v91
	v_add_f32_e32 v99, v5, v13
	v_fmamk_f32 v5, v36, 0x42e40000, v37
	v_max3_f32 v4, v4, v92, v93
	v_add_f32_e32 v100, v5, v14
	v_fmamk_f32 v5, v36, 0x42e60000, v37
	v_max3_f32 v4, v4, v94, v95
	v_add_f32_e32 v101, v5, v15
	v_fmamk_f32 v5, v36, 0x42f00000, v37
	v_max3_f32 v4, v4, v96, v97
	v_add_f32_e32 v102, v5, v16
	v_fmamk_f32 v5, v36, 0x42f20000, v37
	v_max3_f32 v4, v4, v98, v99
	v_add_f32_e32 v103, v5, v17
	v_fmamk_f32 v5, v36, 0x42f40000, v37
	v_fmac_f32_e32 v37, 0x42f60000, v36
	v_max3_f32 v4, v4, v100, v101
	v_add_f32_e32 v104, v5, v18
	v_add_f32_e32 v5, v37, v19
	v_max3_f32 v4, v4, v102, v103
	v_cndmask_b32_e64 v105, v246, v5, s[12:13]
	v_max3_f32 v4, v4, v104, v105
	ds_bpermute_b32 v5, v194, v4
	s_waitcnt lgkmcnt(0)
	v_max3_f32 v106, v4, v5, s14
	v_sub_f32_e32 v4, v38, v106
	v_exp_f32_e32 v8, v4
	v_sub_f32_e32 v4, v39, v106
	v_exp_f32_e32 v9, v4
	v_sub_f32_e32 v4, v40, v106
	v_exp_f32_e32 v10, v4
	v_sub_f32_e32 v4, v41, v106
	v_exp_f32_e32 v11, v4
	v_sub_f32_e32 v4, v52, v106
	v_exp_f32_e32 v12, v4
	v_sub_f32_e32 v4, v53, v106
	v_exp_f32_e32 v13, v4
	v_sub_f32_e32 v4, v54, v106
	v_exp_f32_e32 v14, v4
	v_sub_f32_e32 v4, v55, v106
	v_exp_f32_e32 v15, v4
	v_sub_f32_e32 v4, v56, v106
	v_exp_f32_e32 v32, v4
	v_sub_f32_e32 v4, v57, v106
	v_exp_f32_e32 v33, v4
	v_sub_f32_e32 v4, v58, v106
	v_exp_f32_e32 v34, v4
	v_sub_f32_e32 v4, v59, v106
	v_exp_f32_e32 v35, v4
	v_sub_f32_e32 v4, v42, v106
	v_exp_f32_e32 v42, v4
	v_sub_f32_e32 v4, v43, v106
	v_exp_f32_e32 v43, v4
	v_sub_f32_e32 v4, v44, v106
	v_exp_f32_e32 v44, v4
	v_sub_f32_e32 v4, v45, v106
	v_exp_f32_e32 v45, v4
	v_mul_f32_e32 v4, 0.5, v11
	v_mul_f32_e32 v6, 0.5, v15
	ds_bpermute_b32 v4, v194, v4
	v_mul_f32_e32 v18, 0.5, v45
	ds_bpermute_b32 v52, v194, v18
	v_add_f32_e32 v18, 0, v8
	v_add_f32_e32 v18, v9, v18
	v_add_f32_e32 v18, v10, v18
	v_add_f32_e32 v18, v11, v18
	v_add_f32_e32 v18, v12, v18
	v_add_f32_e32 v18, v13, v18
	v_add_f32_e32 v18, v14, v18
	v_add_f32_e32 v18, v15, v18
	v_add_f32_e32 v18, v32, v18
	ds_bpermute_b32 v6, v194, v6
	v_mul_f32_e32 v16, 0.5, v35
	v_add_f32_e32 v18, v33, v18
	ds_bpermute_b32 v16, v194, v16
	v_add_f32_e32 v18, v34, v18
	v_add_f32_e32 v18, v35, v18
	v_add_f32_e32 v5, v8, v9
	v_add_f32_e32 v7, v12, v13
	v_add_f32_e32 v18, v42, v18
	v_add_f32_e32 v5, v10, v5
	v_add_f32_e32 v7, v14, v7
	v_add_f32_e32 v18, v43, v18
	v_fmac_f32_e32 v5, 0.5, v11
	v_fmac_f32_e32 v7, 0.5, v15
	v_add_f32_e32 v53, v44, v18
	s_waitcnt lgkmcnt(3)
	v_cndmask_b32_e64 v18, v4, 0, s[12:13]
	s_waitcnt lgkmcnt(1)
	v_cndmask_b32_e64 v4, v6, v4, s[12:13]
	v_add_f32_e32 v78, v18, v5
	v_add_f32_e32 v77, v4, v7
	s_waitcnt lgkmcnt(0)
	v_cndmask_b32_e64 v18, v16, v6, s[12:13]
	ds_read2_b64 v[4:7], v107 offset1:2
	v_add_f32_e32 v17, v32, v33
	v_add_f32_e32 v19, v42, v43
	v_add_f32_e32 v17, v34, v17
	v_add_f32_e32 v19, v44, v19
	v_fmac_f32_e32 v17, 0.5, v35
	v_fmac_f32_e32 v19, 0.5, v45
	v_cndmask_b32_e64 v16, v52, v16, s[12:13]
	v_cvt_pk_bf16_f32 v20, v8, v9
	v_cvt_pk_bf16_f32 v21, v10, v11
	v_cvt_pk_bf16_f32 v22, v12, v13
	v_cvt_pk_bf16_f32 v23, v14, v15
	v_add_f32_e32 v80, v18, v17
	v_add_f32_e32 v79, v16, v19
	s_waitcnt lgkmcnt(0)
	v_mfma_f32_32x32x16_bf16 v[4:19], v[4:7], v[20:23], 0
	v_cvt_pk_bf16_f32 v40, v32, v33
	v_cvt_pk_bf16_f32 v41, v34, v35
	v_cvt_pk_bf16_f32 v42, v42, v43
	v_cvt_pk_bf16_f32 v43, v44, v45
	ds_read2_b64 v[24:27], v108 offset1:2
	ds_read2_b64 v[36:39], v108 offset0:4 offset1:6
	v_mfma_f32_32x32x16_bf16 v[4:19], v[28:31], v[40:43], v[4:19]
	v_sub_f32_e32 v29, v46, v106
	v_exp_f32_e32 v32, v29
	v_sub_f32_e32 v29, v47, v106
	v_exp_f32_e32 v33, v29
	v_sub_f32_e32 v29, v48, v106
	v_exp_f32_e32 v34, v29
	v_sub_f32_e32 v29, v49, v106
	v_exp_f32_e32 v35, v29
	v_sub_f32_e32 v29, v51, v106
	v_exp_f32_e32 v46, v29
	v_sub_f32_e32 v29, v60, v106
	v_exp_f32_e32 v47, v29
	v_sub_f32_e32 v29, v61, v106
	v_add_f32_e32 v28, v45, v53
	v_exp_f32_e32 v48, v29
	v_sub_f32_e32 v29, v62, v106
	v_exp_f32_e32 v49, v29
	v_sub_f32_e32 v29, v64, v106
	v_add_f32_e32 v28, v32, v28
	v_exp_f32_e32 v51, v29
	v_sub_f32_e32 v29, v65, v106
	v_add_f32_e32 v28, v33, v28
	v_exp_f32_e32 v56, v29
	v_sub_f32_e32 v29, v63, v106
	v_add_f32_e32 v28, v34, v28
	v_exp_f32_e32 v57, v29
	v_sub_f32_e32 v29, v66, v106
	v_add_f32_e32 v28, v35, v28
	v_exp_f32_e32 v58, v29
	v_sub_f32_e32 v29, v67, v106
	v_add_f32_e32 v28, v46, v28
	v_exp_f32_e32 v59, v29
	v_sub_f32_e32 v29, v50, v106
	v_add_f32_e32 v28, v47, v28
	v_exp_f32_e32 v50, v29
	v_sub_f32_e32 v29, v68, v106
	v_add_f32_e32 v28, v48, v28
	v_exp_f32_e32 v60, v29
	v_sub_f32_e32 v29, v69, v106
	v_add_f32_e32 v28, v49, v28
	v_exp_f32_e32 v61, v29
	v_mul_f32_e32 v29, 0.5, v35
	v_add_f32_e32 v28, v51, v28
	ds_bpermute_b32 v29, v194, v29
	v_mul_f32_e32 v31, 0.5, v49
	v_add_f32_e32 v28, v56, v28
	ds_bpermute_b32 v45, v194, v31
	v_add_f32_e32 v28, v57, v28
	v_add_f32_e32 v28, v58, v28
	v_add_f32_e32 v30, v32, v33
	v_add_f32_e32 v28, v59, v28
	v_add_f32_e32 v30, v34, v30
	v_mul_f32_e32 v31, 0.5, v58
	v_add_f32_e32 v28, v50, v28
	v_fmac_f32_e32 v30, 0.5, v35
	ds_bpermute_b32 v54, v194, v31
	v_mul_f32_e32 v31, 0.5, v61
	v_add_f32_e32 v63, v60, v28
	s_waitcnt lgkmcnt(2)
	v_cndmask_b32_e64 v28, v29, v52, s[12:13]
	ds_bpermute_b32 v62, v194, v31
	v_add_f32_e32 v109, v28, v30
	s_waitcnt lgkmcnt(2)
	v_cndmask_b32_e64 v52, v45, v29, s[12:13]
	ds_read2_b64 v[28:31], v107 offset0:8 offset1:10
	v_add_f32_e32 v44, v46, v47
	v_add_f32_e32 v44, v48, v44
	v_add_f32_e32 v53, v51, v56
	v_fmac_f32_e32 v44, 0.5, v49
	v_add_f32_e32 v53, v57, v53
	v_fmac_f32_e32 v53, 0.5, v58
	v_add_f32_e32 v110, v52, v44
	s_waitcnt lgkmcnt(2)
	v_cndmask_b32_e64 v44, v54, v45, s[12:13]
	v_add_f32_e32 v111, v44, v53
	v_cvt_pk_bf16_f32 v44, v32, v33
	v_cvt_pk_bf16_f32 v45, v34, v35
	v_cvt_pk_bf16_f32 v46, v46, v47
	v_cvt_pk_bf16_f32 v47, v48, v49
	ds_read2_b64 v[32:35], v107 offset0:12 offset1:14
	v_add_f32_e32 v55, v59, v50
	s_waitcnt lgkmcnt(1)
	v_mfma_f32_32x32x16_bf16 v[4:19], v[28:31], v[44:47], v[4:19]
	v_cvt_pk_bf16_f32 v48, v51, v56
	v_cvt_pk_bf16_f32 v49, v57, v58
	v_cvt_pk_bf16_f32 v50, v59, v50
	v_cvt_pk_bf16_f32 v51, v60, v61
	v_sub_f32_e32 v29, v70, v106
	v_add_f32_e32 v55, v60, v55
	v_fmac_f32_e32 v55, 0.5, v61
	s_waitcnt lgkmcnt(0)
	v_mfma_f32_32x32x16_bf16 v[4:19], v[32:35], v[48:51], v[4:19]
	v_exp_f32_e32 v32, v29
	v_sub_f32_e32 v29, v71, v106
	v_exp_f32_e32 v33, v29
	v_sub_f32_e32 v29, v72, v106
	v_exp_f32_e32 v34, v29
	v_sub_f32_e32 v29, v73, v106
	v_cndmask_b32_e64 v28, v62, v54, s[12:13]
	v_exp_f32_e32 v35, v29
	v_sub_f32_e32 v29, v74, v106
	v_add_f32_e32 v112, v28, v55
	v_add_f32_e32 v28, v61, v63
	v_exp_f32_e32 v63, v29
	v_sub_f32_e32 v29, v75, v106
	v_exp_f32_e32 v64, v29
	v_sub_f32_e32 v29, v76, v106
	v_exp_f32_e32 v65, v29
	v_sub_f32_e32 v29, v81, v106
	v_exp_f32_e32 v66, v29
	v_sub_f32_e32 v29, v82, v106
	v_add_f32_e32 v28, v32, v28
	v_exp_f32_e32 v67, v29
	v_sub_f32_e32 v29, v83, v106
	v_add_f32_e32 v28, v33, v28
	v_exp_f32_e32 v72, v29
	v_sub_f32_e32 v29, v84, v106
	v_add_f32_e32 v28, v34, v28
	v_exp_f32_e32 v73, v29
	v_sub_f32_e32 v29, v85, v106
	v_add_f32_e32 v28, v35, v28
	v_exp_f32_e32 v74, v29
	v_sub_f32_e32 v29, v86, v106
	v_add_f32_e32 v28, v63, v28
	v_exp_f32_e32 v75, v29
	v_sub_f32_e32 v29, v87, v106
	v_add_f32_e32 v28, v64, v28
	v_exp_f32_e32 v76, v29
	v_sub_f32_e32 v29, v88, v106
	v_add_f32_e32 v28, v65, v28
	v_exp_f32_e32 v81, v29
	v_sub_f32_e32 v29, v89, v106
	v_add_f32_e32 v28, v66, v28
	v_exp_f32_e32 v82, v29
	v_mul_f32_e32 v29, 0.5, v35
	v_add_f32_e32 v28, v67, v28
	ds_bpermute_b32 v29, v194, v29
	v_mul_f32_e32 v31, 0.5, v66
	v_add_f32_e32 v28, v72, v28
	ds_bpermute_b32 v61, v194, v31
	v_add_f32_e32 v28, v73, v28
	v_add_f32_e32 v28, v74, v28
	v_add_f32_e32 v30, v32, v33
	v_add_f32_e32 v28, v75, v28
	v_add_f32_e32 v30, v34, v30
	v_mul_f32_e32 v31, 0.5, v74
	v_add_f32_e32 v28, v76, v28
	v_fmac_f32_e32 v30, 0.5, v35
	ds_bpermute_b32 v69, v194, v31
	v_mul_f32_e32 v31, 0.5, v82
	v_add_f32_e32 v84, v81, v28
	s_waitcnt lgkmcnt(2)
	v_cndmask_b32_e64 v28, v29, v62, s[12:13]
	ds_bpermute_b32 v83, v194, v31
	v_add_f32_e32 v113, v28, v30
	s_waitcnt lgkmcnt(2)
	v_cndmask_b32_e64 v62, v61, v29, s[12:13]
	ds_read2_b64 v[28:31], v107 offset0:16 offset1:18
	v_add_f32_e32 v60, v63, v64
	v_add_f32_e32 v60, v65, v60
	v_add_f32_e32 v68, v67, v72
	v_fmac_f32_e32 v60, 0.5, v66
	v_add_f32_e32 v68, v73, v68
	v_fmac_f32_e32 v68, 0.5, v74
	v_add_f32_e32 v130, v62, v60
	s_waitcnt lgkmcnt(2)
	v_cndmask_b32_e64 v60, v69, v61, s[12:13]
	v_add_f32_e32 v131, v60, v68
	v_cvt_pk_bf16_f32 v60, v32, v33
	v_cvt_pk_bf16_f32 v61, v34, v35
	v_cvt_pk_bf16_f32 v62, v63, v64
	v_cvt_pk_bf16_f32 v63, v65, v66
	ds_read2_b64 v[32:35], v107 offset0:20 offset1:22
	v_cvt_pk_bf16_f32 v64, v67, v72
	s_waitcnt lgkmcnt(1)
	v_mfma_f32_32x32x16_bf16 v[4:19], v[28:31], v[60:63], v[4:19]
	v_cvt_pk_bf16_f32 v65, v73, v74
	v_cvt_pk_bf16_f32 v66, v75, v76
	v_cvt_pk_bf16_f32 v67, v81, v82
	v_sub_f32_e32 v29, v90, v106
	v_add_f32_e32 v70, v75, v76
	v_add_f32_e32 v70, v81, v70
	v_fmac_f32_e32 v70, 0.5, v82
	s_waitcnt lgkmcnt(0)
	v_mfma_f32_32x32x16_bf16 v[4:19], v[32:35], v[64:67], v[4:19]
	v_exp_f32_e32 v32, v29
	v_sub_f32_e32 v29, v91, v106
	v_exp_f32_e32 v33, v29
	v_sub_f32_e32 v29, v92, v106
	v_exp_f32_e32 v34, v29
	v_sub_f32_e32 v29, v93, v106
	v_exp_f32_e32 v35, v29
	v_sub_f32_e32 v29, v94, v106
	v_exp_f32_e32 v76, v29
	v_sub_f32_e32 v29, v95, v106
	v_cndmask_b32_e64 v28, v83, v69, s[12:13]
	v_exp_f32_e32 v81, v29
	v_sub_f32_e32 v29, v96, v106
	v_add_f32_e32 v132, v28, v70
	v_add_f32_e32 v28, v82, v84
	v_exp_f32_e32 v82, v29
	v_sub_f32_e32 v29, v97, v106
	v_exp_f32_e32 v87, v29
	v_sub_f32_e32 v29, v98, v106
	v_add_f32_e32 v28, v32, v28
	v_exp_f32_e32 v92, v29
	v_sub_f32_e32 v29, v99, v106
	v_add_f32_e32 v28, v33, v28
	v_exp_f32_e32 v93, v29
	v_sub_f32_e32 v29, v100, v106
	v_add_f32_e32 v28, v34, v28
	v_exp_f32_e32 v94, v29
	v_sub_f32_e32 v29, v101, v106
	v_add_f32_e32 v28, v35, v28
	v_exp_f32_e32 v95, v29
	v_sub_f32_e32 v29, v102, v106
	v_add_f32_e32 v28, v76, v28
	v_exp_f32_e32 v96, v29
	v_sub_f32_e32 v29, v103, v106
	v_add_f32_e32 v28, v81, v28
	v_exp_f32_e32 v97, v29
	v_sub_f32_e32 v29, v104, v106
	v_add_f32_e32 v28, v82, v28
	v_exp_f32_e32 v98, v29
	v_sub_f32_e32 v29, v105, v106
	v_add_f32_e32 v28, v87, v28
	v_exp_f32_e32 v99, v29
	v_mul_f32_e32 v29, 0.5, v35
	v_add_f32_e32 v28, v92, v28
	ds_bpermute_b32 v29, v194, v29
	v_mul_f32_e32 v31, 0.5, v87
	v_add_f32_e32 v28, v93, v28
	ds_bpermute_b32 v85, v194, v31
	v_add_f32_e32 v28, v94, v28
	v_add_f32_e32 v28, v95, v28
	v_add_f32_e32 v30, v32, v33
	v_add_f32_e32 v28, v96, v28
	v_add_f32_e32 v30, v34, v30
	v_add_f32_e32 v84, v76, v81
	v_add_f32_e32 v28, v97, v28
	v_fmac_f32_e32 v30, 0.5, v35
	v_add_f32_e32 v84, v82, v84
	v_mul_f32_e32 v31, 0.5, v95
	v_add_f32_e32 v100, v98, v28
	s_waitcnt lgkmcnt(1)
	v_cndmask_b32_e64 v28, v29, v83, s[12:13]
	v_fmac_f32_e32 v84, 0.5, v87
	ds_bpermute_b32 v88, v194, v31
	v_mul_f32_e32 v31, 0.5, v99
	v_add_f32_e32 v101, v28, v30
	s_waitcnt lgkmcnt(1)
	v_cndmask_b32_e64 v28, v85, v29, s[12:13]
	ds_bpermute_b32 v90, v194, v31
	v_add_f32_e32 v102, v28, v84
	ds_read2_b64 v[28:31], v107 offset0:24 offset1:26
	v_add_f32_e32 v86, v92, v93
	v_cvt_pk_bf16_f32 v84, v32, v33
	v_add_f32_e32 v32, v99, v100
	v_add_f32_e32 v86, v94, v86
	ds_bpermute_b32 v33, v194, v32
	v_fmac_f32_e32 v86, 0.5, v95
	s_waitcnt lgkmcnt(3)
	v_cndmask_b32_e64 v83, v88, v85, s[12:13]
	v_add_f32_e32 v103, v83, v86
	v_cvt_pk_bf16_f32 v85, v34, v35
	v_cvt_pk_bf16_f32 v86, v76, v81
	v_cvt_pk_bf16_f32 v87, v82, v87
	s_waitcnt lgkmcnt(0)
	v_add_f32_e32 v32, v32, v33
	v_max_f32_e32 v32, 0xda24260, v32
	v_mfma_f32_32x32x16_bf16 v[4:19], v[28:31], v[84:87], v[4:19]
	ds_read2_b64 v[28:31], v107 offset0:28 offset1:30
	v_div_scale_f32 v33, s[4:5], v32, v32, 1.0
	v_rcp_f32_e32 v34, v33
	v_cvt_pk_bf16_f32 v92, v92, v93
	v_cvt_pk_bf16_f32 v93, v94, v95
	v_cvt_pk_bf16_f32 v94, v96, v97
	v_cvt_pk_bf16_f32 v95, v98, v99
	ds_read2_b64 v[52:55], v108 offset0:8 offset1:10
	ds_read2_b64 v[56:59], v108 offset0:12 offset1:14
	s_waitcnt lgkmcnt(2)
	v_mfma_f32_32x32x16_bf16 v[4:19], v[28:31], v[92:95], v[4:19]
	v_fma_f32 v28, -v33, v34, 1.0
	v_fmac_f32_e32 v34, v28, v34
	v_div_scale_f32 v28, vcc, 1.0, v32, 1.0
	v_mul_f32_e32 v29, v28, v34
	v_fma_f32 v30, -v33, v29, v28
	v_fmac_f32_e32 v29, v30, v34
	v_fma_f32 v28, -v33, v29, v28
	v_div_fmas_f32 v28, v28, v34, v29
	v_div_fixup_f32 v76, v28, v32, 1.0
	v_mul_f32_e32 v28, v78, v76
	ds_bpermute_b32 v81, v195, v28
	v_mfma_f32_32x32x16_bf16 v[20:35], v[24:27], v[20:23], 0
	ds_read2_b64 v[68:71], v108 offset0:16 offset1:18
	ds_read2_b64 v[72:75], v108 offset0:20 offset1:22
	v_add_f32_e32 v89, v96, v97
	v_add_f32_e32 v89, v98, v89
	v_fmac_f32_e32 v89, 0.5, v99
	v_cndmask_b32_e64 v83, v90, v88, s[12:13]
	v_add_f32_e32 v104, v89, v83
	v_mfma_f32_32x32x16_bf16 v[20:35], v[36:39], v[40:43], v[20:35]
	ds_read2_b64 v[88:91], v108 offset0:24 offset1:26
	ds_read2_b64 v[96:99], v108 offset0:28 offset1:30
	v_mul_f32_e32 v82, v77, v76
	v_mul_f32_e32 v83, v80, v76
	v_mul_f32_e32 v100, v79, v76
	v_mul_f32_e32 v105, v109, v76
	v_mul_f32_e32 v106, v110, v76
	s_waitcnt lgkmcnt(6)
	v_mfma_f32_32x32x16_bf16 v[20:35], v[52:55], v[44:47], v[20:35]
	v_mul_f32_e32 v107, v111, v76
	v_mul_f32_e32 v108, v112, v76
	v_mul_f32_e32 v133, v113, v76
	v_mul_f32_e32 v134, v130, v76
	v_mul_f32_e32 v135, v131, v76
	v_mul_f32_e32 v136, v132, v76
	v_mul_f32_e32 v137, v101, v76
	s_waitcnt lgkmcnt(5)
	v_mfma_f32_32x32x16_bf16 v[20:35], v[56:59], v[48:51], v[20:35]
	v_mul_f32_e32 v138, v102, v76
	v_mul_f32_e32 v139, v103, v76
	v_mul_f32_e32 v140, v104, v76
	ds_bpermute_b32 v82, v195, v82
	ds_bpermute_b32 v83, v195, v83
	ds_bpermute_b32 v37, v195, v100
	ds_bpermute_b32 v39, v195, v105
	s_waitcnt lgkmcnt(7)
	v_mfma_f32_32x32x16_bf16 v[20:35], v[68:71], v[60:63], v[20:35]
	ds_bpermute_b32 v40, v195, v106
	ds_bpermute_b32 v43, v195, v107
	ds_bpermute_b32 v45, v195, v108
	ds_bpermute_b32 v47, v195, v133
	ds_bpermute_b32 v49, v195, v134
	ds_bpermute_b32 v51, v195, v135
	ds_bpermute_b32 v53, v195, v136
	s_waitcnt lgkmcnt(13)
	v_mfma_f32_32x32x16_bf16 v[20:35], v[72:75], v[64:67], v[20:35]
	ds_bpermute_b32 v54, v195, v137
	ds_bpermute_b32 v58, v195, v138
	ds_bpermute_b32 v59, v195, v139
	ds_bpermute_b32 v61, v195, v140
	v_fmac_f32_e32 v81, v78, v76
	s_waitcnt lgkmcnt(14)
	v_fmac_f32_e32 v82, v77, v76
	s_waitcnt lgkmcnt(13)
	v_fmac_f32_e32 v83, v80, v76
	v_mfma_f32_32x32x16_bf16 v[20:35], v[88:91], v[84:87], v[20:35]
	s_waitcnt lgkmcnt(12)
	v_fmac_f32_e32 v37, v79, v76
	s_waitcnt lgkmcnt(11)
	v_fmac_f32_e32 v39, v109, v76
	s_waitcnt lgkmcnt(10)
	v_fmac_f32_e32 v40, v110, v76
	s_waitcnt lgkmcnt(9)
	v_fmac_f32_e32 v43, v111, v76
	s_waitcnt lgkmcnt(8)
	v_fmac_f32_e32 v45, v112, v76
	s_waitcnt lgkmcnt(7)
	v_fmac_f32_e32 v47, v113, v76
	s_waitcnt lgkmcnt(6)
	v_fmac_f32_e32 v49, v130, v76
	v_mfma_f32_32x32x16_bf16 v[20:35], v[96:99], v[92:95], v[20:35]
	s_waitcnt lgkmcnt(5)
	v_fmac_f32_e32 v51, v131, v76
	s_waitcnt lgkmcnt(4)
	v_fmac_f32_e32 v53, v132, v76
	s_waitcnt lgkmcnt(3)
	v_fmac_f32_e32 v54, v101, v76
	s_waitcnt lgkmcnt(2)
	v_fmac_f32_e32 v58, v102, v76
	s_waitcnt lgkmcnt(1)
	v_fmac_f32_e32 v59, v103, v76
	s_waitcnt lgkmcnt(0)
	v_fmac_f32_e32 v61, v104, v76
	ds_bpermute_b32 v78, v196, v81
	ds_bpermute_b32 v36, v196, v82
	ds_bpermute_b32 v38, v196, v83
	ds_bpermute_b32 v41, v196, v37
	ds_bpermute_b32 v42, v196, v39
	ds_bpermute_b32 v44, v196, v40
	ds_bpermute_b32 v46, v196, v43
	ds_bpermute_b32 v48, v196, v45
	ds_bpermute_b32 v50, v196, v47
	ds_bpermute_b32 v52, v196, v49
	ds_bpermute_b32 v55, v196, v51
	ds_bpermute_b32 v56, v196, v53
	ds_bpermute_b32 v57, v196, v54
	ds_bpermute_b32 v60, v196, v58
	ds_bpermute_b32 v62, v196, v59
	ds_bpermute_b32 v63, v196, v61
	s_mov_b64 s[8:9], exec
	v_readlane_b32 s4, v253, 55
	v_readlane_b32 s5, v253, 56
	s_and_b64 s[4:5], s[8:9], s[4:5]
	s_mov_b64 exec, s[4:5]
	s_cbranch_execz .LBB0_1484
	s_waitcnt lgkmcnt(12)
	v_add_f32_e32 v37, v37, v41
	v_add_f32_e32 v36, v82, v36
	v_add_f32_e32 v41, v81, v78
	s_waitcnt lgkmcnt(0)
	v_add_f32_e32 v61, v61, v63
	v_add_f32_e32 v59, v59, v62
	v_add_f32_e32 v58, v58, v60
	v_add_f32_e32 v54, v54, v57
	v_add_f32_e32 v53, v53, v56
	v_add_f32_e32 v51, v51, v55
	v_add_f32_e32 v49, v49, v52
	v_add_f32_e32 v47, v47, v50
	v_add_f32_e32 v45, v45, v48
	v_add_f32_e32 v43, v43, v46
	v_add_f32_e32 v40, v40, v44
	v_add_f32_e32 v39, v39, v42
	v_add_f32_e32 v38, v83, v38
	ds_write2_b32 v235, v41, v36 offset1:2
	ds_write2_b32 v235, v38, v37 offset0:4 offset1:6
	ds_write2_b32 v235, v39, v40 offset0:8 offset1:10
	ds_write2_b32 v235, v43, v45 offset0:12 offset1:14
	ds_write2_b32 v235, v47, v49 offset0:16 offset1:18
	ds_write2_b32 v235, v51, v53 offset0:20 offset1:22
	ds_write2_b32 v235, v54, v58 offset0:24 offset1:26
	ds_write2_b32 v235, v59, v61 offset0:28 offset1:30
.LBB0_1484:
	s_or_b64 exec, exec, s[8:9]
	v_readlane_b32 s4, v253, 57
	v_readlane_b32 s5, v253, 58
	s_and_b64 exec, exec, s[4:5]
	s_cbranch_execz .LBB0_1486
	v_mul_f32_e32 v4, v4, v76
	v_mul_f32_e32 v5, v5, v76
	v_mul_f32_e32 v20, v20, v76
	v_mul_f32_e32 v21, v21, v76
	ds_write2_b32 v236, v4, v5 offset1:32
	v_add_u32_e32 v4, 0x1000, v236
	v_mul_f32_e32 v8, v8, v76
	v_mul_f32_e32 v9, v9, v76
	v_mul_f32_e32 v6, v6, v76
	v_mul_f32_e32 v7, v7, v76
	v_mul_f32_e32 v24, v24, v76
	v_mul_f32_e32 v25, v25, v76
	v_mul_f32_e32 v22, v22, v76
	v_mul_f32_e32 v23, v23, v76
	ds_write2_b32 v4, v20, v21 offset1:32
	ds_write2_b32 v236, v6, v7 offset0:64 offset1:96
	ds_write2_b32 v4, v22, v23 offset0:64 offset1:96
	v_add_u32_e32 v4, 0x400, v236
	v_add_u32_e32 v5, 0x1400, v236
	v_mul_f32_e32 v12, v12, v76
	v_mul_f32_e32 v13, v13, v76
	v_mul_f32_e32 v10, v10, v76
	v_mul_f32_e32 v11, v11, v76
	v_mul_f32_e32 v28, v28, v76
	v_mul_f32_e32 v29, v29, v76
	v_mul_f32_e32 v26, v26, v76
	v_mul_f32_e32 v27, v27, v76
	ds_write2_b32 v4, v8, v9 offset1:32
	ds_write2_b32 v5, v24, v25 offset1:32
	ds_write2_b32 v4, v10, v11 offset0:64 offset1:96
	ds_write2_b32 v5, v26, v27 offset0:64 offset1:96
	v_add_u32_e32 v4, 0x800, v236
	v_add_u32_e32 v5, 0x1800, v236
	v_mul_f32_e32 v16, v16, v76
	v_mul_f32_e32 v17, v17, v76
	v_mul_f32_e32 v14, v14, v76
	v_mul_f32_e32 v15, v15, v76
	v_mul_f32_e32 v32, v32, v76
	v_mul_f32_e32 v33, v33, v76
	v_mul_f32_e32 v30, v30, v76
	v_mul_f32_e32 v31, v31, v76
	ds_write2_b32 v4, v12, v13 offset1:32
	ds_write2_b32 v5, v28, v29 offset1:32
	ds_write2_b32 v4, v14, v15 offset0:64 offset1:96
	ds_write2_b32 v5, v30, v31 offset0:64 offset1:96
	v_add_u32_e32 v4, 0xc00, v236
	v_add_u32_e32 v5, 0x1c00, v236
	v_mul_f32_e32 v18, v18, v76
	v_mul_f32_e32 v19, v19, v76
	v_mul_f32_e32 v34, v34, v76
	v_mul_f32_e32 v35, v35, v76
	ds_write2_b32 v4, v16, v17 offset1:32
	ds_write2_b32 v5, v32, v33 offset1:32
	ds_write2_b32 v4, v18, v19 offset0:64 offset1:96
	ds_write2_b32 v5, v34, v35 offset0:64 offset1:96

.LBB0_1490:
	s_or_b64 exec, exec, s[20:21]
	v_readlane_b32 s4, v255, 3
	v_readlane_b32 s5, v255, 4
	v_mul_u32_u24_e32 v3, 3, v3
	v_lshlrev_b32_e32 v6, 2, v3
	v_mov_b64_e32 v[4:5], s[4:5]
	s_movk_i32 s4, 0xc0
	v_mad_i64_i32 v[4:5], s[4:5], v174, s4, v[4:5]
	v_mov_b32_e32 v7, v2
	v_lshl_add_u64 v[176:177], v[4:5], 0, v[6:7]
	global_load_dword v4, v[176:177], off
	ds_bpermute_b32 v3, v195, v18
	s_mov_b32 s4, 0x80000001
	s_lshl_b64 s[8:9], s[16:17], 20
	s_lshl_b32 s6, s16, 4
	s_lshl_b64 s[10:11], s[16:17], 14
	s_waitcnt lgkmcnt(0)
	v_or_b32_e32 v3, v3, v18
	ds_bpermute_b32 v5, v196, v3
	ds_read2_b32 v[6:7], v224 offset1:32
	ds_read2_b32 v[8:9], v224 offset0:64 offset1:96
	v_readlane_b32 s5, v255, 7
	s_mov_b64 s[28:29], 1
	s_waitcnt lgkmcnt(2)
	v_or_b32_e32 v3, v3, v5
	ds_bpermute_b32 v5, v194, v3
	s_waitcnt lgkmcnt(0)
	v_or3_b32 v3, v5, v3, s4
	ds_bpermute_b32 v167, v201, v3
	v_readlane_b32 s4, v255, 5
	s_add_u32 s7, s4, s8
	v_readlane_b32 s4, v255, 6
	s_addc_u32 s4, s4, s9
	s_waitcnt lgkmcnt(0)
	ds_bpermute_b32 v3, v189, v167
	s_add_u32 s16, s80, s8
	s_addc_u32 s17, s81, s9
	s_add_u32 s20, s5, s10
	v_readlane_b32 s5, v255, 8
	s_waitcnt lgkmcnt(0)
	v_or_b32_e32 v3, v3, v167
	ds_bpermute_b32 v5, v190, v3
	s_addc_u32 s21, s5, s11
	s_mov_b64 s[8:9], -1
	s_waitcnt lgkmcnt(0)
	v_or_b32_e32 v3, v3, v5
	ds_bpermute_b32 v5, v191, v3
	s_waitcnt lgkmcnt(0)
	v_or_b32_e32 v3, v3, v5
	s_nop 0
	v_readfirstlane_b32 s5, v3
	s_waitcnt vmcnt(0)
	v_mul_f32_e32 v180, v4, v6
	v_mul_f32_e32 v181, v4, v7
	v_mul_f32_e32 v178, v4, v8
	v_mul_f32_e32 v179, v4, v9
	s_branch .LBB0_1492
.LBB0_1491:
	s_or_b64 exec, exec, s[8:9]
	v_lshl_add_u64 v[4:5], s[28:29], 2, v[176:177]
	s_waitcnt lgkmcnt(0)
	s_barrier
	global_load_dword v3, v[4:5], off
	ds_read2_b32 v[4:5], v229 offset1:32
	ds_read2_b32 v[6:7], v229 offset0:64 offset1:96
	ds_read2_b32 v[8:9], v229 offset0:128 offset1:160
	ds_read2_b32 v[10:11], v229 offset0:192 offset1:224
	ds_read2_b32 v[12:13], v231 offset1:32
	ds_read2_b32 v[14:15], v243 offset1:32
	ds_read2_b32 v[16:17], v243 offset0:64 offset1:96
	s_waitcnt lgkmcnt(6)
	v_max3_f32 v52, v4, s33, v5
	s_waitcnt lgkmcnt(5)
	v_max3_f32 v52, v52, v6, v7
	s_waitcnt lgkmcnt(4)
	v_max3_f32 v52, v52, v8, v9
	s_waitcnt lgkmcnt(3)
	v_max3_f32 v52, v52, v10, v11
	v_sub_f32_e32 v4, v4, v52
	v_sub_f32_e32 v5, v5, v52
	v_exp_f32_e32 v4, v4
	v_exp_f32_e32 v5, v5
	ds_read2_b32 v[18:19], v231 offset0:64 offset1:96
	v_sub_f32_e32 v6, v6, v52
	v_sub_f32_e32 v7, v7, v52
	v_exp_f32_e32 v6, v6
	v_exp_f32_e32 v7, v7
	ds_read2_b32 v[20:21], v231 offset0:128 offset1:160
	v_sub_f32_e32 v8, v8, v52
	v_sub_f32_e32 v9, v9, v52
	v_exp_f32_e32 v8, v8
	v_exp_f32_e32 v9, v9
	s_waitcnt lgkmcnt(4)
	v_mul_f32_e32 v12, v12, v4
	v_mul_f32_e32 v13, v13, v5
	ds_read_b32 v22, v232
	ds_read_b32 v23, v233
	v_sub_f32_e32 v10, v10, v52
	v_sub_f32_e32 v11, v11, v52
	s_waitcnt lgkmcnt(5)
	v_fma_f32 v14, v14, v4, 0
	v_fma_f32 v15, v15, v4, 0
	v_mov_b32_e32 v52, v5
	v_add_f32_e32 v5, 0, v12
	v_exp_f32_e32 v10, v10
	v_exp_f32_e32 v11, v11
	s_waitcnt lgkmcnt(3)
	v_mul_f32_e32 v18, v6, v18
	v_mul_f32_e32 v19, v7, v19
	v_add_f32_e32 v5, v5, v13
	v_add_f32_e32 v5, v5, v18
	s_waitcnt lgkmcnt(2)
	v_mul_f32_e32 v20, v8, v20
	v_mul_f32_e32 v21, v9, v21
	v_add_f32_e32 v5, v5, v19
	v_add_f32_e32 v5, v5, v20
	s_waitcnt lgkmcnt(0)
	v_mul_f32_e32 v22, v22, v10
	v_mul_f32_e32 v23, v23, v11
	v_add_f32_e32 v5, v5, v21
	v_add_u32_e32 v26, 0x2000, v243
	v_add_u32_e32 v30, 0x4000, v243
	v_add_u32_e32 v34, 0x6000, v243
	v_add_u32_e32 v38, 0x8000, v243
	v_add_u32_e32 v42, 0xa000, v243
	v_add_u32_e32 v46, 0xc000, v243
	v_add_u32_e32 v50, 0xe000, v243
	v_add_f32_e32 v5, v5, v22
	ds_read2_b32 v[24:25], v26 offset1:32
	ds_read2_b32 v[26:27], v26 offset0:64 offset1:96
	ds_read2_b32 v[28:29], v30 offset1:32
	ds_read2_b32 v[30:31], v30 offset0:64 offset1:96
	ds_read2_b32 v[32:33], v34 offset1:32
	ds_read2_b32 v[34:35], v34 offset0:64 offset1:96
	ds_read2_b32 v[36:37], v38 offset1:32
	ds_read2_b32 v[38:39], v38 offset0:64 offset1:96
	ds_read2_b32 v[40:41], v42 offset1:32
	ds_read2_b32 v[42:43], v42 offset0:64 offset1:96
	ds_read2_b32 v[44:45], v46 offset1:32
	ds_read2_b32 v[46:47], v46 offset0:64 offset1:96
	ds_read2_b32 v[48:49], v50 offset1:32
	ds_read2_b32 v[50:51], v50 offset0:64 offset1:96
	s_waitcnt lgkmcnt(13)
	v_fma_f32 v14, v52, v24, v14
	v_fma_f32 v15, v52, v25, v15
	v_add_f32_e32 v5, v5, v23
	v_mov_b32_e32 v54, v7
	s_waitcnt lgkmcnt(11)
	v_fma_f32 v12, v6, v28, v14
	v_fma_f32 v13, v6, v29, v15
	v_max_f32_e32 v5, 0xda24260, v5
	s_waitcnt lgkmcnt(9)
	v_fma_f32 v12, v54, v32, v12
	v_fma_f32 v13, v54, v33, v13
	v_mov_b32_e32 v56, v9
	s_waitcnt lgkmcnt(7)
	v_fma_f32 v12, v8, v36, v12
	v_fma_f32 v13, v8, v37, v13
	s_waitcnt lgkmcnt(5)
	v_fma_f32 v12, v56, v40, v12
	v_fma_f32 v13, v56, v41, v13
	s_waitcnt lgkmcnt(3)
	v_fma_f32 v12, v10, v44, v12
	v_fma_f32 v13, v10, v45, v13
	s_mov_b64 s[28:29], 2
	s_waitcnt lgkmcnt(0)
	s_barrier
	s_waitcnt vmcnt(0)
	v_div_scale_f32 v7, s[8:9], v5, v5, v3
	v_rcp_f32_e32 v9, v7
	v_div_scale_f32 v14, vcc, v3, v5, v3
	s_mov_b64 s[8:9], 0
	v_fma_f32 v15, -v7, v9, 1.0
	v_fmac_f32_e32 v9, v15, v9
	v_mul_f32_e32 v15, v14, v9
	v_fma_f32 v18, -v7, v15, v14
	v_fmac_f32_e32 v15, v18, v9
	v_fma_f32 v7, -v7, v15, v14
	v_div_fmas_f32 v7, v7, v9, v15
	v_div_fixup_f32 v14, v7, v5, v3
	v_fma_f32 v5, v4, v17, 0
	v_fma_f32 v4, v4, v16, 0
	v_fma_f32 v4, v52, v26, v4
	v_fma_f32 v5, v52, v27, v5
	v_fma_f32 v4, v6, v30, v4
	v_fma_f32 v5, v6, v31, v5
	v_fma_f32 v4, v54, v34, v4
	v_fma_f32 v5, v54, v35, v5
	v_fma_f32 v4, v8, v38, v4
	v_fma_f32 v5, v8, v39, v5
	v_fma_f32 v4, v56, v42, v4
	v_fma_f32 v5, v56, v43, v5
	v_mov_b32_e32 v18, v11
	v_fma_f32 v4, v10, v46, v4
	v_fma_f32 v5, v10, v47, v5
	v_fma_f32 v12, v18, v48, v12
	v_fma_f32 v13, v18, v49, v13
	v_fma_f32 v4, v18, v50, v4
	v_fma_f32 v5, v18, v51, v5
	v_fma_f32 v180, v12, v14, v180
	v_fma_f32 v181, v13, v14, v181
	v_fma_f32 v178, v4, v14, v178
	v_fma_f32 v179, v5, v14, v179
	s_andn2_b64 vcc, exec, s[24:25]
	s_cbranch_vccz .LBB0_1470

.LBB0_1493:
	v_sub_f32_e32 v8, v66, v4
	v_sub_f32_e32 v9, v67, v4
	v_sub_f32_e32 v10, v68, v4
	v_sub_f32_e32 v11, v69, v4
	v_sub_f32_e32 v12, v70, v4
	v_sub_f32_e32 v13, v71, v4
	v_sub_f32_e32 v14, v72, v4
	v_sub_f32_e32 v15, v73, v4
	v_add_u32_e32 v3, v226, v220
	v_exp_f32_e32 v8, v8
	v_exp_f32_e32 v9, v9
	v_exp_f32_e32 v10, v10
	v_exp_f32_e32 v11, v11
	v_exp_f32_e32 v12, v12
	v_exp_f32_e32 v13, v13
	v_exp_f32_e32 v14, v14
	v_exp_f32_e32 v15, v15
	v_add_u32_e32 v3, 0x2000, v3
	v_sub_f32_e32 v66, v76, v4
	v_sub_f32_e32 v67, v77, v4
	v_sub_f32_e32 v68, v78, v4
	v_sub_f32_e32 v69, v79, v4
	v_sub_f32_e32 v70, v80, v4
	v_sub_f32_e32 v71, v81, v4
	ds_read2_b64 v[76:79], v3 offset0:128 offset1:130
	ds_read2_b64 v[80:83], v3 offset0:132 offset1:134
	v_sub_f32_e32 v16, v74, v4
	v_sub_f32_e32 v17, v75, v4
	v_add_u32_e32 v5, v226, v221
	v_cvt_pk_bf16_f32 v72, v8, v9
	v_cvt_pk_bf16_f32 v73, v10, v11
	v_cvt_pk_bf16_f32 v74, v12, v13
	v_cvt_pk_bf16_f32 v75, v14, v15
	v_add_u32_e32 v5, 0x2000, v5
	v_exp_f32_e32 v16, v16
	s_waitcnt lgkmcnt(1)
	v_mfma_f32_32x32x16_bf16 v[34:49], v[76:79], v[72:75], v[34:49]
	ds_read2_b64 v[76:79], v5 offset0:128 offset1:130
	ds_read2_b64 v[84:87], v5 offset0:132 offset1:134
	v_exp_f32_e32 v17, v17
	v_exp_f32_e32 v66, v66
	v_exp_f32_e32 v67, v67
	v_exp_f32_e32 v68, v68
	v_exp_f32_e32 v69, v69
	v_exp_f32_e32 v70, v70
	s_waitcnt lgkmcnt(1)
	v_mfma_f32_32x32x16_bf16 v[18:33], v[76:79], v[72:75], v[18:33]
	v_exp_f32_e32 v71, v71
	v_cvt_pk_bf16_f32 v72, v16, v17
	v_cvt_pk_bf16_f32 v73, v66, v67
	v_cvt_pk_bf16_f32 v74, v68, v69
	v_cvt_pk_bf16_f32 v75, v70, v71
	s_nop 1
	v_mfma_f32_32x32x16_bf16 v[34:49], v[80:83], v[72:75], v[34:49]
	s_waitcnt lgkmcnt(0)
	v_mfma_f32_32x32x16_bf16 v[18:33], v[84:87], v[72:75], v[18:33]
	v_add_f32_e64 v56, v56, -v4
	v_add_f32_e64 v57, v57, -v4
	v_add_f32_e64 v50, v50, -v4
	v_add_f32_e64 v51, v51, -v4
	v_add_f32_e64 v52, v52, -v4
	v_add_f32_e64 v53, v53, -v4
	v_sub_f32_e32 v54, v54, v4
	v_sub_f32_e32 v55, v55, v4
	v_exp_f32_e32 v80, v56
	v_exp_f32_e32 v81, v57
	v_sub_f32_e32 v56, v58, v4
	v_sub_f32_e32 v57, v59, v4
	v_exp_f32_e32 v50, v50
	v_exp_f32_e32 v51, v51
	v_exp_f32_e32 v52, v52
	v_exp_f32_e32 v53, v53
	v_exp_f32_e32 v54, v54
	v_exp_f32_e32 v55, v55
	v_exp_f32_e32 v82, v56
	v_exp_f32_e32 v83, v57
	v_sub_f32_e32 v56, v60, v4
	v_sub_f32_e32 v57, v61, v4
	v_cvt_pk_bf16_f32 v58, v54, v55
	v_exp_f32_e32 v84, v56
	v_exp_f32_e32 v85, v57
	v_sub_f32_e32 v56, v62, v4
	v_sub_f32_e32 v57, v63, v4
	ds_read2_b64 v[60:63], v3 offset0:136 offset1:138
	ds_read2_b64 v[72:75], v3 offset0:140 offset1:142
	v_exp_f32_e32 v86, v56
	v_exp_f32_e32 v87, v57
	v_sub_f32_e32 v56, v64, v4
	v_sub_f32_e32 v57, v65, v4
	v_cvt_pk_bf16_f32 v59, v80, v81
	v_exp_f32_e32 v64, v56
	v_exp_f32_e32 v65, v57
	v_cvt_pk_bf16_f32 v56, v50, v51
	v_cvt_pk_bf16_f32 v57, v52, v53
	v_add_f32_e32 v8, 0, v8
	v_add_f32_e32 v9, 0, v9
	s_waitcnt lgkmcnt(1)
	v_mfma_f32_32x32x16_bf16 v[34:49], v[60:63], v[56:59], v[34:49]
	ds_read2_b64 v[60:63], v5 offset0:136 offset1:138
	ds_read2_b64 v[76:79], v5 offset0:140 offset1:142
	v_add_f32_e64 v8, v10, v8
	v_add_f32_e64 v9, v11, v9
	v_add_f32_e64 v8, v12, v8
	v_add_f32_e64 v9, v13, v9
	v_add_f32_e32 v8, v14, v8
	v_add_f32_e32 v9, v15, v9
	s_waitcnt lgkmcnt(1)
	v_mfma_f32_32x32x16_bf16 v[18:33], v[60:63], v[56:59], v[18:33]
	v_add_f32_e64 v8, v16, v8
	v_add_f32_e64 v9, v17, v9
	v_cvt_pk_bf16_f32 v56, v82, v83
	v_add_f32_e64 v8, v66, v8
	v_add_f32_e64 v9, v67, v9
	v_cvt_pk_bf16_f32 v57, v84, v85
	v_add_f32_e32 v8, v68, v8
	v_add_f32_e32 v9, v69, v9
	v_cvt_pk_bf16_f32 v58, v86, v87
	v_add_f32_e32 v8, v70, v8
	v_add_f32_e32 v9, v71, v9
	v_cvt_pk_bf16_f32 v59, v64, v65
	v_add_f32_e32 v8, v50, v8
	v_add_f32_e32 v9, v51, v9
	s_nop 0
	v_add_f32_e32 v8, v52, v8
	v_add_f32_e32 v9, v53, v9
	v_mfma_f32_32x32x16_bf16 v[34:49], v[72:75], v[56:59], v[34:49]
	v_add_f32_e64 v8, v54, v8
	v_add_f32_e64 v9, v55, v9
	v_add_f32_e64 v8, v80, v8
	v_add_f32_e64 v9, v81, v9
	v_add_f32_e64 v8, v82, v8
	v_add_f32_e64 v9, v83, v9
	v_add_f32_e32 v8, v84, v8
	v_add_f32_e32 v9, v85, v9
	s_waitcnt lgkmcnt(0)
	v_mfma_f32_32x32x16_bf16 v[18:33], v[76:79], v[56:59], v[18:33]
	v_add_f32_e64 v8, v86, v8
	v_add_f32_e64 v9, v87, v9
	v_add_f32_e64 v8, v64, v8
	v_add_f32_e64 v9, v65, v9
	v_mov_b64_e32 v[64:65], v[48:49]
	v_add_f32_e32 v3, v8, v9
	ds_bpermute_b32 v10, v194, v3
	v_mov_b64_e32 v[62:63], v[46:47]
	s_nop 3
	v_mov_b64_e32 v[80:81], v[32:33]
	v_mov_b64_e32 v[60:61], v[44:45]
	v_mov_b64_e32 v[58:59], v[42:43]
	v_mov_b64_e32 v[56:57], v[40:41]
	v_mov_b64_e32 v[54:55], v[38:39]
	v_mov_b64_e32 v[52:53], v[36:37]
	v_mov_b64_e32 v[50:51], v[34:35]
	v_mov_b64_e32 v[78:79], v[30:31]
	v_mov_b64_e32 v[76:77], v[28:29]
	v_mov_b64_e32 v[74:75], v[26:27]
	v_mov_b64_e32 v[72:73], v[24:25]
	v_mov_b64_e32 v[70:71], v[22:23]
	v_mov_b64_e32 v[68:69], v[20:21]
	v_mov_b64_e32 v[66:67], v[18:19]

.LBB0_1576:
	s_or_b64 exec, exec, s[8:9]
	v_cvt_pk_bf16_f32 v3, v70, v74
	v_cvt_pk_bf16_f32 v16, v71, v75
	v_cvt_pk_bf16_f32 v17, v72, v76
	v_cvt_pk_bf16_f32 v71, v82, v78
	v_add_u32_e32 v72, 0x2400, v242
	ds_write2_b32 v72, v3, v71 offset1:4
	v_cvt_pk_bf16_f32 v3, v83, v79
	ds_write2_b32 v72, v16, v3 offset0:34 offset1:38
	v_cvt_pk_bf16_f32 v3, v84, v80
	v_cvt_pk_bf16_f32 v70, v73, v77
	ds_write2_b32 v72, v17, v3 offset0:68 offset1:72
	v_cvt_pk_bf16_f32 v3, v85, v81
	ds_write2_b32 v72, v70, v3 offset0:102 offset1:106
	v_cvt_pk_bf16_f32 v3, v98, v94
	v_cvt_pk_bf16_f32 v71, v130, v110
	v_cvt_pk_bf16_f32 v16, v99, v95
	ds_write2_b32 v72, v3, v71 offset0:8 offset1:12
	v_cvt_pk_bf16_f32 v3, v131, v111
	v_cvt_pk_bf16_f32 v17, v100, v96
	ds_write2_b32 v72, v16, v3 offset0:42 offset1:46
	v_cvt_pk_bf16_f32 v3, v132, v112
	v_cvt_pk_bf16_f32 v70, v101, v97
	ds_write2_b32 v72, v17, v3 offset0:76 offset1:80
	v_cvt_pk_bf16_f32 v3, v133, v113
	ds_write2_b32 v72, v70, v3 offset0:110 offset1:114
	s_waitcnt vmcnt(0) lgkmcnt(0)
	v_cvt_pk_bf16_f32 v3, v8, v4
	v_cvt_pk_bf16_f32 v4, v9, v5
	v_cvt_pk_bf16_f32 v5, v10, v6
	v_cvt_pk_bf16_f32 v6, v11, v7
	v_cvt_pk_bf16_f32 v7, v50, v12
	ds_write2_b32 v72, v3, v7 offset0:16 offset1:20
	v_cvt_pk_bf16_f32 v3, v51, v13
	ds_write2_b32 v72, v4, v3 offset0:50 offset1:54
	v_cvt_pk_bf16_f32 v3, v52, v14
	ds_write2_b32 v72, v5, v3 offset0:84 offset1:88
	v_cvt_pk_bf16_f32 v3, v53, v15
	ds_write2_b32 v72, v6, v3 offset0:118 offset1:122
	v_cvt_pk_bf16_f32 v3, v58, v54
	v_cvt_pk_bf16_f32 v7, v66, v62
	v_cvt_pk_bf16_f32 v4, v59, v55
	ds_write2_b32 v72, v3, v7 offset0:24 offset1:28
	v_cvt_pk_bf16_f32 v3, v67, v63
	v_cvt_pk_bf16_f32 v5, v60, v56
	ds_write2_b32 v72, v4, v3 offset0:58 offset1:62
	v_cvt_pk_bf16_f32 v3, v68, v64
	v_cvt_pk_bf16_f32 v6, v61, v57
	ds_write2_b32 v72, v5, v3 offset0:92 offset1:96
	v_cvt_pk_bf16_f32 v3, v69, v65
	v_sub_u32_e32 v5, v169, v219
	ds_write2_b32 v72, v6, v3 offset0:126 offset1:130
	v_cvt_f32_i32_e32 v7, v5
	s_waitcnt lgkmcnt(0)
	s_andn2_b64 vcc, exec, s[24:25]
	s_mov_b64 s[8:9], -1
	s_cbranch_vccnz .LBB0_1586
	v_add_u32_e32 v3, -1, v173
	v_cmp_lt_u32_e32 vcc, 6, v3
	s_and_saveexec_b64 s[8:9], vcc
	s_xor_b64 s[42:43], exec, s[8:9]
	s_cbranch_execz .LBB0_1581
	v_mov_b32_e32 v3, v152
	v_add_u32_e32 v16, v225, v192
	v_mul_f32_e64 v4, v7, -v3
	v_cndmask_b32_e64 v4, v246, v4, s[50:51]
	v_mov_b32_e32 v6, v3
	v_fma_f32 v8, 0, v3, v4
	v_add_f32_e32 v50, v2, v8
	v_add_f32_e32 v51, v3, v8
	v_fma_f32 v52, v6, s0, v8
	v_fma_f32 v53, v6, s1, v8
	ds_read_b128 v[8:11], v16
	v_fmamk_f32 v12, v3, 0x41000000, v4
	v_add_f32_e32 v54, v2, v12
	v_add_f32_e32 v55, v3, v12
	v_fma_f32 v56, v6, s0, v12
	v_fma_f32 v57, v6, s1, v12
	v_fmamk_f32 v12, v3, 0x41800000, v4
	v_add_f32_e32 v58, v2, v12
	v_add_f32_e32 v59, v3, v12
	v_fma_f32 v60, v6, s0, v12
	v_fma_f32 v61, v6, s1, v12
	v_fmamk_f32 v12, v3, 0x41c00000, v4
	v_add_f32_e32 v62, v2, v12
	v_add_f32_e32 v63, v3, v12
	v_fma_f32 v64, v6, s0, v12
	v_fma_f32 v65, v6, s1, v12
	ds_read_b128 v[12:15], v16 offset:32
	v_add_u32_e32 v17, v225, v193
	s_waitcnt lgkmcnt(1)
	v_mfma_f32_32x32x16_bf16 v[50:65], v[8:11], v[114:117], v[50:65]
	ds_read_b128 v[8:11], v16 offset:64
	v_fmamk_f32 v72, v3, 0x42200000, v4
	v_fmamk_f32 v76, v3, 0x42400000, v4
	v_add_f32_e64 v70, v2, v72
	v_add_f32_e64 v71, v3, v72
	v_fma_f32 v73, v6, s1, v72
	v_fma_f32 v72, v6, s0, v72
	v_add_f32_e32 v74, v2, v76
	v_add_f32_e32 v75, v3, v76
	v_fma_f32 v77, v6, s1, v76
	v_fma_f32 v76, v6, s0, v76
	s_waitcnt lgkmcnt(1)
	v_mfma_f32_32x32x16_bf16 v[50:65], v[12:15], v[118:121], v[50:65]
	ds_read_b128 v[12:15], v16 offset:96
	v_fmamk_f32 v16, v3, 0x42000000, v4
	v_fmac_f32_e32 v4, 0x42600000, v3
	v_add_f32_e64 v66, v2, v16
	v_add_f32_e64 v67, v3, v16
	v_fma_f32 v68, v6, s0, v16
	v_fma_f32 v69, v6, s1, v16
	v_add_f32_e32 v78, v2, v4
	v_add_f32_e32 v79, v3, v4
	v_fma_f32 v80, v6, s0, v4
	v_fma_f32 v81, v6, s1, v4
	s_waitcnt lgkmcnt(1)
	v_mfma_f32_32x32x16_bf16 v[50:65], v[8:11], v[122:125], v[50:65]
	ds_read_b128 v[8:11], v17
	v_cmp_gt_u32_e32 vcc, s15, v5
	v_add_u32_e32 v3, -1, v5
	v_add_u32_e32 v4, -2, v5
	s_waitcnt lgkmcnt(1)
	v_mfma_f32_32x32x16_bf16 v[50:65], v[12:15], v[126:129], v[50:65]
	ds_read_b128 v[12:15], v17 offset:32
	s_waitcnt lgkmcnt(1)
	v_mfma_f32_32x32x16_bf16 v[66:81], v[8:11], v[114:117], v[66:81]
	ds_read_b128 v[8:11], v17 offset:64
	ds_read_b128 v[82:85], v17 offset:96
	s_nop 6
	v_cndmask_b32_e32 v90, v246, v50, vcc
	v_cmp_gt_u32_e32 vcc, s15, v3
	s_nop 1
	v_cndmask_b32_e32 v91, v246, v51, vcc
	v_cmp_gt_u32_e32 vcc, s15, v4
	s_waitcnt lgkmcnt(2)
	v_mfma_f32_32x32x16_bf16 v[66:81], v[12:15], v[118:121], v[66:81]
	v_add_u32_e32 v4, -3, v5
	v_cndmask_b32_e32 v96, v246, v52, vcc
	v_cmp_gt_u32_e32 vcc, s15, v4
	v_add_u32_e32 v4, -8, v5
	v_max3_f32 v3, v90, s33, v91
	v_cndmask_b32_e32 v97, v246, v53, vcc
	v_cmp_gt_u32_e32 vcc, s15, v4
	s_waitcnt lgkmcnt(1)
	v_mfma_f32_32x32x16_bf16 v[66:81], v[8:11], v[122:125], v[66:81]
	v_add_u32_e32 v4, -9, v5
	v_cndmask_b32_e32 v98, v246, v54, vcc
	v_cmp_gt_u32_e32 vcc, s15, v4
	v_add_u32_e32 v4, -10, v5
	v_max3_f32 v3, v3, v96, v97
	v_cndmask_b32_e32 v99, v246, v55, vcc
	v_cmp_gt_u32_e32 vcc, s15, v4
	v_add_u32_e32 v4, -11, v5
	s_waitcnt lgkmcnt(0)
	v_mfma_f32_32x32x16_bf16 v[66:81], v[82:85], v[126:129], v[66:81]
	v_cndmask_b32_e32 v100, v246, v56, vcc
	v_cmp_gt_u32_e32 vcc, s15, v4
	v_add_u32_e32 v4, -16, v5
	v_max3_f32 v3, v3, v98, v99
	v_cndmask_b32_e32 v101, v246, v57, vcc
	v_cmp_gt_u32_e32 vcc, s15, v4
	v_subrev_u32_e32 v4, 17, v5
	v_max3_f32 v3, v3, v100, v101
	v_cndmask_b32_e32 v102, v246, v58, vcc
	v_cmp_gt_u32_e32 vcc, s15, v4
	v_subrev_u32_e32 v4, 18, v5
	s_nop 0
	v_cndmask_b32_e32 v103, v246, v59, vcc
	v_cmp_gt_u32_e32 vcc, s15, v4
	v_subrev_u32_e32 v4, 19, v5
	v_max3_f32 v3, v3, v102, v103
	v_cndmask_b32_e32 v92, v246, v60, vcc
	v_cmp_gt_u32_e32 vcc, s15, v4
	v_subrev_u32_e32 v4, 24, v5
	s_nop 0
	v_cndmask_b32_e32 v93, v246, v61, vcc
	v_cmp_gt_u32_e32 vcc, s15, v4
	v_subrev_u32_e32 v4, 25, v5
	v_max3_f32 v3, v3, v92, v93
	v_cndmask_b32_e32 v94, v246, v62, vcc
	v_cmp_gt_u32_e32 vcc, s15, v4
	v_subrev_u32_e32 v4, 26, v5
	s_nop 0
	v_cndmask_b32_e32 v95, v246, v63, vcc
	v_cmp_gt_u32_e32 vcc, s15, v4
	v_subrev_u32_e32 v4, 27, v5
	v_max3_f32 v3, v3, v94, v95
	v_cndmask_b32_e32 v88, v246, v64, vcc
	v_cmp_gt_u32_e32 vcc, s15, v4
	v_subrev_u32_e32 v4, 32, v5
	s_nop 0
	v_cndmask_b32_e32 v89, v246, v65, vcc
	v_cmp_gt_u32_e32 vcc, s15, v4
	v_subrev_u32_e32 v4, 33, v5
	v_max3_f32 v3, v3, v88, v89
	v_cndmask_b32_e32 v14, v246, v66, vcc
	v_cmp_gt_u32_e32 vcc, s15, v4
	v_subrev_u32_e32 v4, 34, v5
	v_mov_b64_e32 v[64:65], v[48:49]
	v_cndmask_b32_e32 v15, v246, v67, vcc
	v_cmp_gt_u32_e32 vcc, s15, v4
	v_subrev_u32_e32 v4, 35, v5
	v_max3_f32 v3, v3, v14, v15
	v_cndmask_b32_e32 v16, v246, v68, vcc
	v_cmp_gt_u32_e32 vcc, s15, v4
	v_subrev_u32_e32 v4, 40, v5
	v_mov_b64_e32 v[62:63], v[46:47]
	v_cndmask_b32_e32 v17, v246, v69, vcc
	v_cmp_gt_u32_e32 vcc, s15, v4
	v_subrev_u32_e32 v4, 41, v5
	v_max3_f32 v3, v3, v16, v17
	v_cndmask_b32_e32 v82, v246, v70, vcc
	v_cmp_gt_u32_e32 vcc, s15, v4
	v_subrev_u32_e32 v4, 42, v5
	v_mov_b64_e32 v[60:61], v[44:45]
	v_cndmask_b32_e32 v83, v246, v71, vcc
	v_cmp_gt_u32_e32 vcc, s15, v4
	v_subrev_u32_e32 v4, 43, v5
	v_max3_f32 v3, v3, v82, v83
	v_cndmask_b32_e32 v84, v246, v72, vcc
	v_cmp_gt_u32_e32 vcc, s15, v4
	v_subrev_u32_e32 v4, 48, v5
	v_mov_b64_e32 v[58:59], v[42:43]
	v_cndmask_b32_e32 v85, v246, v73, vcc
	v_cmp_gt_u32_e32 vcc, s15, v4
	v_subrev_u32_e32 v4, 49, v5
	v_max3_f32 v3, v3, v84, v85
	v_cndmask_b32_e32 v86, v246, v74, vcc
	v_cmp_gt_u32_e32 vcc, s15, v4
	v_subrev_u32_e32 v4, 50, v5
	v_mov_b64_e32 v[56:57], v[40:41]
	v_cndmask_b32_e32 v87, v246, v75, vcc
	v_cmp_gt_u32_e32 vcc, s15, v4
	v_subrev_u32_e32 v4, 51, v5
	v_max3_f32 v3, v3, v86, v87
	v_cndmask_b32_e32 v12, v246, v76, vcc
	v_cmp_gt_u32_e32 vcc, s15, v4
	v_subrev_u32_e32 v4, 56, v5
	v_mov_b64_e32 v[54:55], v[38:39]
	v_cndmask_b32_e32 v13, v246, v77, vcc
	v_cmp_gt_u32_e32 vcc, s15, v4
	v_subrev_u32_e32 v4, 57, v5
	v_max3_f32 v3, v3, v12, v13
	v_cndmask_b32_e32 v8, v246, v78, vcc
	v_cmp_gt_u32_e32 vcc, s15, v4
	v_subrev_u32_e32 v4, 58, v5
	v_mov_b64_e32 v[52:53], v[36:37]
	v_cndmask_b32_e32 v9, v246, v79, vcc
	v_cmp_gt_u32_e32 vcc, s15, v4
	v_subrev_u32_e32 v4, 59, v5
	v_max3_f32 v3, v3, v8, v9
	v_cndmask_b32_e32 v10, v246, v80, vcc
	v_cmp_gt_u32_e32 vcc, s15, v4
	v_mov_b64_e32 v[50:51], v[34:35]
	s_nop 0
	v_cndmask_b32_e32 v11, v246, v81, vcc
	v_max3_f32 v3, v3, v10, v11
	ds_bpermute_b32 v4, v194, v3
	v_mov_b64_e32 v[80:81], v[32:33]
	v_mov_b64_e32 v[78:79], v[30:31]
	v_mov_b64_e32 v[76:77], v[28:29]
	v_mov_b64_e32 v[74:75], v[26:27]
	s_waitcnt lgkmcnt(0)
	v_max_f32_e32 v4, v4, v4
	v_max_f32_e32 v3, v3, v4
	v_max3_f32 v4, v249, v3, s14
	v_sub_f32_e32 v3, v249, v4
	v_exp_f32_e32 v6, v3
	v_mov_b64_e32 v[72:73], v[24:25]
	v_mov_b64_e32 v[70:71], v[22:23]
	v_mov_b64_e32 v[68:69], v[20:21]
	v_cmp_eq_f32_e32 vcc, 1.0, v6
	s_cmp_eq_u64 vcc, exec
	v_mov_b64_e32 v[66:67], v[18:19]
	s_cbranch_scc1 .LBB0_1580
	v_mul_f32_e32 v64, v48, v6
	v_mul_f32_e32 v65, v49, v6
	v_mul_f32_e32 v62, v46, v6
	v_mul_f32_e32 v63, v47, v6
	v_mul_f32_e32 v60, v44, v6
	v_mul_f32_e32 v61, v45, v6
	v_mul_f32_e32 v58, v42, v6
	v_mul_f32_e32 v59, v43, v6
	v_mul_f32_e32 v56, v40, v6
	v_mul_f32_e32 v57, v41, v6
	v_mul_f32_e32 v54, v38, v6
	v_mul_f32_e32 v55, v39, v6
	v_mul_f32_e32 v52, v36, v6
	v_mul_f32_e32 v53, v37, v6
	v_mul_f32_e32 v50, v34, v6
	v_mul_f32_e32 v51, v35, v6
	v_mul_f32_e32 v80, v32, v6
	v_mul_f32_e32 v81, v33, v6
	v_mul_f32_e32 v78, v30, v6
	v_mul_f32_e32 v79, v31, v6
	v_mul_f32_e32 v76, v28, v6
	v_mul_f32_e32 v77, v29, v6
	v_mul_f32_e32 v74, v26, v6
	v_mul_f32_e32 v75, v27, v6
	v_mul_f32_e32 v72, v24, v6
	v_mul_f32_e32 v73, v25, v6
	v_mul_f32_e32 v70, v22, v6
	v_mul_f32_e32 v71, v23, v6
	v_mul_f32_e32 v68, v20, v6
	v_mul_f32_e32 v69, v21, v6
	v_mul_f32_e32 v66, v18, v6
	v_mul_f32_e32 v67, v19, v6
.LBB0_1580:
	v_sub_f32_e32 v96, v96, v4
	v_sub_f32_e32 v97, v97, v4
	v_add_u32_e32 v3, v226, v220
	v_exp_f32_e32 v108, v96
	v_exp_f32_e32 v109, v97
	v_sub_f32_e32 v96, v98, v4
	v_sub_f32_e32 v97, v99, v4
	v_add_u32_e32 v3, 0x2000, v3
	v_exp_f32_e32 v110, v96
	v_exp_f32_e32 v111, v97
	v_sub_f32_e32 v96, v100, v4
	v_sub_f32_e32 v97, v101, v4
	v_add_u32_e32 v104, v226, v221
	v_exp_f32_e32 v112, v96
	v_exp_f32_e32 v113, v97
	ds_read2_b64 v[96:99], v3 offset0:128 offset1:130
	v_add_u32_e32 v136, 0x2000, v104
	v_sub_f32_e32 v90, v90, v4
	v_sub_f32_e32 v91, v91, v4
	ds_read2_b64 v[104:107], v136 offset0:128 offset1:130
	v_exp_f32_e32 v90, v90
	v_exp_f32_e32 v91, v91
	v_sub_f32_e32 v92, v92, v4
	v_sub_f32_e32 v93, v93, v4
	v_sub_f32_e32 v100, v102, v4
	v_sub_f32_e32 v101, v103, v4
	v_exp_f32_e32 v132, v92
	v_exp_f32_e32 v133, v93
	v_sub_f32_e32 v92, v94, v4
	v_sub_f32_e32 v93, v95, v4
	v_exp_f32_e32 v130, v100
	v_exp_f32_e32 v131, v101
	v_cvt_pk_bf16_f32 v100, v90, v91
	v_cvt_pk_bf16_f32 v101, v108, v109
	v_cvt_pk_bf16_f32 v102, v110, v111
	v_cvt_pk_bf16_f32 v103, v112, v113
	v_exp_f32_e32 v134, v92
	v_exp_f32_e32 v135, v93
	ds_read2_b64 v[92:95], v3 offset0:132 offset1:134
	s_waitcnt lgkmcnt(2)
	v_mfma_f32_32x32x16_bf16 v[50:65], v[96:99], v[100:103], v[50:65]
	v_add_f32_e64 v88, v88, -v4
	v_add_f32_e64 v89, v89, -v4
	v_cvt_pk_bf16_f32 v96, v130, v131
	v_cvt_pk_bf16_f32 v97, v132, v133
	v_cvt_pk_bf16_f32 v98, v134, v135
	s_waitcnt lgkmcnt(1)
	v_mfma_f32_32x32x16_bf16 v[66:81], v[104:107], v[100:103], v[66:81]
	v_exp_f32_e32 v100, v88
	v_exp_f32_e32 v101, v89
	s_nop 0
	v_cvt_pk_bf16_f32 v99, v100, v101
	s_waitcnt lgkmcnt(0)
	s_nop 0
	v_mfma_f32_32x32x16_bf16 v[50:65], v[92:95], v[96:99], v[50:65]
	ds_read2_b64 v[92:95], v136 offset0:132 offset1:134
	s_waitcnt lgkmcnt(0)
	v_mfma_f32_32x32x16_bf16 v[66:81], v[92:95], v[96:99], v[66:81]
	v_add_f32_e64 v14, v14, -v4
	v_add_f32_e64 v15, v15, -v4
	v_add_f32_e64 v12, v12, -v4
	v_add_f32_e64 v13, v13, -v4
	v_exp_f32_e32 v92, v14
	v_exp_f32_e32 v93, v15
	v_sub_f32_e32 v14, v16, v4
	v_sub_f32_e32 v15, v17, v4
	v_sub_f32_e32 v8, v8, v4
	v_sub_f32_e32 v9, v9, v4
	v_exp_f32_e32 v94, v14
	v_exp_f32_e32 v95, v15
	v_sub_f32_e32 v14, v82, v4
	v_sub_f32_e32 v15, v83, v4
	v_sub_f32_e32 v82, v86, v4
	v_sub_f32_e32 v83, v87, v4
	v_exp_f32_e32 v96, v14
	v_exp_f32_e32 v97, v15
	v_sub_f32_e32 v14, v84, v4
	v_sub_f32_e32 v15, v85, v4
	ds_read2_b64 v[86:89], v136 offset0:136 offset1:138
	v_exp_f32_e32 v98, v14
	v_exp_f32_e32 v99, v15
	ds_read2_b64 v[14:17], v3 offset0:136 offset1:138
	v_exp_f32_e32 v102, v82
	v_exp_f32_e32 v103, v83
	v_cvt_pk_bf16_f32 v82, v92, v93
	v_cvt_pk_bf16_f32 v83, v94, v95
	v_cvt_pk_bf16_f32 v84, v96, v97
	v_cvt_pk_bf16_f32 v85, v98, v99
	v_exp_f32_e32 v104, v8
	v_exp_f32_e32 v105, v9
	s_waitcnt lgkmcnt(0)
	v_mfma_f32_32x32x16_bf16 v[50:65], v[14:17], v[82:85], v[50:65]
	v_exp_f32_e32 v16, v12
	v_exp_f32_e32 v17, v13
	v_sub_f32_e32 v12, v10, v4
	v_sub_f32_e32 v13, v11, v4
	ds_read2_b64 v[8:11], v3 offset0:140 offset1:142
	v_mfma_f32_32x32x16_bf16 v[66:81], v[86:89], v[82:85], v[66:81]
	v_exp_f32_e32 v86, v12
	v_exp_f32_e32 v87, v13
	v_cvt_pk_bf16_f32 v82, v102, v103
	v_cvt_pk_bf16_f32 v83, v16, v17
	v_cvt_pk_bf16_f32 v84, v104, v105
	v_cvt_pk_bf16_f32 v85, v86, v87
	ds_read2_b64 v[12:15], v136 offset0:140 offset1:142
	s_waitcnt lgkmcnt(1)
	v_mfma_f32_32x32x16_bf16 v[50:65], v[8:11], v[82:85], v[50:65]
	v_add_f32_e64 v8, v90, 0
	v_add_f32_e64 v9, v91, 0
	v_add_f32_e64 v8, v108, v8
	v_add_f32_e64 v9, v109, v9
	v_add_f32_e64 v8, v110, v8
	v_add_f32_e64 v9, v111, v9
	v_add_f32_e32 v8, v112, v8
	v_add_f32_e32 v9, v113, v9
	s_waitcnt lgkmcnt(0)
	v_mfma_f32_32x32x16_bf16 v[66:81], v[12:15], v[82:85], v[66:81]
	v_add_f32_e64 v8, v130, v8
	v_add_f32_e64 v9, v131, v9
	v_add_f32_e64 v8, v132, v8
	v_add_f32_e64 v9, v133, v9
	v_add_f32_e64 v8, v134, v8
	v_add_f32_e64 v9, v135, v9
	v_add_f32_e32 v8, v100, v8
	v_add_f32_e32 v9, v101, v9
	s_nop 0
	v_add_f32_e32 v8, v92, v8
	v_add_f32_e32 v9, v93, v9
	s_nop 0
	v_add_f32_e32 v8, v94, v8
	v_add_f32_e32 v9, v95, v9
	s_nop 0
	v_add_f32_e32 v8, v96, v8
	v_add_f32_e32 v9, v97, v9
	s_nop 0
	v_add_f32_e32 v8, v98, v8
	v_add_f32_e32 v9, v99, v9
	s_nop 0
	v_add_f32_e32 v8, v102, v8
	v_add_f32_e32 v9, v103, v9
	s_nop 0
	v_add_f32_e32 v8, v16, v8
	v_add_f32_e32 v9, v17, v9
	s_nop 0
	v_add_f32_e32 v8, v104, v8
	v_add_f32_e32 v9, v105, v9
	s_nop 0
	v_add_f32_e32 v8, v86, v8
	v_add_f32_e32 v9, v87, v9
	s_nop 0
	v_add_f32_e32 v3, v8, v9
	ds_bpermute_b32 v10, v194, v3
.LBB0_1581:
	s_andn2_saveexec_b64 s[42:43], s[42:43]
	s_cbranch_execz .LBB0_1585
	v_mov_b32_e32 v3, v152
	v_add_u32_e32 v16, v225, v192
	v_mul_f32_e64 v4, v7, -v3
	v_cndmask_b32_e64 v4, v246, v4, s[50:51]
	v_mov_b32_e32 v6, v3
	v_fma_f32 v8, 0, v3, v4
	v_add_f32_e32 v98, v2, v8
	v_add_f32_e32 v99, v3, v8
	v_fma_f32 v100, v6, s0, v8
	v_fma_f32 v101, v6, s1, v8
	s_waitcnt lgkmcnt(0)
	ds_read_b128 v[8:11], v16
	v_fmamk_f32 v12, v3, 0x41000000, v4
	v_add_f32_e32 v102, v2, v12
	v_add_f32_e32 v103, v3, v12
	v_fma_f32 v104, v6, s0, v12
	v_fma_f32 v105, v6, s1, v12
	v_fmamk_f32 v12, v3, 0x41800000, v4
	v_add_f32_e32 v106, v2, v12
	v_add_f32_e32 v107, v3, v12
	v_fma_f32 v108, v6, s0, v12
	v_fma_f32 v109, v6, s1, v12
	v_fmamk_f32 v12, v3, 0x41c00000, v4
	v_add_f32_e32 v110, v2, v12
	v_add_f32_e32 v111, v3, v12
	v_fma_f32 v112, v6, s0, v12
	v_fma_f32 v113, v6, s1, v12
	ds_read_b128 v[12:15], v16 offset:32
	v_add_u32_e32 v17, v225, v193
	s_waitcnt lgkmcnt(1)
	v_mfma_f32_32x32x16_bf16 v[98:113], v[8:11], v[114:117], v[98:113]
	ds_read_b128 v[8:11], v16 offset:64
	v_fmamk_f32 v50, v3, 0x42200000, v4
	v_fmamk_f32 v52, v3, 0x42400000, v4
	v_add_f32_e64 v86, v2, v50
	v_add_f32_e64 v87, v3, v50
	v_fma_f32 v88, v6, s0, v50
	v_fma_f32 v89, v6, s1, v50
	v_add_f32_e32 v90, v2, v52
	v_add_f32_e32 v91, v3, v52
	v_fma_f32 v92, v6, s0, v52
	v_fma_f32 v93, v6, s1, v52
	s_waitcnt lgkmcnt(1)
	v_mfma_f32_32x32x16_bf16 v[98:113], v[12:15], v[118:121], v[98:113]
	ds_read_b128 v[12:15], v16 offset:96
	v_fmamk_f32 v16, v3, 0x42000000, v4
	v_fmac_f32_e32 v4, 0x42600000, v3
	v_add_f32_e64 v82, v2, v16
	v_add_f32_e64 v83, v3, v16
	v_fma_f32 v84, v6, s0, v16
	v_fma_f32 v85, v6, s1, v16
	v_add_f32_e32 v94, v2, v4
	v_add_f32_e32 v95, v3, v4
	v_fma_f32 v96, v6, s0, v4
	v_fma_f32 v97, v6, s1, v4
	s_waitcnt lgkmcnt(1)
	v_mfma_f32_32x32x16_bf16 v[98:113], v[8:11], v[122:125], v[98:113]
	ds_read_b128 v[8:11], v17
	v_mov_b64_e32 v[64:65], v[48:49]
	v_mov_b64_e32 v[80:81], v[32:33]
	v_mov_b64_e32 v[62:63], v[46:47]
	v_mov_b64_e32 v[60:61], v[44:45]
	v_mov_b64_e32 v[58:59], v[42:43]
	v_mov_b64_e32 v[56:57], v[40:41]
	s_waitcnt lgkmcnt(1)
	v_mfma_f32_32x32x16_bf16 v[98:113], v[12:15], v[126:129], v[98:113]
	ds_read_b128 v[12:15], v17 offset:32
	v_mov_b64_e32 v[54:55], v[38:39]
	v_mov_b64_e32 v[52:53], v[36:37]
	v_mov_b64_e32 v[50:51], v[34:35]
	v_mov_b64_e32 v[78:79], v[30:31]
	v_mov_b64_e32 v[76:77], v[28:29]
	v_mov_b64_e32 v[74:75], v[26:27]
	s_waitcnt lgkmcnt(1)
	v_mfma_f32_32x32x16_bf16 v[82:97], v[8:11], v[114:117], v[82:97]
	s_nop 2
	v_max3_f32 v3, v98, s33, v99
	v_max3_f32 v3, v3, v100, v101
	v_max3_f32 v3, v3, v102, v103
	v_max3_f32 v3, v3, v104, v105
	v_max3_f32 v3, v3, v106, v107
	v_max3_f32 v3, v3, v108, v109
	v_max3_f32 v3, v3, v110, v111
	s_waitcnt lgkmcnt(0)
	v_mfma_f32_32x32x16_bf16 v[82:97], v[12:15], v[118:121], v[82:97]
	ds_read_b128 v[8:11], v17 offset:64
	ds_read_b128 v[12:15], v17 offset:96
	v_max3_f32 v3, v3, v112, v113
	v_mov_b64_e32 v[72:73], v[24:25]
	v_mov_b64_e32 v[70:71], v[22:23]
	v_mov_b64_e32 v[68:69], v[20:21]
	v_mov_b64_e32 v[66:67], v[18:19]
	s_waitcnt lgkmcnt(1)
	v_mfma_f32_32x32x16_bf16 v[82:97], v[8:11], v[122:125], v[82:97]
	s_waitcnt lgkmcnt(0)
	v_mfma_f32_32x32x16_bf16 v[82:97], v[12:15], v[126:129], v[82:97]
	s_nop 11
	v_max3_f32 v3, v3, v82, v83
	v_max3_f32 v3, v3, v84, v85
	v_max3_f32 v3, v3, v86, v87
	v_max3_f32 v3, v3, v88, v89
	v_max3_f32 v3, v3, v90, v91
	v_max3_f32 v3, v3, v92, v93
	v_max3_f32 v3, v3, v94, v95
	v_max3_f32 v3, v3, v96, v97
	ds_bpermute_b32 v4, v194, v3
	s_waitcnt lgkmcnt(0)
	v_max_f32_e32 v4, v4, v4
	v_max_f32_e32 v3, v3, v4
	v_max3_f32 v4, v249, v3, s14
	v_sub_f32_e32 v3, v249, v4
	v_exp_f32_e32 v6, v3
	s_nop 0
	v_cmp_eq_f32_e32 vcc, 1.0, v6
	s_cmp_eq_u64 vcc, exec
	s_cbranch_scc1 .LBB0_1584
	v_mul_f32_e32 v64, v48, v6
	v_mul_f32_e32 v65, v49, v6
	v_mul_f32_e32 v62, v46, v6
	v_mul_f32_e32 v63, v47, v6
	v_mul_f32_e32 v60, v44, v6
	v_mul_f32_e32 v61, v45, v6
	v_mul_f32_e32 v58, v42, v6
	v_mul_f32_e32 v59, v43, v6
	v_mul_f32_e32 v56, v40, v6
	v_mul_f32_e32 v57, v41, v6
	v_mul_f32_e32 v54, v38, v6
	v_mul_f32_e32 v55, v39, v6
	v_mul_f32_e32 v52, v36, v6
	v_mul_f32_e32 v53, v37, v6
	v_mul_f32_e32 v50, v34, v6
	v_mul_f32_e32 v51, v35, v6
	v_mul_f32_e32 v80, v32, v6
	v_mul_f32_e32 v81, v33, v6
	v_mul_f32_e32 v78, v30, v6
	v_mul_f32_e32 v79, v31, v6
	v_mul_f32_e32 v76, v28, v6
	v_mul_f32_e32 v77, v29, v6
	v_mul_f32_e32 v74, v26, v6
	v_mul_f32_e32 v75, v27, v6
	v_mul_f32_e32 v72, v24, v6
	v_mul_f32_e32 v73, v25, v6
	v_mul_f32_e32 v70, v22, v6
	v_mul_f32_e32 v71, v23, v6
	v_mul_f32_e32 v68, v20, v6
	v_mul_f32_e32 v69, v21, v6
	v_mul_f32_e32 v66, v18, v6
	v_mul_f32_e32 v67, v19, v6
.LBB0_1584:
	v_sub_f32_e32 v8, v98, v4
	v_sub_f32_e32 v9, v99, v4
	v_sub_f32_e32 v10, v100, v4
	v_sub_f32_e32 v11, v101, v4
	v_sub_f32_e32 v12, v102, v4
	v_sub_f32_e32 v13, v103, v4
	v_sub_f32_e32 v14, v104, v4
	v_sub_f32_e32 v15, v105, v4
	v_add_u32_e32 v3, v226, v220
	v_exp_f32_e32 v8, v8
	v_exp_f32_e32 v9, v9
	v_exp_f32_e32 v10, v10
	v_exp_f32_e32 v11, v11
	v_exp_f32_e32 v12, v12
	v_exp_f32_e32 v13, v13
	v_exp_f32_e32 v14, v14
	v_exp_f32_e32 v15, v15
	v_add_u32_e32 v3, 0x2000, v3
	v_sub_f32_e32 v98, v108, v4
	v_sub_f32_e32 v99, v109, v4
	v_sub_f32_e32 v100, v110, v4
	v_sub_f32_e32 v101, v111, v4
	ds_read2_b64 v[108:111], v3 offset0:128 offset1:130
	ds_read2_b64 v[130:133], v3 offset0:132 offset1:134
	v_sub_f32_e32 v16, v106, v4
	v_sub_f32_e32 v17, v107, v4
	v_cvt_pk_bf16_f32 v104, v8, v9
	v_cvt_pk_bf16_f32 v105, v10, v11
	v_cvt_pk_bf16_f32 v106, v12, v13
	v_cvt_pk_bf16_f32 v107, v14, v15
	v_sub_f32_e32 v102, v112, v4
	v_sub_f32_e32 v103, v113, v4
	v_exp_f32_e32 v16, v16
	s_waitcnt lgkmcnt(1)
	v_mfma_f32_32x32x16_bf16 v[50:65], v[108:111], v[104:107], v[50:65]
	v_add_u32_e32 v108, v226, v221
	v_add_u32_e32 v138, 0x2000, v108
	ds_read2_b64 v[108:111], v138 offset0:128 offset1:130
	ds_read2_b64 v[134:137], v138 offset0:132 offset1:134
	v_exp_f32_e32 v17, v17
	v_exp_f32_e32 v98, v98
	v_exp_f32_e32 v99, v99
	v_exp_f32_e32 v100, v100
	s_waitcnt lgkmcnt(1)
	v_mfma_f32_32x32x16_bf16 v[66:81], v[108:111], v[104:107], v[66:81]
	v_exp_f32_e32 v101, v101
	v_exp_f32_e32 v102, v102
	v_exp_f32_e32 v103, v103
	v_cvt_pk_bf16_f32 v104, v16, v17
	v_cvt_pk_bf16_f32 v105, v98, v99
	v_cvt_pk_bf16_f32 v106, v100, v101
	v_cvt_pk_bf16_f32 v107, v102, v103
	s_nop 1
	v_mfma_f32_32x32x16_bf16 v[50:65], v[130:133], v[104:107], v[50:65]
	s_waitcnt lgkmcnt(0)
	v_mfma_f32_32x32x16_bf16 v[66:81], v[134:137], v[104:107], v[66:81]
	v_add_f32_e64 v88, v88, -v4
	v_add_f32_e64 v89, v89, -v4
	v_add_f32_e64 v82, v82, -v4
	v_add_f32_e64 v83, v83, -v4
	v_add_f32_e64 v84, v84, -v4
	v_add_f32_e64 v85, v85, -v4
	v_sub_f32_e32 v86, v86, v4
	v_sub_f32_e32 v87, v87, v4
	v_exp_f32_e32 v112, v88
	v_exp_f32_e32 v113, v89
	v_sub_f32_e32 v88, v90, v4
	v_sub_f32_e32 v89, v91, v4
	v_exp_f32_e32 v82, v82
	v_exp_f32_e32 v83, v83
	v_exp_f32_e32 v84, v84
	v_exp_f32_e32 v85, v85
	v_exp_f32_e32 v86, v86
	v_exp_f32_e32 v87, v87
	v_exp_f32_e32 v130, v88
	v_exp_f32_e32 v131, v89
	v_sub_f32_e32 v88, v92, v4
	v_sub_f32_e32 v89, v93, v4
	v_add_f32_e32 v8, 0, v8
	v_add_f32_e32 v9, 0, v9
	v_exp_f32_e32 v132, v88
	v_exp_f32_e32 v133, v89
	v_sub_f32_e32 v88, v94, v4
	v_sub_f32_e32 v89, v95, v4
	ds_read2_b64 v[92:95], v3 offset0:136 offset1:138
	ds_read2_b64 v[104:107], v3 offset0:140 offset1:142
	v_exp_f32_e32 v134, v88
	v_exp_f32_e32 v135, v89
	v_sub_f32_e32 v88, v96, v4
	v_sub_f32_e32 v89, v97, v4
	v_cvt_pk_bf16_f32 v90, v86, v87
	v_exp_f32_e32 v96, v88
	v_exp_f32_e32 v97, v89
	v_cvt_pk_bf16_f32 v88, v82, v83
	v_cvt_pk_bf16_f32 v89, v84, v85
	v_cvt_pk_bf16_f32 v91, v112, v113
	v_add_f32_e32 v8, v10, v8
	v_add_f32_e32 v9, v11, v9
	s_waitcnt lgkmcnt(1)
	v_mfma_f32_32x32x16_bf16 v[50:65], v[92:95], v[88:91], v[50:65]
	ds_read2_b64 v[92:95], v138 offset0:136 offset1:138
	ds_read2_b64 v[108:111], v138 offset0:140 offset1:142
	v_add_f32_e64 v8, v12, v8
	v_add_f32_e64 v9, v13, v9
	v_add_f32_e64 v8, v14, v8
	v_add_f32_e64 v9, v15, v9
	v_add_f32_e32 v8, v16, v8
	v_add_f32_e32 v9, v17, v9
	s_nop 0
	v_add_f32_e32 v8, v98, v8
	v_add_f32_e32 v9, v99, v9
	s_waitcnt lgkmcnt(1)
	v_mfma_f32_32x32x16_bf16 v[66:81], v[92:95], v[88:91], v[66:81]
	v_add_f32_e64 v8, v100, v8
	v_add_f32_e64 v9, v101, v9
	v_cvt_pk_bf16_f32 v88, v130, v131
	v_add_f32_e64 v8, v102, v8
	v_add_f32_e64 v9, v103, v9
	v_cvt_pk_bf16_f32 v89, v132, v133
	v_add_f32_e32 v8, v82, v8
	v_add_f32_e32 v9, v83, v9
	v_cvt_pk_bf16_f32 v90, v134, v135
	v_add_f32_e32 v8, v84, v8
	v_add_f32_e32 v9, v85, v9
	v_cvt_pk_bf16_f32 v91, v96, v97
	v_add_f32_e32 v8, v86, v8
	v_add_f32_e32 v9, v87, v9
	s_nop 0
	v_add_f32_e32 v8, v112, v8
	v_add_f32_e32 v9, v113, v9
	v_mfma_f32_32x32x16_bf16 v[50:65], v[104:107], v[88:91], v[50:65]
	v_add_f32_e64 v8, v130, v8
	v_add_f32_e64 v9, v131, v9
	v_add_f32_e64 v8, v132, v8
	v_add_f32_e64 v9, v133, v9
	v_add_f32_e64 v8, v134, v8
	v_add_f32_e64 v9, v135, v9
	v_add_f32_e32 v8, v96, v8
	v_add_f32_e32 v9, v97, v9
	s_waitcnt lgkmcnt(0)
	v_mfma_f32_32x32x16_bf16 v[66:81], v[108:111], v[88:91], v[66:81]
	v_add_f32_e32 v3, v8, v9
	ds_bpermute_b32 v10, v194, v3

.LBB0_1586:
	s_andn2_b64 vcc, exec, s[8:9]
	s_cbranch_vccnz .LBB0_1495
	v_cmp_lt_i32_e32 vcc, 31, v247
	v_add_u32_e32 v9, v225, v192
	v_add_u32_e32 v8, v225, v193
	s_and_saveexec_b64 s[8:9], vcc
	s_xor_b64 s[42:43], exec, s[8:9]
	s_cbranch_execz .LBB0_1591
	v_mov_b32_e32 v3, v152
	v_cmp_lt_i32_e32 vcc, -1, v5
	v_mul_f32_e64 v4, v7, -v3
	v_cndmask_b32_e64 v4, v246, v4, s[50:51]
	v_mov_b32_e32 v6, v3
	s_waitcnt lgkmcnt(0)
	v_fma_f32 v10, 0, v3, v4
	v_add_f32_e32 v50, v2, v10
	v_add_f32_e32 v51, v3, v10
	v_fma_f32 v52, v6, s0, v10
	v_fma_f32 v53, v6, s1, v10
	v_fmamk_f32 v10, v3, 0x41000000, v4
	v_add_f32_e32 v54, v2, v10
	v_add_f32_e32 v55, v3, v10
	v_fma_f32 v56, v6, s0, v10
	v_fma_f32 v57, v6, s1, v10
	v_fmamk_f32 v10, v3, 0x41800000, v4
	v_add_f32_e32 v58, v2, v10
	v_add_f32_e32 v59, v3, v10
	v_fma_f32 v60, v6, s0, v10
	v_fma_f32 v61, v6, s1, v10
	v_fmamk_f32 v10, v3, 0x41c00000, v4
	v_add_f32_e32 v62, v2, v10
	v_add_f32_e32 v63, v3, v10
	v_fma_f32 v64, v6, s0, v10
	v_fma_f32 v65, v6, s1, v10
	ds_read_b128 v[10:13], v9
	ds_read_b128 v[14:17], v9 offset:32
	s_waitcnt lgkmcnt(1)
	v_mfma_f32_32x32x16_bf16 v[50:65], v[10:13], v[114:117], v[50:65]
	ds_read_b128 v[10:13], v9 offset:64
	s_waitcnt lgkmcnt(1)
	v_mfma_f32_32x32x16_bf16 v[50:65], v[14:17], v[118:121], v[50:65]
	s_waitcnt lgkmcnt(0)
	v_mfma_f32_32x32x16_bf16 v[50:65], v[10:13], v[122:125], v[50:65]
	ds_read_b128 v[10:13], v9 offset:96
	s_waitcnt lgkmcnt(0)
	v_mfma_f32_32x32x16_bf16 v[50:65], v[10:13], v[126:129], v[50:65]
	v_fmamk_f32 v10, v3, 0x42000000, v4
	v_add_f32_e64 v66, v2, v10
	v_add_f32_e64 v67, v3, v10
	v_fma_f32 v68, v6, s0, v10
	v_fma_f32 v69, v6, s1, v10
	v_fmamk_f32 v10, v3, 0x42200000, v4
	v_add_f32_e32 v70, v2, v10
	v_add_f32_e32 v71, v3, v10
	v_fma_f32 v72, v6, s0, v10
	v_fma_f32 v73, v6, s1, v10
	v_fmamk_f32 v10, v3, 0x42400000, v4
	v_add_f32_e32 v74, v2, v10
	v_add_f32_e32 v75, v3, v10
	v_fma_f32 v76, v6, s0, v10
	v_fma_f32 v77, v6, s1, v10
	ds_read_b128 v[10:13], v8
	ds_read_b128 v[14:17], v8 offset:32
	v_fmac_f32_e32 v4, 0x42600000, v3
	v_add_f32_e32 v78, v2, v4
	v_add_f32_e32 v79, v3, v4
	v_fma_f32 v80, v6, s0, v4
	v_fma_f32 v81, v6, s1, v4
	v_cndmask_b32_e32 v82, v246, v50, vcc
	v_cmp_lt_i32_e32 vcc, 0, v5
	s_waitcnt lgkmcnt(1)
	v_mfma_f32_32x32x16_bf16 v[66:81], v[10:13], v[114:117], v[66:81]
	ds_read_b128 v[10:13], v8 offset:64
	ds_read_b128 v[6:9], v8 offset:96
	v_cndmask_b32_e32 v83, v246, v51, vcc
	v_cmp_lt_i32_e32 vcc, 1, v5
	v_max3_f32 v3, v82, s33, v83
	s_nop 0
	v_cndmask_b32_e32 v84, v246, v52, vcc
	s_waitcnt lgkmcnt(2)
	v_mfma_f32_32x32x16_bf16 v[66:81], v[14:17], v[118:121], v[66:81]
	v_cmp_lt_i32_e32 vcc, 2, v5
	s_nop 1
	v_cndmask_b32_e32 v85, v246, v53, vcc
	v_cmp_lt_i32_e32 vcc, 7, v5
	v_max3_f32 v3, v3, v84, v85
	s_waitcnt lgkmcnt(1)
	v_mfma_f32_32x32x16_bf16 v[66:81], v[10:13], v[122:125], v[66:81]
	v_cndmask_b32_e32 v88, v246, v54, vcc
	v_cmp_lt_i32_e32 vcc, 8, v5
	s_nop 1
	v_cndmask_b32_e32 v89, v246, v55, vcc
	v_cmp_lt_i32_e32 vcc, 9, v5
	v_max3_f32 v3, v3, v88, v89
	s_waitcnt lgkmcnt(0)
	v_mfma_f32_32x32x16_bf16 v[66:81], v[6:9], v[126:129], v[66:81]
	v_cndmask_b32_e32 v86, v246, v56, vcc
	v_cmp_lt_i32_e32 vcc, 10, v5
	s_nop 1
	v_cndmask_b32_e32 v87, v246, v57, vcc
	v_cmp_lt_i32_e32 vcc, 15, v5
	v_max3_f32 v3, v3, v86, v87
	s_nop 0
	v_cndmask_b32_e32 v90, v246, v58, vcc
	v_cmp_lt_i32_e32 vcc, 16, v5
	s_nop 1
	v_cndmask_b32_e32 v91, v246, v59, vcc
	v_cmp_lt_i32_e32 vcc, 17, v5
	v_max3_f32 v3, v3, v90, v91
	s_nop 0
	v_cndmask_b32_e32 v60, v246, v60, vcc
	v_cmp_lt_i32_e32 vcc, 18, v5
	s_nop 1
	v_cndmask_b32_e32 v61, v246, v61, vcc
	v_cmp_lt_i32_e32 vcc, 23, v5
	v_max3_f32 v3, v3, v60, v61
	s_nop 0
	v_cndmask_b32_e32 v62, v246, v62, vcc
	v_cmp_lt_i32_e32 vcc, 24, v5
	s_nop 1
	v_cndmask_b32_e32 v63, v246, v63, vcc
	v_cmp_lt_i32_e32 vcc, 25, v5
	v_max3_f32 v3, v3, v62, v63
	s_nop 0
	v_cndmask_b32_e32 v58, v246, v64, vcc
	v_cmp_lt_i32_e32 vcc, 26, v5
	s_nop 1
	v_cndmask_b32_e32 v59, v246, v65, vcc
	v_cmp_lt_i32_e32 vcc, 31, v5
	v_max3_f32 v3, v3, v58, v59
	s_nop 0
	v_cndmask_b32_e32 v54, v246, v66, vcc
	v_cmp_lt_i32_e32 vcc, 32, v5
	s_nop 1
	v_cndmask_b32_e32 v55, v246, v67, vcc
	v_cmp_lt_i32_e32 vcc, 33, v5
	v_max3_f32 v3, v3, v54, v55
	s_nop 0
	v_cndmask_b32_e32 v52, v246, v68, vcc
	v_cmp_lt_i32_e32 vcc, 34, v5
	s_nop 1
	v_cndmask_b32_e32 v53, v246, v69, vcc
	v_cmp_lt_i32_e32 vcc, 39, v5
	v_max3_f32 v3, v3, v52, v53
	s_nop 0
	v_cndmask_b32_e32 v50, v246, v70, vcc
	v_cmp_lt_i32_e32 vcc, 40, v5
	s_nop 1
	v_cndmask_b32_e32 v51, v246, v71, vcc
	v_cmp_lt_i32_e32 vcc, 41, v5
	v_max3_f32 v3, v3, v50, v51
	s_nop 0
	v_cndmask_b32_e32 v16, v246, v72, vcc
	v_cmp_lt_i32_e32 vcc, 42, v5
	s_nop 1
	v_cndmask_b32_e32 v17, v246, v73, vcc
	v_cmp_lt_i32_e32 vcc, 47, v5
	v_max3_f32 v3, v3, v16, v17
	s_nop 0
	v_cndmask_b32_e32 v14, v246, v74, vcc
	v_cmp_lt_i32_e32 vcc, 48, v5
	s_nop 1
	v_cndmask_b32_e32 v15, v246, v75, vcc
	v_cmp_lt_i32_e32 vcc, 49, v5
	v_max3_f32 v3, v3, v14, v15
	s_nop 0
	v_cndmask_b32_e32 v12, v246, v76, vcc
	v_cmp_lt_i32_e32 vcc, 50, v5
	s_nop 1
	v_cndmask_b32_e32 v13, v246, v77, vcc
	v_cmp_lt_i32_e32 vcc, 55, v5
	v_max3_f32 v3, v3, v12, v13
	s_nop 0
	v_cndmask_b32_e32 v8, v246, v78, vcc
	v_cmp_lt_i32_e32 vcc, 56, v5
	s_nop 1
	v_cndmask_b32_e32 v9, v246, v79, vcc
	v_cmp_lt_i32_e32 vcc, 57, v5
	v_max3_f32 v3, v3, v8, v9
	s_nop 0
	v_cndmask_b32_e32 v10, v246, v80, vcc
	v_cmp_lt_i32_e32 vcc, 58, v5
	s_nop 1
	v_cndmask_b32_e32 v11, v246, v81, vcc
	v_max3_f32 v3, v3, v10, v11
	ds_bpermute_b32 v4, v194, v3
	s_waitcnt lgkmcnt(0)
	v_max_f32_e32 v4, v4, v4
	v_max_f32_e32 v3, v3, v4
	v_max3_f32 v4, v249, v3, s14
	v_sub_f32_e32 v3, v249, v4
	v_exp_f32_e32 v6, v3
	s_nop 0
	v_cmp_eq_f32_e32 vcc, 1.0, v6
	s_cmp_eq_u64 vcc, exec
	s_cbranch_scc1 .LBB0_1590
	v_mul_f32_e32 v48, v48, v6
	v_mul_f32_e32 v49, v49, v6
	v_mul_f32_e32 v46, v46, v6
	v_mul_f32_e32 v47, v47, v6
	v_mul_f32_e32 v44, v44, v6
	v_mul_f32_e32 v45, v45, v6
	v_mul_f32_e32 v42, v42, v6
	v_mul_f32_e32 v43, v43, v6
	v_mul_f32_e32 v40, v40, v6
	v_mul_f32_e32 v41, v41, v6
	v_mul_f32_e32 v38, v38, v6
	v_mul_f32_e32 v39, v39, v6
	v_mul_f32_e32 v36, v36, v6
	v_mul_f32_e32 v37, v37, v6
	v_mul_f32_e32 v34, v34, v6
	v_mul_f32_e32 v35, v35, v6
	v_mul_f32_e32 v32, v32, v6
	v_mul_f32_e32 v33, v33, v6
	v_mul_f32_e32 v30, v30, v6
	v_mul_f32_e32 v31, v31, v6
	v_mul_f32_e32 v28, v28, v6
	v_mul_f32_e32 v29, v29, v6
	v_mul_f32_e32 v26, v26, v6
	v_mul_f32_e32 v27, v27, v6
	v_mul_f32_e32 v24, v24, v6
	v_mul_f32_e32 v25, v25, v6
	v_mul_f32_e32 v22, v22, v6
	v_mul_f32_e32 v23, v23, v6
	v_mul_f32_e32 v20, v20, v6
	v_mul_f32_e32 v21, v21, v6
	v_mul_f32_e32 v18, v18, v6
	v_mul_f32_e32 v19, v19, v6
.LBB0_1590:
	v_sub_f32_e32 v64, v84, v4
	v_sub_f32_e32 v65, v85, v4
	v_add_u32_e32 v3, v226, v220
	v_exp_f32_e32 v76, v64
	v_exp_f32_e32 v77, v65
	v_sub_f32_e32 v64, v88, v4
	v_sub_f32_e32 v65, v89, v4
	v_add_u32_e32 v3, 0x2000, v3
	v_exp_f32_e32 v78, v64
	v_exp_f32_e32 v79, v65
	v_sub_f32_e32 v64, v86, v4
	v_sub_f32_e32 v65, v87, v4
	v_sub_f32_e32 v56, v82, v4
	v_sub_f32_e32 v57, v83, v4
	v_exp_f32_e32 v80, v64
	v_exp_f32_e32 v81, v65
	ds_read2_b64 v[64:67], v3 offset0:128 offset1:130
	v_sub_f32_e32 v68, v90, v4
	v_sub_f32_e32 v69, v91, v4
	v_add_u32_e32 v5, v226, v221
	v_add_u32_e32 v5, 0x2000, v5
	ds_read2_b64 v[72:75], v5 offset0:128 offset1:130
	v_exp_f32_e32 v56, v56
	v_exp_f32_e32 v57, v57
	v_sub_f32_e32 v60, v60, v4
	v_sub_f32_e32 v61, v61, v4
	v_exp_f32_e32 v82, v68
	v_exp_f32_e32 v84, v60
	v_exp_f32_e32 v85, v61
	v_sub_f32_e32 v60, v62, v4
	v_sub_f32_e32 v61, v63, v4
	v_exp_f32_e32 v83, v69
	v_cvt_pk_bf16_f32 v68, v56, v57
	v_cvt_pk_bf16_f32 v69, v76, v77
	v_cvt_pk_bf16_f32 v70, v78, v79
	v_cvt_pk_bf16_f32 v71, v80, v81
	v_exp_f32_e32 v86, v60
	v_exp_f32_e32 v87, v61
	ds_read2_b64 v[60:63], v3 offset0:132 offset1:134
	s_waitcnt lgkmcnt(2)
	v_mfma_f32_32x32x16_bf16 v[34:49], v[64:67], v[68:71], v[34:49]
	v_add_f32_e64 v58, v58, -v4
	v_add_f32_e64 v59, v59, -v4
	v_cvt_pk_bf16_f32 v64, v82, v83
	v_cvt_pk_bf16_f32 v65, v84, v85
	v_cvt_pk_bf16_f32 v66, v86, v87
	s_waitcnt lgkmcnt(1)
	v_mfma_f32_32x32x16_bf16 v[18:33], v[72:75], v[68:71], v[18:33]
	v_exp_f32_e32 v68, v58
	v_exp_f32_e32 v69, v59
	s_nop 0
	v_cvt_pk_bf16_f32 v67, v68, v69
	s_waitcnt lgkmcnt(0)
	s_nop 0
	v_mfma_f32_32x32x16_bf16 v[34:49], v[60:63], v[64:67], v[34:49]
	ds_read2_b64 v[58:61], v5 offset0:132 offset1:134
	s_waitcnt lgkmcnt(0)
	v_mfma_f32_32x32x16_bf16 v[18:33], v[58:61], v[64:67], v[18:33]
	v_add_f32_e64 v50, v50, -v4
	v_add_f32_e64 v51, v51, -v4
	v_add_f32_e64 v16, v16, -v4
	v_add_f32_e64 v17, v17, -v4
	v_exp_f32_e32 v64, v50
	v_exp_f32_e32 v65, v51
	v_exp_f32_e32 v66, v16
	v_exp_f32_e32 v67, v17
	v_sub_f32_e32 v50, v14, v4
	v_sub_f32_e32 v51, v15, v4
	ds_read2_b64 v[14:17], v3 offset0:136 offset1:138
	v_sub_f32_e32 v54, v54, v4
	v_sub_f32_e32 v55, v55, v4
	v_sub_f32_e32 v52, v52, v4
	v_sub_f32_e32 v53, v53, v4
	v_exp_f32_e32 v54, v54
	v_exp_f32_e32 v55, v55
	v_exp_f32_e32 v62, v52
	v_exp_f32_e32 v63, v53
	ds_read2_b64 v[58:61], v5 offset0:136 offset1:138
	v_exp_f32_e32 v70, v50
	v_exp_f32_e32 v71, v51
	v_sub_f32_e32 v12, v12, v4
	v_sub_f32_e32 v13, v13, v4
	v_cvt_pk_bf16_f32 v50, v54, v55
	v_cvt_pk_bf16_f32 v51, v62, v63
	v_cvt_pk_bf16_f32 v52, v64, v65
	v_cvt_pk_bf16_f32 v53, v66, v67
	v_sub_f32_e32 v8, v8, v4
	v_sub_f32_e32 v9, v9, v4
	s_waitcnt lgkmcnt(1)
	v_mfma_f32_32x32x16_bf16 v[34:49], v[14:17], v[50:53], v[34:49]
	v_exp_f32_e32 v16, v12
	v_exp_f32_e32 v17, v13
	v_exp_f32_e32 v72, v8
	v_exp_f32_e32 v73, v9
	v_sub_f32_e32 v12, v10, v4
	v_sub_f32_e32 v13, v11, v4
	ds_read2_b64 v[8:11], v3 offset0:140 offset1:142
	s_waitcnt lgkmcnt(1)
	v_mfma_f32_32x32x16_bf16 v[18:33], v[58:61], v[50:53], v[18:33]
	v_exp_f32_e32 v58, v12
	v_exp_f32_e32 v59, v13
	v_cvt_pk_bf16_f32 v50, v70, v71
	v_cvt_pk_bf16_f32 v51, v16, v17
	v_cvt_pk_bf16_f32 v52, v72, v73
	v_cvt_pk_bf16_f32 v53, v58, v59
	ds_read2_b64 v[12:15], v5 offset0:140 offset1:142
	s_waitcnt lgkmcnt(1)
	v_mfma_f32_32x32x16_bf16 v[34:49], v[8:11], v[50:53], v[34:49]
	v_add_f32_e64 v8, v56, 0
	v_add_f32_e64 v9, v57, 0
	v_add_f32_e64 v8, v76, v8
	v_add_f32_e64 v9, v77, v9
	v_add_f32_e64 v8, v78, v8
	v_add_f32_e64 v9, v79, v9
	v_add_f32_e32 v8, v80, v8
	v_add_f32_e32 v9, v81, v9
	s_waitcnt lgkmcnt(0)
	v_mfma_f32_32x32x16_bf16 v[18:33], v[12:15], v[50:53], v[18:33]
	v_add_f32_e64 v8, v82, v8
	v_add_f32_e64 v9, v83, v9
	v_add_f32_e64 v8, v84, v8
	v_add_f32_e64 v9, v85, v9
	v_add_f32_e64 v8, v86, v8
	v_add_f32_e64 v9, v87, v9
	v_add_f32_e32 v8, v68, v8
	v_add_f32_e32 v9, v69, v9
	s_nop 0
	v_add_f32_e32 v8, v54, v8
	v_add_f32_e32 v9, v55, v9
	s_nop 0
	v_add_f32_e32 v8, v62, v8
	v_add_f32_e32 v9, v63, v9
	s_nop 0
	v_add_f32_e32 v8, v64, v8
	v_add_f32_e32 v9, v65, v9
	s_nop 0
	v_add_f32_e32 v8, v66, v8
	v_add_f32_e32 v9, v67, v9
	s_nop 0
	v_add_f32_e32 v8, v70, v8
	v_add_f32_e32 v9, v71, v9
	s_nop 0
	v_add_f32_e32 v8, v16, v8
	v_add_f32_e32 v9, v17, v9
	s_nop 0
	v_add_f32_e32 v8, v72, v8
	v_add_f32_e32 v9, v73, v9
	v_mov_b64_e32 v[80:81], v[32:33]
	v_add_f32_e32 v8, v58, v8
	v_add_f32_e32 v9, v59, v9
	v_mov_b64_e32 v[64:65], v[48:49]
	v_add_f32_e32 v3, v8, v9
	ds_bpermute_b32 v10, v194, v3
	v_mov_b64_e32 v[62:63], v[46:47]
	v_mov_b64_e32 v[60:61], v[44:45]
	v_mov_b64_e32 v[58:59], v[42:43]
	v_mov_b64_e32 v[56:57], v[40:41]
	v_mov_b64_e32 v[54:55], v[38:39]
	v_mov_b64_e32 v[52:53], v[36:37]
	v_mov_b64_e32 v[50:51], v[34:35]
	v_mov_b64_e32 v[78:79], v[30:31]
	v_mov_b64_e32 v[76:77], v[28:29]
	v_mov_b64_e32 v[74:75], v[26:27]
	v_mov_b64_e32 v[72:73], v[24:25]
	v_mov_b64_e32 v[70:71], v[22:23]
	v_mov_b64_e32 v[68:69], v[20:21]
	v_mov_b64_e32 v[66:67], v[18:19]
.LBB0_1591:
	s_andn2_saveexec_b64 s[42:43], s[42:43]
	s_cbranch_execz .LBB0_1494
	v_mov_b32_e32 v3, v152
	s_nop 0
	v_mul_f32_e64 v4, v7, -v3
	v_cndmask_b32_e64 v14, v246, v4, s[50:51]
	v_mov_b32_e32 v16, v3
	v_fma_f32 v4, 0, v3, v14
	v_add_f32_e32 v66, v2, v4
	v_add_f32_e32 v67, v3, v4
	v_fma_f32 v68, v16, s0, v4
	v_fma_f32 v69, v16, s1, v4
	v_fmamk_f32 v4, v3, 0x41000000, v14
	v_add_f32_e32 v70, v2, v4
	v_add_f32_e32 v71, v3, v4
	v_fma_f32 v72, v16, s0, v4
	v_fma_f32 v73, v16, s1, v4
	v_fmamk_f32 v4, v3, 0x41800000, v14
	v_add_f32_e32 v74, v2, v4
	v_add_f32_e32 v75, v3, v4
	v_fma_f32 v76, v16, s0, v4
	v_fma_f32 v77, v16, s1, v4
	v_fmamk_f32 v4, v3, 0x41c00000, v14
	v_add_f32_e32 v78, v2, v4
	v_add_f32_e32 v79, v3, v4
	v_fma_f32 v80, v16, s0, v4
	v_fma_f32 v81, v16, s1, v4
	ds_read_b128 v[4:7], v9
	s_waitcnt lgkmcnt(1)
	ds_read_b128 v[10:13], v9 offset:32
	s_waitcnt lgkmcnt(1)
	v_mfma_f32_32x32x16_bf16 v[66:81], v[4:7], v[114:117], v[66:81]
	ds_read_b128 v[4:7], v9 offset:64
	s_waitcnt lgkmcnt(1)
	v_mfma_f32_32x32x16_bf16 v[66:81], v[10:13], v[118:121], v[66:81]
	s_waitcnt lgkmcnt(0)
	v_mfma_f32_32x32x16_bf16 v[66:81], v[4:7], v[122:125], v[66:81]
	ds_read_b128 v[4:7], v9 offset:96
	s_waitcnt lgkmcnt(0)
	v_mfma_f32_32x32x16_bf16 v[66:81], v[4:7], v[126:129], v[66:81]
	v_fmamk_f32 v4, v3, 0x42000000, v14
	v_add_f32_e64 v50, v2, v4
	v_add_f32_e64 v51, v3, v4
	v_fma_f32 v52, v16, s0, v4
	v_fma_f32 v53, v16, s1, v4
	v_fmamk_f32 v4, v3, 0x42200000, v14
	v_add_f32_e32 v54, v2, v4
	v_add_f32_e32 v55, v3, v4
	v_fma_f32 v56, v16, s0, v4
	v_fma_f32 v57, v16, s1, v4
	v_fmamk_f32 v4, v3, 0x42400000, v14
	v_add_f32_e32 v58, v2, v4
	v_add_f32_e32 v59, v3, v4
	v_fma_f32 v60, v16, s0, v4
	v_fma_f32 v61, v16, s1, v4
	ds_read_b128 v[4:7], v8
	ds_read_b128 v[10:13], v8 offset:32
	v_fmac_f32_e32 v14, 0x42600000, v3
	v_add_f32_e32 v62, v2, v14
	v_add_f32_e32 v63, v3, v14
	v_fma_f32 v64, v16, s0, v14
	v_fma_f32 v65, v16, s1, v14
	v_max3_f32 v3, v66, s33, v67
	v_max3_f32 v3, v3, v68, v69
	s_waitcnt lgkmcnt(1)
	v_mfma_f32_32x32x16_bf16 v[50:65], v[4:7], v[114:117], v[50:65]
	ds_read_b128 v[4:7], v8 offset:64
	v_max3_f32 v3, v3, v70, v71
	v_max3_f32 v3, v3, v72, v73
	v_max3_f32 v3, v3, v74, v75
	v_max3_f32 v3, v3, v76, v77
	v_max3_f32 v3, v3, v78, v79
	v_max3_f32 v3, v3, v80, v81
	s_waitcnt lgkmcnt(1)
	v_mfma_f32_32x32x16_bf16 v[50:65], v[10:13], v[118:121], v[50:65]
	s_waitcnt lgkmcnt(0)
	v_mfma_f32_32x32x16_bf16 v[50:65], v[4:7], v[122:125], v[50:65]
	ds_read_b128 v[4:7], v8 offset:96
	s_waitcnt lgkmcnt(0)
	v_mfma_f32_32x32x16_bf16 v[50:65], v[4:7], v[126:129], v[50:65]
	s_nop 11
	v_max3_f32 v3, v3, v50, v51
	v_max3_f32 v3, v3, v52, v53
	v_max3_f32 v3, v3, v54, v55
	v_max3_f32 v3, v3, v56, v57
	v_max3_f32 v3, v3, v58, v59
	v_max3_f32 v3, v3, v60, v61
	v_max3_f32 v3, v3, v62, v63
	v_max3_f32 v3, v3, v64, v65
	ds_bpermute_b32 v4, v194, v3
	s_waitcnt lgkmcnt(0)
	v_max_f32_e32 v4, v4, v4
	v_max_f32_e32 v3, v3, v4
	v_max3_f32 v4, v249, v3, s14
	v_sub_f32_e32 v3, v249, v4
	v_exp_f32_e32 v6, v3
	s_nop 0
	v_cmp_eq_f32_e32 vcc, 1.0, v6
	s_cmp_eq_u64 vcc, exec
	s_cbranch_scc1 .LBB0_1493
	v_mul_f32_e32 v48, v48, v6
	v_mul_f32_e32 v49, v49, v6
	v_mul_f32_e32 v46, v46, v6
	v_mul_f32_e32 v47, v47, v6
	v_mul_f32_e32 v44, v44, v6
	v_mul_f32_e32 v45, v45, v6
	v_mul_f32_e32 v42, v42, v6
	v_mul_f32_e32 v43, v43, v6
	v_mul_f32_e32 v40, v40, v6
	v_mul_f32_e32 v41, v41, v6
	v_mul_f32_e32 v38, v38, v6
	v_mul_f32_e32 v39, v39, v6
	v_mul_f32_e32 v36, v36, v6
	v_mul_f32_e32 v37, v37, v6
	v_mul_f32_e32 v34, v34, v6
	v_mul_f32_e32 v35, v35, v6
	v_mul_f32_e32 v32, v32, v6
	v_mul_f32_e32 v33, v33, v6
	v_mul_f32_e32 v30, v30, v6
	v_mul_f32_e32 v31, v31, v6
	v_mul_f32_e32 v28, v28, v6
	v_mul_f32_e32 v29, v29, v6
	v_mul_f32_e32 v26, v26, v6
	v_mul_f32_e32 v27, v27, v6
	v_mul_f32_e32 v24, v24, v6
	v_mul_f32_e32 v25, v25, v6
	v_mul_f32_e32 v22, v22, v6
	v_mul_f32_e32 v23, v23, v6
	v_mul_f32_e32 v20, v20, v6
	v_mul_f32_e32 v21, v21, v6
	v_mul_f32_e32 v18, v18, v6
	v_mul_f32_e32 v19, v19, v6
	s_branch .LBB0_1493
